# speedup vs baseline: 1.0073x; 1.0073x over previous
; #define WAIT_V(n) asm volatile("s_waitcnt vmcnt(" #n ")" ::: "memory")
; #define BAR __builtin_amdgcn_s_barrier()
; template <int EPI>
; __device__ __forceinline__ void phase_gemm(const Params& p, const GemmDesc& d, char* shmc) {
;     ...
;     f32x4 acc[2][2][4][2];
; #pragma unroll
;     for (int a = 0; a < 2; ++a)
; #pragma unroll
;       for (int b = 0; b < 2; ++b)
; #pragma unroll
;         for (int m = 0; m < 4; ++m)
; #pragma unroll
;           for (int n = 0; n < 2; ++n) acc[a][b][m][n] = f32x4{0.f, 0.f, 0.f, 0.f};
;     bf16x8 At[4][2], B0[2][2], B1[2][2];
;     if constexpr (EPI == EPI_UP || EPI == EPI_QKV) {
;       if (wid == 0)
;         __builtin_amdgcn_global_load_lds((const unsigned*)(p.rstd + brow + lane * 4), (unsigned*)(shmc + 143360), 16, 0, 0);
;     }
;     STAGE_B(SB(0, 0), 0, 0); STAGE_A(SA(0, 0), 0, 0);
;     STAGE_B(SB(0, 1), 1, 0); STAGE_A(SA(0, 1), 1, 0);
;     if (wr == 1) BAR;
;     WAIT_V(4); BAR;
;     STAGE_B(SB(1, 0), 0, 1); STAGE_A(SA(1, 0), 0, 1); STAGE_B(SB(1, 1), 1, 1);
;     WAIT_V(6); BAR;
;     for (int t = 0; t < nt - 2; t += 2) {
.LBB0_295:
	s_or_b64 exec, exec, s[64:65]
	v_mov_b32_e32 v175, v163
	v_lshl_add_u64 v[2:3], s[62:63], 0, v[174:175]
	v_mov_b32_e32 v177, v163
	s_mov_b32 m0, s87
	v_lshl_add_u64 v[4:5], s[62:63], 0, v[176:177]
	v_lshl_add_u64 v[2:3], v[2:3], 0, s[26:27]
	v_lshl_add_u64 v[6:7], s[8:9], 0, v[174:175]
	v_mov_b32_e32 v10, 0
	v_mov_b32_e32 v11, 0
	v_mov_b32_e32 v12, 0
	v_mov_b32_e32 v13, 0
	v_mov_b32_e32 v18, 0
	v_mov_b32_e32 v19, 0
	v_mov_b32_e32 v20, 0
	v_mov_b32_e32 v21, 0
	v_mov_b32_e32 v30, 0
	v_mov_b32_e32 v31, 0
	v_mov_b32_e32 v32, 0
	v_mov_b32_e32 v33, 0
	v_mov_b32_e32 v42, 0
	v_mov_b32_e32 v43, 0
	v_mov_b32_e32 v44, 0
	v_mov_b32_e32 v45, 0
	v_mov_b32_e32 v54, 0
	v_mov_b32_e32 v55, 0
	v_mov_b32_e32 v56, 0
	v_mov_b32_e32 v57, 0
	v_mov_b32_e32 v66, 0
	v_mov_b32_e32 v67, 0
	v_mov_b32_e32 v68, 0
	v_mov_b32_e32 v69, 0
	v_mov_b32_e32 v14, 0
	v_mov_b32_e32 v15, 0
	v_mov_b32_e32 v16, 0
	v_mov_b32_e32 v17, 0
	v_mov_b32_e32 v22, 0
	v_mov_b32_e32 v23, 0
	v_mov_b32_e32 v24, 0
	v_mov_b32_e32 v25, 0
	v_mov_b32_e32 v34, 0
	v_mov_b32_e32 v35, 0
	v_mov_b32_e32 v36, 0
	v_mov_b32_e32 v37, 0
	v_mov_b32_e32 v46, 0
	v_mov_b32_e32 v47, 0
	v_mov_b32_e32 v48, 0
	v_mov_b32_e32 v49, 0
	v_mov_b32_e32 v58, 0
	v_mov_b32_e32 v59, 0
	v_mov_b32_e32 v60, 0
	v_mov_b32_e32 v61, 0
	v_mov_b32_e32 v70, 0
	v_mov_b32_e32 v71, 0
	v_mov_b32_e32 v72, 0
	v_mov_b32_e32 v73, 0
	v_mov_b32_e32 v78, 0
	v_mov_b32_e32 v79, 0
	v_mov_b32_e32 v80, 0
	v_mov_b32_e32 v81, 0
	v_mov_b32_e32 v86, 0
	v_mov_b32_e32 v87, 0
	v_mov_b32_e32 v88, 0
	v_mov_b32_e32 v89, 0
	v_mov_b32_e32 v26, 0
	v_mov_b32_e32 v27, 0
	v_mov_b32_e32 v28, 0
	v_mov_b32_e32 v29, 0
	v_mov_b32_e32 v38, 0
	v_mov_b32_e32 v39, 0
	v_mov_b32_e32 v40, 0
	v_mov_b32_e32 v41, 0
	v_mov_b32_e32 v50, 0
	v_mov_b32_e32 v51, 0
	v_mov_b32_e32 v52, 0
	v_mov_b32_e32 v53, 0
	v_mov_b32_e32 v62, 0
	v_mov_b32_e32 v63, 0
	v_mov_b32_e32 v64, 0
	v_mov_b32_e32 v65, 0
	v_mov_b32_e32 v74, 0
	v_mov_b32_e32 v75, 0
	v_mov_b32_e32 v76, 0
	v_mov_b32_e32 v77, 0
	v_mov_b32_e32 v82, 0
	v_mov_b32_e32 v83, 0
	v_mov_b32_e32 v84, 0
	v_mov_b32_e32 v85, 0
	v_mov_b32_e32 v90, 0
	v_mov_b32_e32 v91, 0
	v_mov_b32_e32 v92, 0
	v_mov_b32_e32 v93, 0
	v_mov_b32_e32 v94, 0
	v_mov_b32_e32 v95, 0
	v_mov_b32_e32 v96, 0
	v_mov_b32_e32 v97, 0
	v_mov_b32_e32 v98, 0
	v_mov_b32_e32 v99, 0
	v_mov_b32_e32 v100, 0
	v_mov_b32_e32 v101, 0
	v_mov_b32_e32 v102, 0
	v_mov_b32_e32 v103, 0
	v_mov_b32_e32 v104, 0
	v_mov_b32_e32 v105, 0
	v_mov_b32_e32 v106, 0
	v_mov_b32_e32 v107, 0
	v_mov_b32_e32 v108, 0
	v_mov_b32_e32 v109, 0
	v_mov_b32_e32 v110, 0
	v_mov_b32_e32 v111, 0
	v_mov_b32_e32 v112, 0
	v_mov_b32_e32 v113, 0
	v_mov_b32_e32 v114, 0
	v_mov_b32_e32 v115, 0
	v_mov_b32_e32 v116, 0
	v_mov_b32_e32 v117, 0
	v_mov_b32_e32 v118, 0
	v_mov_b32_e32 v119, 0
	v_mov_b32_e32 v120, 0
	v_mov_b32_e32 v121, 0
	v_mov_b32_e32 v122, 0
	v_mov_b32_e32 v123, 0
	v_mov_b32_e32 v124, 0
	v_mov_b32_e32 v125, 0
	v_mov_b32_e32 v126, 0
	v_mov_b32_e32 v127, 0
	v_mov_b32_e32 v128, 0
	v_mov_b32_e32 v129, 0
	s_waitcnt vmcnt(2)
	s_barrier
	global_load_lds_dwordx4 v[2:3], off
	v_lshl_add_u64 v[2:3], v[4:5], 0, s[26:27]
	s_mov_b32 m0, s88
	v_lshl_add_u64 v[8:9], s[8:9], 0, v[176:177]
	global_load_lds_dwordx4 v[2:3], off
	v_lshl_add_u64 v[2:3], v[6:7], 0, s[26:27]
	s_mov_b32 m0, s89
	s_add_u32 s62, s62, 0x80080
	global_load_lds_dwordx4 v[2:3], off
	v_lshl_add_u64 v[2:3], v[8:9], 0, s[26:27]
	s_mov_b32 m0, s90
	s_addc_u32 s63, s63, 0
	global_load_lds_dwordx4 v[2:3], off
	s_mov_b32 m0, s91
	v_lshl_add_u64 v[130:131], v[166:167], 0, s[10:11]
	global_load_lds_dwordx4 v174, s[62:63]
	s_mov_b32 m0, s92
	v_lshl_add_u64 v[132:133], v[168:169], 0, s[10:11]
	global_load_lds_dwordx4 v176, s[62:63]
	s_lshl_b32 s10, s35, 11
	s_lshl_b32 s11, s68, 8
	s_or_b32 s10, s10, s11
	s_waitcnt vmcnt(6)
	s_ashr_i32 s11, s10, 31
	s_lshl_b64 s[10:11], s[10:11], 12
	v_mov_b32_e32 v2, 0
	v_lshl_add_u64 v[134:135], v[170:171], 0, s[10:11]
	v_lshl_add_u64 v[136:137], v[172:173], 0, s[10:11]
	s_mov_b32 s35, -2
	s_mov_b64 s[10:11], 0
	v_mov_b32_e32 v3, v2
	v_mov_b32_e32 v4, v2
	v_mov_b32_e32 v5, v2
	v_mov_b32_e32 v6, v2
	v_mov_b32_e32 v7, v2
	v_mov_b32_e32 v8, v2
	v_mov_b32_e32 v9, v2
	s_barrier
	v_readfirstlane_b32 s98, v134
	v_readfirstlane_b32 s99, v135
	v_readfirstlane_b32 s100, v130
	v_readfirstlane_b32 s101, v131
	s_nop 3
	v_subrev_u32_e32 v202, s98, v134
	v_add_u32_e32 v202, s38, v202
	v_subrev_u32_e32 v203, s98, v136
	v_add_u32_e32 v203, s38, v203
	v_subrev_u32_e32 v224, s100, v130
	v_add_u32_e32 v224, s40, v224
	v_subrev_u32_e32 v225, s100, v132
	v_add_u32_e32 v225, s40, v225
	v_subrev_u32_e32 v226, s98, v134
	v_add_u32_e32 v226, s42, v226
	v_subrev_u32_e32 v227, s98, v136
	v_add_u32_e32 v227, s42, v227
	v_subrev_u32_e32 v228, s100, v130
	v_add_u32_e32 v228, s48, v228
	v_subrev_u32_e32 v229, s100, v132
	v_add_u32_e32 v229, s48, v229
	v_subrev_u32_e32 v230, s98, v134
	v_add_u32_e32 v230, s52, v230
	v_subrev_u32_e32 v231, s98, v136
	v_add_u32_e32 v231, s52, v231
	v_subrev_u32_e32 v232, s100, v130
	v_add_u32_e32 v232, s54, v232
	v_subrev_u32_e32 v233, s100, v132
	v_add_u32_e32 v233, s54, v233
	v_subrev_u32_e32 v234, s98, v134
	v_add_u32_e32 v234, s56, v234
	v_subrev_u32_e32 v235, s98, v136
	v_add_u32_e32 v235, s56, v235
	v_subrev_u32_e32 v236, s100, v130
	v_add_u32_e32 v236, s58, v236
	v_subrev_u32_e32 v237, s100, v132
	v_add_u32_e32 v237, s58, v237
	s_add_u32 s98, s98, s10
	s_addc_u32 s99, s99, s11
	s_add_u32 s100, s100, s10
	s_addc_u32 s101, s101, s11
; #define LDA(dst, b, h)                                                                                     \
;   _Pragma("unroll") for (int m = 0; m < 4; ++m) _Pragma("unroll") for (int k = 0; k < 2; ++k) dst[m][k] = \
;       *reinterpret_cast<const bf16x8*>(shmc + aL + (((b) * 2 + (h)) * 16384 + (m * 2 + k) * 1024))
; #define LDB(dst, b, h)                                                                                     \
;   _Pragma("unroll") for (int n = 0; n < 2; ++n) _Pragma("unroll") for (int k = 0; k < 2; ++k) dst[n][k] = \
;       *reinterpret_cast<const bf16x8*>(shmc + bL + (((b) * 2 + (h)) * 16384 + (n * 2 + k) * 1024))
; #define OPAQ asm volatile("" : "+v"(aL), "+v"(bL))
; #define WAIT_V(n) asm volatile("s_waitcnt vmcnt(" #n ")" ::: "memory")
; #define WAIT_L(n) asm volatile("s_waitcnt lgkmcnt(" #n ")" ::: "memory")
; #define BAR __builtin_amdgcn_s_barrier()
; #define SCHED __builtin_amdgcn_sched_barrier(0)
; template <int EPI>
; __device__ __forceinline__ void phase_gemm(const Params& p, const GemmDesc& d, char* shmc) {
;     ...
;     for (int t = 0; t < nt - 2; t += 2) {
;       OPAQ;
;       LDB(B0, 0, 0); SCHED; LDA(At, 0, 0); STAGE_A(SA(1, 1), 1, t + 1);
;       WAIT_L(8); BAR; WAIT_L(0); MMA(0, 0, At, B0); BAR; SCHED;
;       LDB(B1, 0, 1); STAGE_B(SB(0, 0), 0, t + 2);
;       BAR; WAIT_L(0); MMA(0, 1, At, B1); BAR;
;       LDA(At, 0, 1); STAGE_A(SA(0, 0), 0, t + 2);
;       BAR; WAIT_L(0); MMA(1, 0, At, B0); BAR; SCHED;
;       STAGE_B(SB(0, 1), 1, t + 2);
;       WAIT_V(6); BAR; MMA(1, 1, At, B1); BAR;
.LBB0_296:
	s_nop 0
	v_add_u32_e32 v162, 0, v205
	v_add_u32_e32 v175, 0, v204
	s_setprio 0
	ds_read_b128 v[138:141], v162
	ds_read_b128 v[142:145], v162 offset:1024
	ds_read_b128 v[146:149], v162 offset:2048
	ds_read_b128 v[150:153], v162 offset:3072
	ds_read_b128 v[208:211], v162 offset:16384
	ds_read_b128 v[212:215], v162 offset:17408
	ds_read_b128 v[216:219], v162 offset:18432
	ds_read_b128 v[220:223], v162 offset:19456
	ds_read_b128 v[154:157], v175
	ds_read_b128 v[158:161], v175 offset:1024
	ds_read_b128 v[178:181], v175 offset:2048
	ds_read_b128 v[182:185], v175 offset:3072
	ds_read_b128 v[186:189], v175 offset:4096
	ds_read_b128 v[190:193], v175 offset:5120
	ds_read_b128 v[194:197], v175 offset:6144
	ds_read_b128 v[198:201], v175 offset:7168
	s_mov_b32 m0, s93
	s_nop 0
	global_load_lds_dwordx4 v202, s[98:99]
	s_mov_b32 m0, s94
	s_nop 0
	global_load_lds_dwordx4 v203, s[98:99]
	s_waitcnt vmcnt(8)
	s_waitcnt lgkmcnt(0)
	s_setprio 1
	s_barrier
	v_mfma_f32_16x16x32_bf16 v[2:5], v[154:157], v[138:141], v[2:5]
	v_mfma_f32_16x16x32_bf16 v[6:9], v[154:157], v[146:149], v[6:9]
	v_mfma_f32_16x16x32_bf16 v[10:13], v[178:181], v[138:141], v[10:13]
	v_mfma_f32_16x16x32_bf16 v[18:21], v[178:181], v[146:149], v[18:21]
	v_mfma_f32_16x16x32_bf16 v[30:33], v[186:189], v[138:141], v[30:33]
	v_mfma_f32_16x16x32_bf16 v[42:45], v[186:189], v[146:149], v[42:45]
	v_mfma_f32_16x16x32_bf16 v[54:57], v[194:197], v[138:141], v[54:57]
	v_mfma_f32_16x16x32_bf16 v[66:69], v[194:197], v[146:149], v[66:69]
	v_mfma_f32_16x16x32_bf16 v[2:5], v[158:161], v[142:145], v[2:5]
	v_mfma_f32_16x16x32_bf16 v[6:9], v[158:161], v[150:153], v[6:9]
	v_mfma_f32_16x16x32_bf16 v[10:13], v[182:185], v[142:145], v[10:13]
	v_mfma_f32_16x16x32_bf16 v[18:21], v[182:185], v[150:153], v[18:21]
	v_mfma_f32_16x16x32_bf16 v[30:33], v[190:193], v[142:145], v[30:33]
	v_mfma_f32_16x16x32_bf16 v[42:45], v[190:193], v[150:153], v[42:45]
	v_mfma_f32_16x16x32_bf16 v[54:57], v[198:201], v[142:145], v[54:57]
	v_mfma_f32_16x16x32_bf16 v[66:69], v[198:201], v[150:153], v[66:69]
	v_mfma_f32_16x16x32_bf16 v[14:17], v[154:157], v[208:211], v[14:17]
	v_mfma_f32_16x16x32_bf16 v[22:25], v[154:157], v[216:219], v[22:25]
	v_mfma_f32_16x16x32_bf16 v[34:37], v[178:181], v[208:211], v[34:37]
	v_mfma_f32_16x16x32_bf16 v[46:49], v[178:181], v[216:219], v[46:49]
	v_mfma_f32_16x16x32_bf16 v[58:61], v[186:189], v[208:211], v[58:61]
	v_mfma_f32_16x16x32_bf16 v[70:73], v[186:189], v[216:219], v[70:73]
	v_mfma_f32_16x16x32_bf16 v[78:81], v[194:197], v[208:211], v[78:81]
	v_mfma_f32_16x16x32_bf16 v[86:89], v[194:197], v[216:219], v[86:89]
	v_mfma_f32_16x16x32_bf16 v[14:17], v[158:161], v[212:215], v[14:17]
	v_mfma_f32_16x16x32_bf16 v[22:25], v[158:161], v[220:223], v[22:25]
	v_mfma_f32_16x16x32_bf16 v[34:37], v[182:185], v[212:215], v[34:37]
	v_mfma_f32_16x16x32_bf16 v[46:49], v[182:185], v[220:223], v[46:49]
	v_mfma_f32_16x16x32_bf16 v[58:61], v[190:193], v[212:215], v[58:61]
	v_mfma_f32_16x16x32_bf16 v[70:73], v[190:193], v[220:223], v[70:73]
	v_mfma_f32_16x16x32_bf16 v[78:81], v[198:201], v[212:215], v[78:81]
	v_mfma_f32_16x16x32_bf16 v[86:89], v[198:201], v[220:223], v[86:89]
	s_barrier
	s_setprio 0
	ds_read_b128 v[154:157], v175 offset:16384
	ds_read_b128 v[158:161], v175 offset:17408
	ds_read_b128 v[178:181], v175 offset:18432
	ds_read_b128 v[182:185], v175 offset:19456
	ds_read_b128 v[186:189], v175 offset:20480
	ds_read_b128 v[190:193], v175 offset:21504
	ds_read_b128 v[194:197], v175 offset:22528
	ds_read_b128 v[198:201], v175 offset:23552
	s_mov_b32 m0, s80
	s_nop 0
	global_load_lds_dwordx4 v224, s[100:101]
	s_mov_b32 m0, s81
	s_nop 0
	global_load_lds_dwordx4 v225, s[100:101]
	s_mov_b32 m0, s77
	s_nop 0
	global_load_lds_dwordx4 v226, s[98:99]
	s_mov_b32 m0, s82
	s_nop 0
	global_load_lds_dwordx4 v227, s[98:99]
	s_mov_b32 m0, s83
	s_nop 0
	global_load_lds_dwordx4 v228, s[100:101]
	s_mov_b32 m0, s84
	s_nop 0
	global_load_lds_dwordx4 v229, s[100:101]
	s_waitcnt vmcnt(8)
	s_waitcnt lgkmcnt(0)
	s_setprio 1
	s_barrier
	v_mfma_f32_16x16x32_bf16 v[26:29], v[154:157], v[138:141], v[26:29]
	v_mfma_f32_16x16x32_bf16 v[38:41], v[154:157], v[146:149], v[38:41]
	v_mfma_f32_16x16x32_bf16 v[50:53], v[178:181], v[138:141], v[50:53]
	v_mfma_f32_16x16x32_bf16 v[62:65], v[178:181], v[146:149], v[62:65]
	v_mfma_f32_16x16x32_bf16 v[74:77], v[186:189], v[138:141], v[74:77]
	v_mfma_f32_16x16x32_bf16 v[82:85], v[186:189], v[146:149], v[82:85]
	v_mfma_f32_16x16x32_bf16 v[90:93], v[194:197], v[138:141], v[90:93]
	v_mfma_f32_16x16x32_bf16 v[94:97], v[194:197], v[146:149], v[94:97]
	v_mfma_f32_16x16x32_bf16 v[26:29], v[158:161], v[142:145], v[26:29]
	v_mfma_f32_16x16x32_bf16 v[38:41], v[158:161], v[150:153], v[38:41]
	v_mfma_f32_16x16x32_bf16 v[50:53], v[182:185], v[142:145], v[50:53]
	v_mfma_f32_16x16x32_bf16 v[62:65], v[182:185], v[150:153], v[62:65]
	v_mfma_f32_16x16x32_bf16 v[74:77], v[190:193], v[142:145], v[74:77]
	v_mfma_f32_16x16x32_bf16 v[82:85], v[190:193], v[150:153], v[82:85]
	v_mfma_f32_16x16x32_bf16 v[90:93], v[198:201], v[142:145], v[90:93]
	v_mfma_f32_16x16x32_bf16 v[94:97], v[198:201], v[150:153], v[94:97]
	v_mfma_f32_16x16x32_bf16 v[98:101], v[154:157], v[208:211], v[98:101]
	v_mfma_f32_16x16x32_bf16 v[102:105], v[154:157], v[216:219], v[102:105]
	v_mfma_f32_16x16x32_bf16 v[106:109], v[178:181], v[208:211], v[106:109]
	v_mfma_f32_16x16x32_bf16 v[110:113], v[178:181], v[216:219], v[110:113]
	v_mfma_f32_16x16x32_bf16 v[114:117], v[186:189], v[208:211], v[114:117]
	v_mfma_f32_16x16x32_bf16 v[118:121], v[186:189], v[216:219], v[118:121]
	v_mfma_f32_16x16x32_bf16 v[122:125], v[194:197], v[208:211], v[122:125]
	v_mfma_f32_16x16x32_bf16 v[126:129], v[194:197], v[216:219], v[126:129]
	v_mfma_f32_16x16x32_bf16 v[98:101], v[158:161], v[212:215], v[98:101]
	v_mfma_f32_16x16x32_bf16 v[102:105], v[158:161], v[220:223], v[102:105]
	v_mfma_f32_16x16x32_bf16 v[106:109], v[182:185], v[212:215], v[106:109]
	v_mfma_f32_16x16x32_bf16 v[110:113], v[182:185], v[220:223], v[110:113]
	v_mfma_f32_16x16x32_bf16 v[114:117], v[190:193], v[212:215], v[114:117]
	v_mfma_f32_16x16x32_bf16 v[118:121], v[190:193], v[220:223], v[118:121]
	v_mfma_f32_16x16x32_bf16 v[122:125], v[198:201], v[212:215], v[122:125]
	v_mfma_f32_16x16x32_bf16 v[126:129], v[198:201], v[220:223], v[126:129]
	s_barrier
; #define LDA(dst, b, h)                                                                                     \
;   _Pragma("unroll") for (int m = 0; m < 4; ++m) _Pragma("unroll") for (int k = 0; k < 2; ++k) dst[m][k] = \
;       *reinterpret_cast<const bf16x8*>(shmc + aL + (((b) * 2 + (h)) * 16384 + (m * 2 + k) * 1024))
; #define LDB(dst, b, h)                                                                                     \
;   _Pragma("unroll") for (int n = 0; n < 2; ++n) _Pragma("unroll") for (int k = 0; k < 2; ++k) dst[n][k] = \
;       *reinterpret_cast<const bf16x8*>(shmc + bL + (((b) * 2 + (h)) * 16384 + (n * 2 + k) * 1024))
; #define WAIT_V(n) asm volatile("s_waitcnt vmcnt(" #n ")" ::: "memory")
; #define WAIT_L(n) asm volatile("s_waitcnt lgkmcnt(" #n ")" ::: "memory")
; #define BAR __builtin_amdgcn_s_barrier()
; #define SCHED __builtin_amdgcn_sched_barrier(0)
; template <int EPI>
; __device__ __forceinline__ void phase_gemm(const Params& p, const GemmDesc& d, char* shmc) {
;     ...
;       WAIT_V(6); BAR; MMA(1, 1, At, B1); BAR;
;       LDB(B0, 1, 0); SCHED; LDA(At, 1, 0); STAGE_A(SA(0, 1), 1, t + 2);
;       WAIT_L(8); BAR; WAIT_L(0); MMA(0, 0, At, B0); BAR; SCHED;
;       LDB(B1, 1, 1); STAGE_B(SB(1, 0), 0, t + 3);
;       BAR; WAIT_L(0); MMA(0, 1, At, B1); BAR;
;       LDA(At, 1, 1); STAGE_A(SA(1, 0), 0, t + 3);
;       BAR; WAIT_L(0); MMA(1, 0, At, B0); BAR; SCHED;
;       STAGE_B(SB(1, 1), 1, t + 3);
;       WAIT_V(6); BAR; MMA(1, 1, At, B1); BAR;
;     }
	s_setprio 0
	ds_read_b128 v[138:141], v162 offset:32768
	ds_read_b128 v[142:145], v162 offset:33792
	ds_read_b128 v[146:149], v162 offset:34816
	ds_read_b128 v[150:153], v162 offset:35840
	ds_read_b128 v[208:211], v162 offset:49152
	ds_read_b128 v[212:215], v162 offset:50176
	ds_read_b128 v[216:219], v162 offset:51200
	ds_read_b128 v[220:223], v162 offset:52224
	ds_read_b128 v[154:157], v175 offset:32768
	ds_read_b128 v[158:161], v175 offset:33792
	ds_read_b128 v[178:181], v175 offset:34816
	ds_read_b128 v[182:185], v175 offset:35840
	ds_read_b128 v[186:189], v175 offset:36864
	ds_read_b128 v[190:193], v175 offset:37888
	ds_read_b128 v[194:197], v175 offset:38912
	ds_read_b128 v[198:201], v175 offset:39936
	s_mov_b32 m0, s85
	s_nop 0
	global_load_lds_dwordx4 v230, s[98:99]
	s_mov_b32 m0, s86
	s_nop 0
	global_load_lds_dwordx4 v231, s[98:99]
	s_waitcnt vmcnt(8)
	s_waitcnt lgkmcnt(0)
	s_setprio 1
	s_barrier
	v_mfma_f32_16x16x32_bf16 v[2:5], v[154:157], v[138:141], v[2:5]
	v_mfma_f32_16x16x32_bf16 v[6:9], v[154:157], v[146:149], v[6:9]
	v_mfma_f32_16x16x32_bf16 v[10:13], v[178:181], v[138:141], v[10:13]
	v_mfma_f32_16x16x32_bf16 v[18:21], v[178:181], v[146:149], v[18:21]
	v_mfma_f32_16x16x32_bf16 v[30:33], v[186:189], v[138:141], v[30:33]
	v_mfma_f32_16x16x32_bf16 v[42:45], v[186:189], v[146:149], v[42:45]
	v_mfma_f32_16x16x32_bf16 v[54:57], v[194:197], v[138:141], v[54:57]
	v_mfma_f32_16x16x32_bf16 v[66:69], v[194:197], v[146:149], v[66:69]
	v_mfma_f32_16x16x32_bf16 v[2:5], v[158:161], v[142:145], v[2:5]
	v_mfma_f32_16x16x32_bf16 v[6:9], v[158:161], v[150:153], v[6:9]
	v_mfma_f32_16x16x32_bf16 v[10:13], v[182:185], v[142:145], v[10:13]
	v_mfma_f32_16x16x32_bf16 v[18:21], v[182:185], v[150:153], v[18:21]
	v_mfma_f32_16x16x32_bf16 v[30:33], v[190:193], v[142:145], v[30:33]
	v_mfma_f32_16x16x32_bf16 v[42:45], v[190:193], v[150:153], v[42:45]
	v_mfma_f32_16x16x32_bf16 v[54:57], v[198:201], v[142:145], v[54:57]
	v_mfma_f32_16x16x32_bf16 v[66:69], v[198:201], v[150:153], v[66:69]
	v_mfma_f32_16x16x32_bf16 v[14:17], v[154:157], v[208:211], v[14:17]
	v_mfma_f32_16x16x32_bf16 v[22:25], v[154:157], v[216:219], v[22:25]
	v_mfma_f32_16x16x32_bf16 v[34:37], v[178:181], v[208:211], v[34:37]
	v_mfma_f32_16x16x32_bf16 v[46:49], v[178:181], v[216:219], v[46:49]
	v_mfma_f32_16x16x32_bf16 v[58:61], v[186:189], v[208:211], v[58:61]
	v_mfma_f32_16x16x32_bf16 v[70:73], v[186:189], v[216:219], v[70:73]
	v_mfma_f32_16x16x32_bf16 v[78:81], v[194:197], v[208:211], v[78:81]
	v_mfma_f32_16x16x32_bf16 v[86:89], v[194:197], v[216:219], v[86:89]
	v_mfma_f32_16x16x32_bf16 v[14:17], v[158:161], v[212:215], v[14:17]
	v_mfma_f32_16x16x32_bf16 v[22:25], v[158:161], v[220:223], v[22:25]
	v_mfma_f32_16x16x32_bf16 v[34:37], v[182:185], v[212:215], v[34:37]
	v_mfma_f32_16x16x32_bf16 v[46:49], v[182:185], v[220:223], v[46:49]
	v_mfma_f32_16x16x32_bf16 v[58:61], v[190:193], v[212:215], v[58:61]
	v_mfma_f32_16x16x32_bf16 v[70:73], v[190:193], v[220:223], v[70:73]
	v_mfma_f32_16x16x32_bf16 v[78:81], v[198:201], v[212:215], v[78:81]
	v_mfma_f32_16x16x32_bf16 v[86:89], v[198:201], v[220:223], v[86:89]
	s_barrier
	s_setprio 0
	ds_read_b128 v[154:157], v175 offset:49152
	ds_read_b128 v[158:161], v175 offset:50176
	ds_read_b128 v[178:181], v175 offset:51200
	ds_read_b128 v[182:185], v175 offset:52224
	ds_read_b128 v[186:189], v175 offset:53248
	ds_read_b128 v[190:193], v175 offset:54272
	ds_read_b128 v[194:197], v175 offset:55296
	ds_read_b128 v[198:201], v175 offset:56320
	s_mov_b32 m0, s87
	s_nop 0
	global_load_lds_dwordx4 v232, s[100:101]
	s_mov_b32 m0, s88
	s_nop 0
	global_load_lds_dwordx4 v233, s[100:101]
	s_mov_b32 m0, s89
	s_nop 0
	global_load_lds_dwordx4 v234, s[98:99]
	s_mov_b32 m0, s90
	s_nop 0
	global_load_lds_dwordx4 v235, s[98:99]
	s_mov_b32 m0, s91
	s_nop 0
	global_load_lds_dwordx4 v236, s[100:101]
	s_mov_b32 m0, s92
	s_nop 0
	global_load_lds_dwordx4 v237, s[100:101]
	s_add_i32 s35, s35, 2
	s_add_u32 s10, s10, 0x100
	s_addc_u32 s11, s11, 0
	s_add_u32 s98, s98, 0x100
	s_addc_u32 s99, s99, 0
	s_add_u32 s100, s100, 0x100
	s_addc_u32 s101, s101, 0
	s_cmp_gt_u32 s35, 27
	s_waitcnt vmcnt(8)
	s_waitcnt lgkmcnt(0)
	s_setprio 1
	s_barrier
	v_mfma_f32_16x16x32_bf16 v[26:29], v[154:157], v[138:141], v[26:29]
	v_mfma_f32_16x16x32_bf16 v[38:41], v[154:157], v[146:149], v[38:41]
	v_mfma_f32_16x16x32_bf16 v[50:53], v[178:181], v[138:141], v[50:53]
	v_mfma_f32_16x16x32_bf16 v[62:65], v[178:181], v[146:149], v[62:65]
	v_mfma_f32_16x16x32_bf16 v[74:77], v[186:189], v[138:141], v[74:77]
	v_mfma_f32_16x16x32_bf16 v[82:85], v[186:189], v[146:149], v[82:85]
	v_mfma_f32_16x16x32_bf16 v[90:93], v[194:197], v[138:141], v[90:93]
	v_mfma_f32_16x16x32_bf16 v[94:97], v[194:197], v[146:149], v[94:97]
	v_mfma_f32_16x16x32_bf16 v[26:29], v[158:161], v[142:145], v[26:29]
	v_mfma_f32_16x16x32_bf16 v[38:41], v[158:161], v[150:153], v[38:41]
	v_mfma_f32_16x16x32_bf16 v[50:53], v[182:185], v[142:145], v[50:53]
	v_mfma_f32_16x16x32_bf16 v[62:65], v[182:185], v[150:153], v[62:65]
	v_mfma_f32_16x16x32_bf16 v[74:77], v[190:193], v[142:145], v[74:77]
	v_mfma_f32_16x16x32_bf16 v[82:85], v[190:193], v[150:153], v[82:85]
	v_mfma_f32_16x16x32_bf16 v[90:93], v[198:201], v[142:145], v[90:93]
	v_mfma_f32_16x16x32_bf16 v[94:97], v[198:201], v[150:153], v[94:97]
	v_mfma_f32_16x16x32_bf16 v[98:101], v[154:157], v[208:211], v[98:101]
	v_mfma_f32_16x16x32_bf16 v[102:105], v[154:157], v[216:219], v[102:105]
	v_mfma_f32_16x16x32_bf16 v[106:109], v[178:181], v[208:211], v[106:109]
	v_mfma_f32_16x16x32_bf16 v[110:113], v[178:181], v[216:219], v[110:113]
	v_mfma_f32_16x16x32_bf16 v[114:117], v[186:189], v[208:211], v[114:117]
	v_mfma_f32_16x16x32_bf16 v[118:121], v[186:189], v[216:219], v[118:121]
	v_mfma_f32_16x16x32_bf16 v[122:125], v[194:197], v[208:211], v[122:125]
	v_mfma_f32_16x16x32_bf16 v[126:129], v[194:197], v[216:219], v[126:129]
	v_mfma_f32_16x16x32_bf16 v[98:101], v[158:161], v[212:215], v[98:101]
	v_mfma_f32_16x16x32_bf16 v[102:105], v[158:161], v[220:223], v[102:105]
	v_mfma_f32_16x16x32_bf16 v[106:109], v[182:185], v[212:215], v[106:109]
	v_mfma_f32_16x16x32_bf16 v[110:113], v[182:185], v[220:223], v[110:113]
	v_mfma_f32_16x16x32_bf16 v[114:117], v[190:193], v[212:215], v[114:117]
	v_mfma_f32_16x16x32_bf16 v[118:121], v[190:193], v[220:223], v[118:121]
	v_mfma_f32_16x16x32_bf16 v[122:125], v[198:201], v[212:215], v[122:125]
	v_mfma_f32_16x16x32_bf16 v[126:129], v[198:201], v[220:223], v[126:129]
	s_barrier
; #define LDA(dst, b, h)                                                                                     \
;   _Pragma("unroll") for (int m = 0; m < 4; ++m) _Pragma("unroll") for (int k = 0; k < 2; ++k) dst[m][k] = \
;       *reinterpret_cast<const bf16x8*>(shmc + aL + (((b) * 2 + (h)) * 16384 + (m * 2 + k) * 1024))
; #define LDB(dst, b, h)                                                                                     \
;   _Pragma("unroll") for (int n = 0; n < 2; ++n) _Pragma("unroll") for (int k = 0; k < 2; ++k) dst[n][k] = \
;       *reinterpret_cast<const bf16x8*>(shmc + bL + (((b) * 2 + (h)) * 16384 + (n * 2 + k) * 1024))
; #define OPAQ asm volatile("" : "+v"(aL), "+v"(bL))
; #define WAIT_V(n) asm volatile("s_waitcnt vmcnt(" #n ")" ::: "memory")
; #define WAIT_L(n) asm volatile("s_waitcnt lgkmcnt(" #n ")" ::: "memory")
; #define BAR __builtin_amdgcn_s_barrier()
; template <int EPI>
; __device__ __forceinline__ void phase_gemm(const Params& p, const GemmDesc& d, char* shmc) {
;     ...
;     }
;     {
;       OPAQ;
;       LDB(B0, 0, 0); LDA(At, 0, 0); STAGE_A(SA(1, 1), 1, nt - 1);
;       BAR; WAIT_L(0); MMA(0, 0, At, B0); BAR;
;       LDB(B1, 0, 1); BAR; WAIT_L(0); MMA(0, 1, At, B1); BAR;
;       LDA(At, 0, 1); WAIT_V(4); BAR; WAIT_L(0); MMA(1, 0, At, B0); MMA(1, 1, At, B1); BAR;
;     }
	s_cbranch_scc0 .LBB0_296
	s_setprio 0
	s_add_u32 s8, s8, 0x80f80
	s_addc_u32 s9, s9, 0
	v_add_u32_e32 v162, 0, v205
	v_add_u32_e32 v175, 0, v204
	s_mov_b32 m0, s93
	ds_read_b128 v[130:133], v162
	ds_read_b128 v[134:137], v162 offset:1024
	ds_read_b128 v[138:141], v162 offset:2048
	ds_read_b128 v[142:145], v162 offset:3072
	ds_read_b128 v[146:149], v175
	ds_read_b128 v[150:153], v175 offset:1024
	ds_read_b128 v[154:157], v175 offset:2048
	ds_read_b128 v[158:161], v175 offset:3072
	ds_read_b128 v[178:181], v175 offset:4096
	ds_read_b128 v[182:185], v175 offset:5120
	ds_read_b128 v[186:189], v175 offset:6144
	ds_read_b128 v[190:193], v175 offset:7168
	global_load_lds_dwordx4 v174, s[8:9]
	s_mov_b32 m0, s94
	s_nop 0
	global_load_lds_dwordx4 v176, s[8:9]
	s_waitcnt vmcnt(8)
	s_barrier
	s_waitcnt lgkmcnt(0)
	s_setprio 1
	s_waitcnt lgkmcnt(0)
	v_mfma_f32_16x16x32_bf16 v[2:5], v[146:149], v[130:133], v[2:5]
	v_mfma_f32_16x16x32_bf16 v[6:9], v[146:149], v[138:141], v[6:9]
	v_mfma_f32_16x16x32_bf16 v[10:13], v[154:157], v[130:133], v[10:13]
	v_mfma_f32_16x16x32_bf16 v[18:21], v[154:157], v[138:141], v[18:21]
	v_mfma_f32_16x16x32_bf16 v[66:69], v[186:189], v[138:141], v[66:69]
	v_mfma_f32_16x16x32_bf16 v[2:5], v[150:153], v[134:137], v[2:5]
	v_mfma_f32_16x16x32_bf16 v[6:9], v[150:153], v[142:145], v[6:9]
	v_mfma_f32_16x16x32_bf16 v[10:13], v[158:161], v[134:137], v[10:13]
	v_mfma_f32_16x16x32_bf16 v[18:21], v[158:161], v[142:145], v[18:21]
	v_mfma_f32_16x16x32_bf16 v[30:33], v[178:181], v[130:133], v[30:33]
	v_mfma_f32_16x16x32_bf16 v[42:45], v[178:181], v[138:141], v[42:45]
	v_mfma_f32_16x16x32_bf16 v[54:57], v[186:189], v[130:133], v[54:57]
	v_mfma_f32_16x16x32_bf16 v[66:69], v[190:193], v[142:145], v[66:69]
	v_mfma_f32_16x16x32_bf16 v[30:33], v[182:185], v[134:137], v[30:33]
	v_mfma_f32_16x16x32_bf16 v[42:45], v[182:185], v[142:145], v[42:45]
	v_mfma_f32_16x16x32_bf16 v[54:57], v[190:193], v[134:137], v[54:57]
	s_setprio 0
	s_barrier
	ds_read_b128 v[194:197], v162 offset:16384
	ds_read_b128 v[198:201], v162 offset:17408
	ds_read_b128 v[208:211], v162 offset:18432
	ds_read_b128 v[212:215], v162 offset:19456
	s_barrier
	s_waitcnt lgkmcnt(0)
	s_setprio 1
	s_waitcnt lgkmcnt(0)
	v_mfma_f32_16x16x32_bf16 v[14:17], v[146:149], v[194:197], v[14:17]
	v_mfma_f32_16x16x32_bf16 v[22:25], v[146:149], v[208:211], v[22:25]
	v_mfma_f32_16x16x32_bf16 v[58:61], v[178:181], v[194:197], v[58:61]
	v_mfma_f32_16x16x32_bf16 v[14:17], v[150:153], v[198:201], v[14:17]
	v_mfma_f32_16x16x32_bf16 v[22:25], v[150:153], v[212:215], v[22:25]
	v_mfma_f32_16x16x32_bf16 v[150:153], v[182:185], v[198:201], v[58:61]
	v_mfma_f32_16x16x32_bf16 v[58:61], v[178:181], v[208:211], v[70:73]
	v_mfma_f32_16x16x32_bf16 v[34:37], v[154:157], v[194:197], v[34:37]
	v_mfma_f32_16x16x32_bf16 v[46:49], v[154:157], v[208:211], v[46:49]
	v_mfma_f32_16x16x32_bf16 v[154:157], v[182:185], v[212:215], v[58:61]
	v_mfma_f32_16x16x32_bf16 v[58:61], v[186:189], v[194:197], v[78:81]
	v_mfma_f32_16x16x32_bf16 v[78:81], v[190:193], v[198:201], v[58:61]
	v_mfma_f32_16x16x32_bf16 v[58:61], v[186:189], v[208:211], v[86:89]
	v_mfma_f32_16x16x32_bf16 v[86:89], v[190:193], v[212:215], v[58:61]
	v_mfma_f32_16x16x32_bf16 v[34:37], v[158:161], v[198:201], v[34:37]
	v_mfma_f32_16x16x32_bf16 v[46:49], v[158:161], v[212:215], v[46:49]
	s_setprio 0
	s_barrier
	s_nop 2
	ds_read_b128 v[58:61], v175 offset:16384
	ds_read_b128 v[70:73], v175 offset:17408
	ds_read_b128 v[146:149], v175 offset:18432
	ds_read_b128 v[158:161], v175 offset:19456
	ds_read_b128 v[178:181], v175 offset:20480
	ds_read_b128 v[182:185], v175 offset:21504
	ds_read_b128 v[186:189], v175 offset:22528
	ds_read_b128 v[190:193], v175 offset:23552
	s_waitcnt vmcnt(4)
	s_barrier
	s_waitcnt lgkmcnt(0)
	s_setprio 1
	s_waitcnt lgkmcnt(0)
	v_mfma_f32_16x16x32_bf16 v[74:77], v[178:181], v[130:133], v[74:77]
	v_mfma_f32_16x16x32_bf16 v[216:219], v[182:185], v[134:137], v[74:77]
	v_mfma_f32_16x16x32_bf16 v[74:77], v[178:181], v[138:141], v[82:85]
	v_mfma_f32_16x16x32_bf16 v[26:29], v[58:61], v[130:133], v[26:29]
	v_mfma_f32_16x16x32_bf16 v[82:85], v[182:185], v[142:145], v[74:77]
	v_mfma_f32_16x16x32_bf16 v[74:77], v[186:189], v[130:133], v[90:93]
	v_mfma_f32_16x16x32_bf16 v[26:29], v[70:73], v[134:137], v[26:29]
	v_mfma_f32_16x16x32_bf16 v[38:41], v[58:61], v[138:141], v[38:41]
	v_mfma_f32_16x16x32_bf16 v[50:53], v[146:149], v[130:133], v[50:53]
	v_mfma_f32_16x16x32_bf16 v[62:65], v[146:149], v[138:141], v[62:65]
	v_mfma_f32_16x16x32_bf16 v[90:93], v[190:193], v[134:137], v[74:77]
	v_mfma_f32_16x16x32_bf16 v[74:77], v[186:189], v[138:141], v[94:97]
	v_mfma_f32_16x16x32_bf16 v[38:41], v[70:73], v[142:145], v[38:41]
	v_mfma_f32_16x16x32_bf16 v[50:53], v[158:161], v[134:137], v[50:53]
	v_mfma_f32_16x16x32_bf16 v[62:65], v[158:161], v[142:145], v[62:65]
	v_mfma_f32_16x16x32_bf16 v[220:223], v[190:193], v[142:145], v[74:77]
	s_setprio 0
	s_setprio 1
	v_mfma_f32_16x16x32_bf16 v[74:77], v[58:61], v[194:197], v[98:101]
	v_mfma_f32_16x16x32_bf16 v[58:61], v[58:61], v[208:211], v[102:105]
	v_mfma_f32_16x16x32_bf16 v[228:231], v[70:73], v[212:215], v[58:61]
	v_mfma_f32_16x16x32_bf16 v[58:61], v[146:149], v[194:197], v[106:109]
	v_mfma_f32_16x16x32_bf16 v[232:235], v[158:161], v[198:201], v[58:61]
	v_mfma_f32_16x16x32_bf16 v[58:61], v[146:149], v[208:211], v[110:113]
	v_mfma_f32_16x16x32_bf16 v[236:239], v[158:161], v[212:215], v[58:61]
	v_mfma_f32_16x16x32_bf16 v[58:61], v[178:181], v[194:197], v[114:117]
	v_mfma_f32_16x16x32_bf16 v[240:243], v[182:185], v[198:201], v[58:61]
	v_mfma_f32_16x16x32_bf16 v[58:61], v[178:181], v[208:211], v[118:121]
	v_mfma_f32_16x16x32_bf16 v[178:181], v[182:185], v[212:215], v[58:61]
	v_mfma_f32_16x16x32_bf16 v[58:61], v[186:189], v[194:197], v[122:125]
	v_mfma_f32_16x16x32_bf16 v[182:185], v[190:193], v[198:201], v[58:61]
	v_mfma_f32_16x16x32_bf16 v[58:61], v[186:189], v[208:211], v[126:129]
	v_mfma_f32_16x16x32_bf16 v[224:227], v[70:73], v[198:201], v[74:77]
	v_mfma_f32_16x16x32_bf16 v[186:189], v[190:193], v[212:215], v[58:61]
	s_setprio 0
	s_barrier
; #define LDA(dst, b, h)                                                                                     \
;   _Pragma("unroll") for (int m = 0; m < 4; ++m) _Pragma("unroll") for (int k = 0; k < 2; ++k) dst[m][k] = \
;       *reinterpret_cast<const bf16x8*>(shmc + aL + (((b) * 2 + (h)) * 16384 + (m * 2 + k) * 1024))
; #define LDB(dst, b, h)                                                                                     \
;   _Pragma("unroll") for (int n = 0; n < 2; ++n) _Pragma("unroll") for (int k = 0; k < 2; ++k) dst[n][k] = \
;       *reinterpret_cast<const bf16x8*>(shmc + bL + (((b) * 2 + (h)) * 16384 + (n * 2 + k) * 1024))
; #define WAIT_V(n) asm volatile("s_waitcnt vmcnt(" #n ")" ::: "memory")
; #define WAIT_L(n) asm volatile("s_waitcnt lgkmcnt(" #n ")" ::: "memory")
; #define BAR __builtin_amdgcn_s_barrier()
; template <int EPI>
; __device__ __forceinline__ void phase_gemm(const Params& p, const GemmDesc& d, char* shmc) {
;     ...
;     {
;       LDB(B0, 1, 0); LDA(At, 1, 0); WAIT_V(2); BAR; WAIT_L(0); MMA(0, 0, At, B0); BAR;
;       LDB(B1, 1, 1); WAIT_V(0); BAR; WAIT_L(0); MMA(0, 1, At, B1); BAR;
;       LDA(At, 1, 1); BAR; WAIT_L(0); MMA(1, 0, At, B0); MMA(1, 1, At, B1); BAR;
;     }
;     if (wr == 0) BAR;
	ds_read_b128 v[98:101], v162 offset:32768
	ds_read_b128 v[106:109], v162 offset:33792
	ds_read_b128 v[190:193], v162 offset:34816
	ds_read_b128 v[194:197], v162 offset:35840
	ds_read_b128 v[58:61], v175 offset:32768
	ds_read_b128 v[70:73], v175 offset:33792
	ds_read_b128 v[114:117], v175 offset:34816
	ds_read_b128 v[122:125], v175 offset:35840
	ds_read_b128 v[130:133], v175 offset:36864
	ds_read_b128 v[138:141], v175 offset:37888
	ds_read_b128 v[198:201], v175 offset:38912
	ds_read_b128 v[208:211], v175 offset:39936
	s_waitcnt vmcnt(2)
	s_barrier
	s_waitcnt lgkmcnt(0)
	s_setprio 1
	s_waitcnt lgkmcnt(0)
	v_mfma_f32_16x16x32_bf16 v[2:5], v[58:61], v[98:101], v[2:5]
	v_mfma_f32_16x16x32_bf16 v[158:161], v[70:73], v[106:109], v[2:5]
	v_mfma_f32_16x16x32_bf16 v[2:5], v[58:61], v[190:193], v[6:9]
	v_mfma_f32_16x16x32_bf16 v[146:149], v[70:73], v[194:197], v[2:5]
	v_mfma_f32_16x16x32_bf16 v[2:5], v[114:117], v[98:101], v[10:13]
	v_mfma_f32_16x16x32_bf16 v[142:145], v[122:125], v[106:109], v[2:5]
	v_mfma_f32_16x16x32_bf16 v[2:5], v[114:117], v[190:193], v[18:21]
	v_mfma_f32_16x16x32_bf16 v[134:137], v[122:125], v[194:197], v[2:5]
	v_mfma_f32_16x16x32_bf16 v[2:5], v[130:133], v[98:101], v[30:33]
	v_mfma_f32_16x16x32_bf16 v[126:129], v[138:141], v[106:109], v[2:5]
	v_mfma_f32_16x16x32_bf16 v[2:5], v[130:133], v[190:193], v[42:45]
	v_mfma_f32_16x16x32_bf16 v[118:121], v[138:141], v[194:197], v[2:5]
	v_mfma_f32_16x16x32_bf16 v[2:5], v[198:201], v[98:101], v[54:57]
	v_mfma_f32_16x16x32_bf16 v[110:113], v[208:211], v[106:109], v[2:5]
	v_mfma_f32_16x16x32_bf16 v[2:5], v[198:201], v[190:193], v[66:69]
	v_mfma_f32_16x16x32_bf16 v[102:105], v[208:211], v[194:197], v[2:5]
	s_setprio 0
	s_barrier
	ds_read_b128 v[30:33], v162 offset:49152
	ds_read_b128 v[42:45], v162 offset:50176
	ds_read_b128 v[54:57], v162 offset:51200
	ds_read_b128 v[212:215], v162 offset:52224
	s_waitcnt vmcnt(0)
	s_barrier
	s_waitcnt lgkmcnt(0)
	s_setprio 1
	s_waitcnt lgkmcnt(0)
	v_mfma_f32_16x16x32_bf16 v[2:5], v[58:61], v[30:33], v[14:17]
	v_mfma_f32_16x16x32_bf16 v[94:97], v[70:73], v[42:45], v[2:5]
	v_mfma_f32_16x16x32_bf16 v[2:5], v[58:61], v[54:57], v[22:25]
	v_mfma_f32_16x16x32_bf16 v[58:61], v[70:73], v[212:215], v[2:5]
	v_mfma_f32_16x16x32_bf16 v[2:5], v[114:117], v[30:33], v[34:37]
	v_mfma_f32_16x16x32_bf16 v[74:77], v[122:125], v[42:45], v[2:5]
	v_mfma_f32_16x16x32_bf16 v[2:5], v[114:117], v[54:57], v[46:49]
	v_mfma_f32_16x16x32_bf16 v[10:13], v[122:125], v[212:215], v[2:5]
	v_mfma_f32_16x16x32_bf16 v[2:5], v[130:133], v[30:33], v[150:153]
	v_mfma_f32_16x16x32_bf16 v[70:73], v[138:141], v[42:45], v[2:5]
	v_mfma_f32_16x16x32_bf16 v[2:5], v[130:133], v[54:57], v[154:157]
	v_mfma_f32_16x16x32_bf16 v[6:9], v[138:141], v[212:215], v[2:5]
	v_mfma_f32_16x16x32_bf16 v[2:5], v[198:201], v[30:33], v[78:81]
	v_mfma_f32_16x16x32_bf16 v[66:69], v[208:211], v[42:45], v[2:5]
	v_mfma_f32_16x16x32_bf16 v[2:5], v[198:201], v[54:57], v[86:89]
	v_mfma_f32_16x16x32_bf16 v[2:5], v[208:211], v[212:215], v[2:5]
	s_setprio 0
	s_barrier
	ds_read_b128 v[14:17], v175 offset:49152
	ds_read_b128 v[18:21], v175 offset:50176
	ds_read_b128 v[22:25], v175 offset:51200
	ds_read_b128 v[34:37], v175 offset:52224
	ds_read_b128 v[46:49], v175 offset:53248
	ds_read_b128 v[78:81], v175 offset:54272
	ds_read_b128 v[198:201], v175 offset:55296
	ds_read_b128 v[208:211], v175 offset:56320
	s_barrier
	s_waitcnt lgkmcnt(0)
	s_setprio 1
	s_waitcnt lgkmcnt(0)
	v_mfma_f32_16x16x32_bf16 v[26:29], v[14:17], v[98:101], v[26:29]
	v_mfma_f32_16x16x32_bf16 v[154:157], v[18:21], v[106:109], v[26:29]
	v_mfma_f32_16x16x32_bf16 v[26:29], v[14:17], v[190:193], v[38:41]
	v_mfma_f32_16x16x32_bf16 v[150:153], v[18:21], v[194:197], v[26:29]
	v_mfma_f32_16x16x32_bf16 v[26:29], v[22:25], v[98:101], v[50:53]
	v_mfma_f32_16x16x32_bf16 v[138:141], v[34:37], v[106:109], v[26:29]
	v_mfma_f32_16x16x32_bf16 v[26:29], v[22:25], v[190:193], v[62:65]
	v_mfma_f32_16x16x32_bf16 v[130:133], v[34:37], v[194:197], v[26:29]
	v_mfma_f32_16x16x32_bf16 v[26:29], v[46:49], v[98:101], v[216:219]
	v_mfma_f32_16x16x32_bf16 v[122:125], v[78:81], v[106:109], v[26:29]
	v_mfma_f32_16x16x32_bf16 v[26:29], v[46:49], v[190:193], v[82:85]
	v_mfma_f32_16x16x32_bf16 v[114:117], v[78:81], v[194:197], v[26:29]
	v_mfma_f32_16x16x32_bf16 v[26:29], v[198:201], v[98:101], v[90:93]
	v_mfma_f32_16x16x32_bf16 v[106:109], v[208:211], v[106:109], v[26:29]
	v_mfma_f32_16x16x32_bf16 v[26:29], v[198:201], v[190:193], v[220:223]
	v_mfma_f32_16x16x32_bf16 v[98:101], v[208:211], v[194:197], v[26:29]
	s_setprio 0
	s_setprio 1
	v_mfma_f32_16x16x32_bf16 v[26:29], v[14:17], v[30:33], v[224:227]
	v_mfma_f32_16x16x32_bf16 v[14:17], v[14:17], v[54:57], v[228:231]
	v_mfma_f32_16x16x32_bf16 v[90:93], v[18:21], v[42:45], v[26:29]
	v_mfma_f32_16x16x32_bf16 v[26:29], v[18:21], v[212:215], v[14:17]
	v_mfma_f32_16x16x32_bf16 v[14:17], v[22:25], v[30:33], v[232:235]
	v_mfma_f32_16x16x32_bf16 v[86:89], v[34:37], v[42:45], v[14:17]
	v_mfma_f32_16x16x32_bf16 v[14:17], v[22:25], v[54:57], v[236:239]
	v_mfma_f32_16x16x32_bf16 v[22:25], v[34:37], v[212:215], v[14:17]
	v_mfma_f32_16x16x32_bf16 v[14:17], v[46:49], v[30:33], v[240:243]
	v_mfma_f32_16x16x32_bf16 v[82:85], v[78:81], v[42:45], v[14:17]
	v_mfma_f32_16x16x32_bf16 v[14:17], v[46:49], v[54:57], v[178:181]
	v_mfma_f32_16x16x32_bf16 v[18:21], v[78:81], v[212:215], v[14:17]
	v_mfma_f32_16x16x32_bf16 v[14:17], v[198:201], v[30:33], v[182:185]
	v_mfma_f32_16x16x32_bf16 v[78:81], v[208:211], v[42:45], v[14:17]
	v_mfma_f32_16x16x32_bf16 v[14:17], v[198:201], v[54:57], v[186:189]
	v_mfma_f32_16x16x32_bf16 v[14:17], v[208:211], v[212:215], v[14:17]
	s_setprio 0
	s_barrier
	s_and_saveexec_b64 s[8:9], s[6:7]
	s_cbranch_execz .LBB0_299
	s_barrier

; #define WAIT_V(n) asm volatile("s_waitcnt vmcnt(" #n ")" ::: "memory")
; #define BAR __builtin_amdgcn_s_barrier()
; template <int EPI>
; __device__ __forceinline__ void phase_gemm(const Params& p, const GemmDesc& d, char* shmc) {
;     ...
;     f32x4 acc[2][2][4][2];
; #pragma unroll
;     for (int a = 0; a < 2; ++a)
; #pragma unroll
;       for (int b = 0; b < 2; ++b)
; #pragma unroll
;         for (int m = 0; m < 4; ++m)
; #pragma unroll
;           for (int n = 0; n < 2; ++n) acc[a][b][m][n] = f32x4{0.f, 0.f, 0.f, 0.f};
;     bf16x8 At[4][2], B0[2][2], B1[2][2];
;     if constexpr (EPI == EPI_UP || EPI == EPI_QKV) {
;       if (wid == 0)
;         __builtin_amdgcn_global_load_lds((const unsigned*)(p.rstd + brow + lane * 4), (unsigned*)(shmc + 143360), 16, 0, 0);
;     }
;     STAGE_B(SB(0, 0), 0, 0); STAGE_A(SA(0, 0), 0, 0);
;     STAGE_B(SB(0, 1), 1, 0); STAGE_A(SA(0, 1), 1, 0);
;     if (wr == 1) BAR;
;     WAIT_V(4); BAR;
;     STAGE_B(SB(1, 0), 0, 1); STAGE_A(SA(1, 0), 0, 1); STAGE_B(SB(1, 1), 1, 1);
;     WAIT_V(6); BAR;
;     for (int t = 0; t < nt - 2; t += 2) {
.LBB0_454:
	s_or_b64 exec, exec, s[56:57]
	v_mov_b32_e32 v141, v131
	s_waitcnt lgkmcnt(0)
	v_lshl_add_u64 v[2:3], s[54:55], 0, v[140:141]
	v_mov_b32_e32 v143, v131
	s_mov_b32 m0, s62
	v_lshl_add_u64 v[4:5], s[54:55], 0, v[142:143]
	v_lshl_add_u64 v[2:3], v[2:3], 0, s[8:9]
	v_lshl_add_u64 v[6:7], s[48:49], 0, v[140:141]
	v_mov_b32_e32 v10, 0
	v_mov_b32_e32 v11, 0
	v_mov_b32_e32 v12, 0
	v_mov_b32_e32 v13, 0
	v_mov_b32_e32 v14, 0
	v_mov_b32_e32 v15, 0
	v_mov_b32_e32 v16, 0
	v_mov_b32_e32 v17, 0
	v_mov_b32_e32 v18, 0
	v_mov_b32_e32 v19, 0
	v_mov_b32_e32 v20, 0
	v_mov_b32_e32 v21, 0
	v_mov_b32_e32 v22, 0
	v_mov_b32_e32 v23, 0
	v_mov_b32_e32 v24, 0
	v_mov_b32_e32 v25, 0
	v_mov_b32_e32 v26, 0
	v_mov_b32_e32 v27, 0
	v_mov_b32_e32 v28, 0
	v_mov_b32_e32 v29, 0
	v_mov_b32_e32 v30, 0
	v_mov_b32_e32 v31, 0
	v_mov_b32_e32 v32, 0
	v_mov_b32_e32 v33, 0
	v_mov_b32_e32 v34, 0
	v_mov_b32_e32 v35, 0
	v_mov_b32_e32 v36, 0
	v_mov_b32_e32 v37, 0
	v_mov_b32_e32 v38, 0
	v_mov_b32_e32 v39, 0
	v_mov_b32_e32 v40, 0
	v_mov_b32_e32 v41, 0
	v_mov_b32_e32 v42, 0
	v_mov_b32_e32 v43, 0
	v_mov_b32_e32 v44, 0
	v_mov_b32_e32 v45, 0
	v_mov_b32_e32 v46, 0
	v_mov_b32_e32 v47, 0
	v_mov_b32_e32 v48, 0
	v_mov_b32_e32 v49, 0
	v_mov_b32_e32 v50, 0
	v_mov_b32_e32 v51, 0
	v_mov_b32_e32 v52, 0
	v_mov_b32_e32 v53, 0
	v_mov_b32_e32 v54, 0
	v_mov_b32_e32 v55, 0
	v_mov_b32_e32 v56, 0
	v_mov_b32_e32 v57, 0
	v_mov_b32_e32 v70, 0
	v_mov_b32_e32 v71, 0
	v_mov_b32_e32 v72, 0
	v_mov_b32_e32 v73, 0
	v_mov_b32_e32 v86, 0
	v_mov_b32_e32 v87, 0
	v_mov_b32_e32 v88, 0
	v_mov_b32_e32 v89, 0
	v_mov_b32_e32 v98, 0
	v_mov_b32_e32 v99, 0
	v_mov_b32_e32 v100, 0
	v_mov_b32_e32 v101, 0
	v_mov_b32_e32 v102, 0
	v_mov_b32_e32 v103, 0
	v_mov_b32_e32 v104, 0
	v_mov_b32_e32 v105, 0
	v_mov_b32_e32 v106, 0
	v_mov_b32_e32 v107, 0
	v_mov_b32_e32 v108, 0
	v_mov_b32_e32 v109, 0
	v_mov_b32_e32 v110, 0
	v_mov_b32_e32 v111, 0
	v_mov_b32_e32 v112, 0
	v_mov_b32_e32 v113, 0
	v_mov_b32_e32 v114, 0
	v_mov_b32_e32 v115, 0
	v_mov_b32_e32 v116, 0
	v_mov_b32_e32 v117, 0
	v_mov_b32_e32 v118, 0
	v_mov_b32_e32 v119, 0
	v_mov_b32_e32 v120, 0
	v_mov_b32_e32 v121, 0
	v_mov_b32_e32 v122, 0
	v_mov_b32_e32 v123, 0
	v_mov_b32_e32 v124, 0
	v_mov_b32_e32 v125, 0
	v_mov_b32_e32 v126, 0
	v_mov_b32_e32 v127, 0
	v_mov_b32_e32 v128, 0
	v_mov_b32_e32 v129, 0
	v_mov_b32_e32 v58, 0
	v_mov_b32_e32 v59, 0
	v_mov_b32_e32 v60, 0
	v_mov_b32_e32 v61, 0
	v_mov_b32_e32 v62, 0
	v_mov_b32_e32 v63, 0
	v_mov_b32_e32 v64, 0
	v_mov_b32_e32 v65, 0
	v_mov_b32_e32 v66, 0
	v_mov_b32_e32 v67, 0
	v_mov_b32_e32 v68, 0
	v_mov_b32_e32 v69, 0
	v_mov_b32_e32 v74, 0
	v_mov_b32_e32 v75, 0
	v_mov_b32_e32 v76, 0
	v_mov_b32_e32 v77, 0
	v_mov_b32_e32 v78, 0
	v_mov_b32_e32 v79, 0
	v_mov_b32_e32 v80, 0
	v_mov_b32_e32 v81, 0
	v_mov_b32_e32 v82, 0
	v_mov_b32_e32 v83, 0
	v_mov_b32_e32 v84, 0
	v_mov_b32_e32 v85, 0
	v_mov_b32_e32 v90, 0
	v_mov_b32_e32 v91, 0
	v_mov_b32_e32 v92, 0
	v_mov_b32_e32 v93, 0
	v_mov_b32_e32 v94, 0
	v_mov_b32_e32 v95, 0
	v_mov_b32_e32 v96, 0
	v_mov_b32_e32 v97, 0
	s_waitcnt vmcnt(2)
	s_barrier
	global_load_lds_dwordx4 v[2:3], off
	v_lshl_add_u64 v[2:3], v[4:5], 0, s[8:9]
	s_mov_b32 m0, s63
	v_lshl_add_u64 v[8:9], s[48:49], 0, v[142:143]
	global_load_lds_dwordx4 v[2:3], off
	v_lshl_add_u64 v[2:3], v[6:7], 0, s[8:9]
	s_mov_b32 m0, s64
	s_add_u32 s54, s54, 0x160080
	global_load_lds_dwordx4 v[2:3], off
	v_lshl_add_u64 v[2:3], v[8:9], 0, s[8:9]
	s_mov_b32 m0, s65
	s_addc_u32 s55, s55, 0
	global_load_lds_dwordx4 v[2:3], off
	s_mov_b32 m0, s68
	s_add_i32 s79, s79, s80
	global_load_lds_dwordx4 v140, s[54:55]
	s_mov_b32 m0, s69
	v_lshl_add_u64 v[144:145], v[132:133], 0, s[52:53]
	global_load_lds_dwordx4 v142, s[54:55]
	s_waitcnt vmcnt(6)
	v_lshl_add_u64 v[146:147], v[134:135], 0, s[52:53]
	v_mad_i64_i32 v[148:149], s[52:53], s79, v154, v[136:137]
	v_mad_i64_i32 v[150:151], s[52:53], s79, v154, v[138:139]
	v_mov_b32_e32 v2, 0
	s_mov_b32 s54, -2
	s_mov_b64 s[52:53], 0
	v_mov_b32_e32 v3, v2
	v_mov_b32_e32 v4, v2
	v_mov_b32_e32 v5, v2
	v_mov_b32_e32 v6, v2
	v_mov_b32_e32 v7, v2
	v_mov_b32_e32 v8, v2
	v_mov_b32_e32 v9, v2
	s_barrier
	v_readfirstlane_b32 s98, v148
	v_readfirstlane_b32 s99, v149
	v_readfirstlane_b32 s100, v144
	v_readfirstlane_b32 s101, v145
	s_nop 3
	v_subrev_u32_e32 v220, s98, v148
	v_add_u32_e32 v220, s10, v220
	v_subrev_u32_e32 v221, s98, v150
	v_add_u32_e32 v221, s10, v221
	v_subrev_u32_e32 v222, s100, v144
	v_add_u32_e32 v222, s26, v222
	v_subrev_u32_e32 v223, s100, v146
	v_add_u32_e32 v223, s26, v223
	v_subrev_u32_e32 v224, s98, v148
	v_add_u32_e32 v224, s26, v224
	v_subrev_u32_e32 v225, s98, v150
	v_add_u32_e32 v225, s26, v225
	v_subrev_u32_e32 v226, s100, v144
	v_add_u32_e32 v226, s38, v226
	v_subrev_u32_e32 v227, s100, v146
	v_add_u32_e32 v227, s38, v227
	v_subrev_u32_e32 v228, s98, v148
	v_add_u32_e32 v228, s38, v228
	v_subrev_u32_e32 v229, s98, v150
	v_add_u32_e32 v229, s38, v229
	v_subrev_u32_e32 v232, s100, v144
	v_add_u32_e32 v232, s40, v232
	v_subrev_u32_e32 v233, s100, v146
	v_add_u32_e32 v233, s40, v233
	v_subrev_u32_e32 v234, s98, v148
	v_add_u32_e32 v234, s40, v234
	v_subrev_u32_e32 v235, s98, v150
	v_add_u32_e32 v235, s40, v235
	v_subrev_u32_e32 v236, s100, v144
	v_add_u32_e32 v236, s42, v236
	v_subrev_u32_e32 v237, s100, v146
	v_add_u32_e32 v237, s42, v237
	s_add_u32 s98, s98, s52
	s_addc_u32 s99, s99, s53
	s_add_u32 s100, s100, s52
	s_addc_u32 s101, s101, s53
; #define LDA(dst, b, h)                                                                                     \
;   _Pragma("unroll") for (int m = 0; m < 4; ++m) _Pragma("unroll") for (int k = 0; k < 2; ++k) dst[m][k] = \
;       *reinterpret_cast<const bf16x8*>(shmc + aL + (((b) * 2 + (h)) * 16384 + (m * 2 + k) * 1024))
; #define LDB(dst, b, h)                                                                                     \
;   _Pragma("unroll") for (int n = 0; n < 2; ++n) _Pragma("unroll") for (int k = 0; k < 2; ++k) dst[n][k] = \
;       *reinterpret_cast<const bf16x8*>(shmc + bL + (((b) * 2 + (h)) * 16384 + (n * 2 + k) * 1024))
; #define OPAQ asm volatile("" : "+v"(aL), "+v"(bL))
; #define WAIT_V(n) asm volatile("s_waitcnt vmcnt(" #n ")" ::: "memory")
; #define WAIT_L(n) asm volatile("s_waitcnt lgkmcnt(" #n ")" ::: "memory")
; #define BAR __builtin_amdgcn_s_barrier()
; #define SCHED __builtin_amdgcn_sched_barrier(0)
; template <int EPI>
; __device__ __forceinline__ void phase_gemm(const Params& p, const GemmDesc& d, char* shmc) {
;     ...
;     for (int t = 0; t < nt - 2; t += 2) {
;       OPAQ;
;       LDB(B0, 0, 0); SCHED; LDA(At, 0, 0); STAGE_A(SA(1, 1), 1, t + 1);
;       WAIT_L(8); BAR; WAIT_L(0); MMA(0, 0, At, B0); BAR; SCHED;
;       LDB(B1, 0, 1); STAGE_B(SB(0, 0), 0, t + 2);
;       BAR; WAIT_L(0); MMA(0, 1, At, B1); BAR;
;       LDA(At, 0, 1); STAGE_A(SA(0, 0), 0, t + 2);
;       BAR; WAIT_L(0); MMA(1, 0, At, B0); BAR; SCHED;
;       STAGE_B(SB(0, 1), 1, t + 2);
;       WAIT_V(6); BAR; MMA(1, 1, At, B1); BAR;
.LBB0_455:
	s_nop 0
	v_add_u32_e32 v130, 0, v153
	v_add_u32_e32 v141, 0, v152
	s_setprio 0
	ds_read_b128 v[156:159], v130
	ds_read_b128 v[160:163], v130 offset:1024
	ds_read_b128 v[164:167], v130 offset:2048
	ds_read_b128 v[168:171], v130 offset:3072
	ds_read_b128 v[204:207], v130 offset:16384
	ds_read_b128 v[208:211], v130 offset:17408
	ds_read_b128 v[212:215], v130 offset:18432
	ds_read_b128 v[216:219], v130 offset:19456
	ds_read_b128 v[172:175], v141
	ds_read_b128 v[176:179], v141 offset:1024
	ds_read_b128 v[180:183], v141 offset:2048
	ds_read_b128 v[184:187], v141 offset:3072
	ds_read_b128 v[188:191], v141 offset:4096
	ds_read_b128 v[192:195], v141 offset:5120
	ds_read_b128 v[196:199], v141 offset:6144
	ds_read_b128 v[200:203], v141 offset:7168
	s_mov_b32 m0, s70
	s_nop 0
	global_load_lds_dwordx4 v220, s[98:99]
	s_mov_b32 m0, s71
	s_nop 0
	global_load_lds_dwordx4 v221, s[98:99]
	s_waitcnt vmcnt(8)
	s_waitcnt lgkmcnt(0)
	s_setprio 1
	s_barrier
	v_mfma_f32_16x16x32_bf16 v[126:129], v[156:159], v[172:175], v[126:129]
	v_mfma_f32_16x16x32_bf16 v[122:125], v[164:167], v[172:175], v[122:125]
	v_mfma_f32_16x16x32_bf16 v[118:121], v[156:159], v[180:183], v[118:121]
	v_mfma_f32_16x16x32_bf16 v[114:117], v[164:167], v[180:183], v[114:117]
	v_mfma_f32_16x16x32_bf16 v[110:113], v[156:159], v[188:191], v[110:113]
	v_mfma_f32_16x16x32_bf16 v[106:109], v[164:167], v[188:191], v[106:109]
	v_mfma_f32_16x16x32_bf16 v[102:105], v[156:159], v[196:199], v[102:105]
	v_mfma_f32_16x16x32_bf16 v[98:101], v[164:167], v[196:199], v[98:101]
	v_mfma_f32_16x16x32_bf16 v[126:129], v[160:163], v[176:179], v[126:129]
	v_mfma_f32_16x16x32_bf16 v[122:125], v[168:171], v[176:179], v[122:125]
	v_mfma_f32_16x16x32_bf16 v[118:121], v[160:163], v[184:187], v[118:121]
	v_mfma_f32_16x16x32_bf16 v[114:117], v[168:171], v[184:187], v[114:117]
	v_mfma_f32_16x16x32_bf16 v[110:113], v[160:163], v[192:195], v[110:113]
	v_mfma_f32_16x16x32_bf16 v[106:109], v[168:171], v[192:195], v[106:109]
	v_mfma_f32_16x16x32_bf16 v[102:105], v[160:163], v[200:203], v[102:105]
	v_mfma_f32_16x16x32_bf16 v[98:101], v[168:171], v[200:203], v[98:101]
	v_mfma_f32_16x16x32_bf16 v[86:89], v[204:207], v[172:175], v[86:89]
	v_mfma_f32_16x16x32_bf16 v[70:73], v[212:215], v[172:175], v[70:73]
	v_mfma_f32_16x16x32_bf16 v[54:57], v[204:207], v[180:183], v[54:57]
	v_mfma_f32_16x16x32_bf16 v[50:53], v[212:215], v[180:183], v[50:53]
	v_mfma_f32_16x16x32_bf16 v[46:49], v[204:207], v[188:191], v[46:49]
	v_mfma_f32_16x16x32_bf16 v[42:45], v[212:215], v[188:191], v[42:45]
	v_mfma_f32_16x16x32_bf16 v[38:41], v[204:207], v[196:199], v[38:41]
	v_mfma_f32_16x16x32_bf16 v[34:37], v[212:215], v[196:199], v[34:37]
	v_mfma_f32_16x16x32_bf16 v[86:89], v[208:211], v[176:179], v[86:89]
	v_mfma_f32_16x16x32_bf16 v[70:73], v[216:219], v[176:179], v[70:73]
	v_mfma_f32_16x16x32_bf16 v[54:57], v[208:211], v[184:187], v[54:57]
	v_mfma_f32_16x16x32_bf16 v[50:53], v[216:219], v[184:187], v[50:53]
	v_mfma_f32_16x16x32_bf16 v[46:49], v[208:211], v[192:195], v[46:49]
	v_mfma_f32_16x16x32_bf16 v[42:45], v[216:219], v[192:195], v[42:45]
	v_mfma_f32_16x16x32_bf16 v[38:41], v[208:211], v[200:203], v[38:41]
	v_mfma_f32_16x16x32_bf16 v[34:37], v[216:219], v[200:203], v[34:37]
	s_barrier
	s_setprio 0
	ds_read_b128 v[172:175], v141 offset:16384
	ds_read_b128 v[176:179], v141 offset:17408
	ds_read_b128 v[180:183], v141 offset:18432
	ds_read_b128 v[184:187], v141 offset:19456
	ds_read_b128 v[188:191], v141 offset:20480
	ds_read_b128 v[192:195], v141 offset:21504
	ds_read_b128 v[196:199], v141 offset:22528
	ds_read_b128 v[200:203], v141 offset:23552
	s_mov_b32 m0, s33
	s_nop 0
	global_load_lds_dwordx4 v222, s[100:101]
	s_mov_b32 m0, s34
	s_nop 0
	global_load_lds_dwordx4 v223, s[100:101]
	s_mov_b32 m0, s14
	s_nop 0
	global_load_lds_dwordx4 v224, s[98:99]
	s_mov_b32 m0, s35
	s_nop 0
	global_load_lds_dwordx4 v225, s[98:99]
	s_mov_b32 m0, s58
	s_nop 0
	global_load_lds_dwordx4 v226, s[100:101]
	s_mov_b32 m0, s59
	s_nop 0
	global_load_lds_dwordx4 v227, s[100:101]
	s_waitcnt vmcnt(8)
	s_waitcnt lgkmcnt(0)
	s_setprio 1
	s_barrier
	v_mfma_f32_16x16x32_bf16 v[30:33], v[156:159], v[172:175], v[30:33]
	v_mfma_f32_16x16x32_bf16 v[26:29], v[164:167], v[172:175], v[26:29]
	v_mfma_f32_16x16x32_bf16 v[22:25], v[156:159], v[180:183], v[22:25]
	v_mfma_f32_16x16x32_bf16 v[18:21], v[164:167], v[180:183], v[18:21]
	v_mfma_f32_16x16x32_bf16 v[14:17], v[156:159], v[188:191], v[14:17]
	v_mfma_f32_16x16x32_bf16 v[10:13], v[164:167], v[188:191], v[10:13]
	v_mfma_f32_16x16x32_bf16 v[6:9], v[156:159], v[196:199], v[6:9]
	v_mfma_f32_16x16x32_bf16 v[2:5], v[164:167], v[196:199], v[2:5]
	v_mfma_f32_16x16x32_bf16 v[30:33], v[160:163], v[176:179], v[30:33]
	v_mfma_f32_16x16x32_bf16 v[26:29], v[168:171], v[176:179], v[26:29]
	v_mfma_f32_16x16x32_bf16 v[22:25], v[160:163], v[184:187], v[22:25]
	v_mfma_f32_16x16x32_bf16 v[18:21], v[168:171], v[184:187], v[18:21]
	v_mfma_f32_16x16x32_bf16 v[14:17], v[160:163], v[192:195], v[14:17]
	v_mfma_f32_16x16x32_bf16 v[10:13], v[168:171], v[192:195], v[10:13]
	v_mfma_f32_16x16x32_bf16 v[6:9], v[160:163], v[200:203], v[6:9]
	v_mfma_f32_16x16x32_bf16 v[2:5], v[168:171], v[200:203], v[2:5]
	v_mfma_f32_16x16x32_bf16 v[58:61], v[204:207], v[172:175], v[58:61]
	v_mfma_f32_16x16x32_bf16 v[62:65], v[212:215], v[172:175], v[62:65]
	v_mfma_f32_16x16x32_bf16 v[66:69], v[204:207], v[180:183], v[66:69]
	v_mfma_f32_16x16x32_bf16 v[74:77], v[212:215], v[180:183], v[74:77]
	v_mfma_f32_16x16x32_bf16 v[78:81], v[204:207], v[188:191], v[78:81]
	v_mfma_f32_16x16x32_bf16 v[82:85], v[212:215], v[188:191], v[82:85]
	v_mfma_f32_16x16x32_bf16 v[90:93], v[204:207], v[196:199], v[90:93]
	v_mfma_f32_16x16x32_bf16 v[94:97], v[212:215], v[196:199], v[94:97]
	v_mfma_f32_16x16x32_bf16 v[58:61], v[208:211], v[176:179], v[58:61]
	v_mfma_f32_16x16x32_bf16 v[62:65], v[216:219], v[176:179], v[62:65]
	v_mfma_f32_16x16x32_bf16 v[66:69], v[208:211], v[184:187], v[66:69]
	v_mfma_f32_16x16x32_bf16 v[74:77], v[216:219], v[184:187], v[74:77]
	v_mfma_f32_16x16x32_bf16 v[78:81], v[208:211], v[192:195], v[78:81]
	v_mfma_f32_16x16x32_bf16 v[82:85], v[216:219], v[192:195], v[82:85]
	v_mfma_f32_16x16x32_bf16 v[90:93], v[208:211], v[200:203], v[90:93]
	v_mfma_f32_16x16x32_bf16 v[94:97], v[216:219], v[200:203], v[94:97]
	s_barrier
; #define LDA(dst, b, h)                                                                                     \
;   _Pragma("unroll") for (int m = 0; m < 4; ++m) _Pragma("unroll") for (int k = 0; k < 2; ++k) dst[m][k] = \
;       *reinterpret_cast<const bf16x8*>(shmc + aL + (((b) * 2 + (h)) * 16384 + (m * 2 + k) * 1024))
; #define LDB(dst, b, h)                                                                                     \
;   _Pragma("unroll") for (int n = 0; n < 2; ++n) _Pragma("unroll") for (int k = 0; k < 2; ++k) dst[n][k] = \
;       *reinterpret_cast<const bf16x8*>(shmc + bL + (((b) * 2 + (h)) * 16384 + (n * 2 + k) * 1024))
; #define WAIT_V(n) asm volatile("s_waitcnt vmcnt(" #n ")" ::: "memory")
; #define WAIT_L(n) asm volatile("s_waitcnt lgkmcnt(" #n ")" ::: "memory")
; #define BAR __builtin_amdgcn_s_barrier()
; #define SCHED __builtin_amdgcn_sched_barrier(0)
; template <int EPI>
; __device__ __forceinline__ void phase_gemm(const Params& p, const GemmDesc& d, char* shmc) {
;     ...
;       WAIT_V(6); BAR; MMA(1, 1, At, B1); BAR;
;       LDB(B0, 1, 0); SCHED; LDA(At, 1, 0); STAGE_A(SA(0, 1), 1, t + 2);
;       WAIT_L(8); BAR; WAIT_L(0); MMA(0, 0, At, B0); BAR; SCHED;
;       LDB(B1, 1, 1); STAGE_B(SB(1, 0), 0, t + 3);
;       BAR; WAIT_L(0); MMA(0, 1, At, B1); BAR;
;       LDA(At, 1, 1); STAGE_A(SA(1, 0), 0, t + 3);
;       BAR; WAIT_L(0); MMA(1, 0, At, B0); BAR; SCHED;
;       STAGE_B(SB(1, 1), 1, t + 3);
;       WAIT_V(6); BAR; MMA(1, 1, At, B1); BAR;
;     }
	s_setprio 0
	ds_read_b128 v[156:159], v130 offset:32768
	ds_read_b128 v[160:163], v130 offset:33792
	ds_read_b128 v[164:167], v130 offset:34816
	ds_read_b128 v[168:171], v130 offset:35840
	ds_read_b128 v[204:207], v130 offset:49152
	ds_read_b128 v[208:211], v130 offset:50176
	ds_read_b128 v[212:215], v130 offset:51200
	ds_read_b128 v[216:219], v130 offset:52224
	ds_read_b128 v[172:175], v141 offset:32768
	ds_read_b128 v[176:179], v141 offset:33792
	ds_read_b128 v[180:183], v141 offset:34816
	ds_read_b128 v[184:187], v141 offset:35840
	ds_read_b128 v[188:191], v141 offset:36864
	ds_read_b128 v[192:195], v141 offset:37888
	ds_read_b128 v[196:199], v141 offset:38912
	ds_read_b128 v[200:203], v141 offset:39936
	s_mov_b32 m0, s60
	s_nop 0
	global_load_lds_dwordx4 v228, s[98:99]
	s_mov_b32 m0, s61
	s_nop 0
	global_load_lds_dwordx4 v229, s[98:99]
	s_waitcnt vmcnt(8)
	s_waitcnt lgkmcnt(0)
	s_setprio 1
	s_barrier
	v_mfma_f32_16x16x32_bf16 v[126:129], v[156:159], v[172:175], v[126:129]
	v_mfma_f32_16x16x32_bf16 v[122:125], v[164:167], v[172:175], v[122:125]
	v_mfma_f32_16x16x32_bf16 v[118:121], v[156:159], v[180:183], v[118:121]
	v_mfma_f32_16x16x32_bf16 v[114:117], v[164:167], v[180:183], v[114:117]
	v_mfma_f32_16x16x32_bf16 v[110:113], v[156:159], v[188:191], v[110:113]
	v_mfma_f32_16x16x32_bf16 v[106:109], v[164:167], v[188:191], v[106:109]
	v_mfma_f32_16x16x32_bf16 v[102:105], v[156:159], v[196:199], v[102:105]
	v_mfma_f32_16x16x32_bf16 v[98:101], v[164:167], v[196:199], v[98:101]
	v_mfma_f32_16x16x32_bf16 v[126:129], v[160:163], v[176:179], v[126:129]
	v_mfma_f32_16x16x32_bf16 v[122:125], v[168:171], v[176:179], v[122:125]
	v_mfma_f32_16x16x32_bf16 v[118:121], v[160:163], v[184:187], v[118:121]
	v_mfma_f32_16x16x32_bf16 v[114:117], v[168:171], v[184:187], v[114:117]
	v_mfma_f32_16x16x32_bf16 v[110:113], v[160:163], v[192:195], v[110:113]
	v_mfma_f32_16x16x32_bf16 v[106:109], v[168:171], v[192:195], v[106:109]
	v_mfma_f32_16x16x32_bf16 v[102:105], v[160:163], v[200:203], v[102:105]
	v_mfma_f32_16x16x32_bf16 v[98:101], v[168:171], v[200:203], v[98:101]
	v_mfma_f32_16x16x32_bf16 v[86:89], v[204:207], v[172:175], v[86:89]
	v_mfma_f32_16x16x32_bf16 v[70:73], v[212:215], v[172:175], v[70:73]
	v_mfma_f32_16x16x32_bf16 v[54:57], v[204:207], v[180:183], v[54:57]
	v_mfma_f32_16x16x32_bf16 v[50:53], v[212:215], v[180:183], v[50:53]
	v_mfma_f32_16x16x32_bf16 v[46:49], v[204:207], v[188:191], v[46:49]
	v_mfma_f32_16x16x32_bf16 v[42:45], v[212:215], v[188:191], v[42:45]
	v_mfma_f32_16x16x32_bf16 v[38:41], v[204:207], v[196:199], v[38:41]
	v_mfma_f32_16x16x32_bf16 v[34:37], v[212:215], v[196:199], v[34:37]
	v_mfma_f32_16x16x32_bf16 v[86:89], v[208:211], v[176:179], v[86:89]
	v_mfma_f32_16x16x32_bf16 v[70:73], v[216:219], v[176:179], v[70:73]
	v_mfma_f32_16x16x32_bf16 v[54:57], v[208:211], v[184:187], v[54:57]
	v_mfma_f32_16x16x32_bf16 v[50:53], v[216:219], v[184:187], v[50:53]
	v_mfma_f32_16x16x32_bf16 v[46:49], v[208:211], v[192:195], v[46:49]
	v_mfma_f32_16x16x32_bf16 v[42:45], v[216:219], v[192:195], v[42:45]
	v_mfma_f32_16x16x32_bf16 v[38:41], v[208:211], v[200:203], v[38:41]
	v_mfma_f32_16x16x32_bf16 v[34:37], v[216:219], v[200:203], v[34:37]
	s_barrier
	s_setprio 0
	ds_read_b128 v[172:175], v141 offset:49152
	ds_read_b128 v[176:179], v141 offset:50176
	ds_read_b128 v[180:183], v141 offset:51200
	ds_read_b128 v[184:187], v141 offset:52224
	ds_read_b128 v[188:191], v141 offset:53248
	ds_read_b128 v[192:195], v141 offset:54272
	ds_read_b128 v[196:199], v141 offset:55296
	ds_read_b128 v[200:203], v141 offset:56320
	s_mov_b32 m0, s62
	s_nop 0
	global_load_lds_dwordx4 v232, s[100:101]
	s_mov_b32 m0, s63
	s_nop 0
	global_load_lds_dwordx4 v233, s[100:101]
	s_mov_b32 m0, s64
	s_nop 0
	global_load_lds_dwordx4 v234, s[98:99]
	s_mov_b32 m0, s65
	s_nop 0
	global_load_lds_dwordx4 v235, s[98:99]
	s_mov_b32 m0, s68
	s_nop 0
	global_load_lds_dwordx4 v236, s[100:101]
	s_mov_b32 m0, s69
	s_nop 0
	global_load_lds_dwordx4 v237, s[100:101]
	s_add_i32 s54, s54, 2
	s_add_u32 s52, s52, 0x100
	s_addc_u32 s53, s53, 0
	s_add_u32 s98, s98, 0x100
	s_addc_u32 s99, s99, 0
	s_add_u32 s100, s100, 0x100
	s_addc_u32 s101, s101, 0
	s_cmpk_gt_u32 s54, 0x53
	s_waitcnt vmcnt(8)
	s_waitcnt lgkmcnt(0)
	s_setprio 1
	s_barrier
	v_mfma_f32_16x16x32_bf16 v[30:33], v[156:159], v[172:175], v[30:33]
	v_mfma_f32_16x16x32_bf16 v[26:29], v[164:167], v[172:175], v[26:29]
	v_mfma_f32_16x16x32_bf16 v[22:25], v[156:159], v[180:183], v[22:25]
	v_mfma_f32_16x16x32_bf16 v[18:21], v[164:167], v[180:183], v[18:21]
	v_mfma_f32_16x16x32_bf16 v[14:17], v[156:159], v[188:191], v[14:17]
	v_mfma_f32_16x16x32_bf16 v[10:13], v[164:167], v[188:191], v[10:13]
	v_mfma_f32_16x16x32_bf16 v[6:9], v[156:159], v[196:199], v[6:9]
	v_mfma_f32_16x16x32_bf16 v[2:5], v[164:167], v[196:199], v[2:5]
	v_mfma_f32_16x16x32_bf16 v[30:33], v[160:163], v[176:179], v[30:33]
	v_mfma_f32_16x16x32_bf16 v[26:29], v[168:171], v[176:179], v[26:29]
	v_mfma_f32_16x16x32_bf16 v[22:25], v[160:163], v[184:187], v[22:25]
	v_mfma_f32_16x16x32_bf16 v[18:21], v[168:171], v[184:187], v[18:21]
	v_mfma_f32_16x16x32_bf16 v[14:17], v[160:163], v[192:195], v[14:17]
	v_mfma_f32_16x16x32_bf16 v[10:13], v[168:171], v[192:195], v[10:13]
	v_mfma_f32_16x16x32_bf16 v[6:9], v[160:163], v[200:203], v[6:9]
	v_mfma_f32_16x16x32_bf16 v[2:5], v[168:171], v[200:203], v[2:5]
	v_mfma_f32_16x16x32_bf16 v[58:61], v[204:207], v[172:175], v[58:61]
	v_mfma_f32_16x16x32_bf16 v[62:65], v[212:215], v[172:175], v[62:65]
	v_mfma_f32_16x16x32_bf16 v[66:69], v[204:207], v[180:183], v[66:69]
	v_mfma_f32_16x16x32_bf16 v[74:77], v[212:215], v[180:183], v[74:77]
	v_mfma_f32_16x16x32_bf16 v[78:81], v[204:207], v[188:191], v[78:81]
	v_mfma_f32_16x16x32_bf16 v[82:85], v[212:215], v[188:191], v[82:85]
	v_mfma_f32_16x16x32_bf16 v[90:93], v[204:207], v[196:199], v[90:93]
	v_mfma_f32_16x16x32_bf16 v[94:97], v[212:215], v[196:199], v[94:97]
	v_mfma_f32_16x16x32_bf16 v[58:61], v[208:211], v[176:179], v[58:61]
	v_mfma_f32_16x16x32_bf16 v[62:65], v[216:219], v[176:179], v[62:65]
	v_mfma_f32_16x16x32_bf16 v[66:69], v[208:211], v[184:187], v[66:69]
	v_mfma_f32_16x16x32_bf16 v[74:77], v[216:219], v[184:187], v[74:77]
	v_mfma_f32_16x16x32_bf16 v[78:81], v[208:211], v[192:195], v[78:81]
	v_mfma_f32_16x16x32_bf16 v[82:85], v[216:219], v[192:195], v[82:85]
	v_mfma_f32_16x16x32_bf16 v[90:93], v[208:211], v[200:203], v[90:93]
	v_mfma_f32_16x16x32_bf16 v[94:97], v[216:219], v[200:203], v[94:97]
	s_barrier
; #define LDA(dst, b, h)                                                                                     \
;   _Pragma("unroll") for (int m = 0; m < 4; ++m) _Pragma("unroll") for (int k = 0; k < 2; ++k) dst[m][k] = \
;       *reinterpret_cast<const bf16x8*>(shmc + aL + (((b) * 2 + (h)) * 16384 + (m * 2 + k) * 1024))
; #define LDB(dst, b, h)                                                                                     \
;   _Pragma("unroll") for (int n = 0; n < 2; ++n) _Pragma("unroll") for (int k = 0; k < 2; ++k) dst[n][k] = \
;       *reinterpret_cast<const bf16x8*>(shmc + bL + (((b) * 2 + (h)) * 16384 + (n * 2 + k) * 1024))
; #define OPAQ asm volatile("" : "+v"(aL), "+v"(bL))
; #define WAIT_V(n) asm volatile("s_waitcnt vmcnt(" #n ")" ::: "memory")
; #define WAIT_L(n) asm volatile("s_waitcnt lgkmcnt(" #n ")" ::: "memory")
; #define BAR __builtin_amdgcn_s_barrier()
; template <int EPI>
; __device__ __forceinline__ void phase_gemm(const Params& p, const GemmDesc& d, char* shmc) {
;     ...
;     }
;     {
;       OPAQ;
;       LDB(B0, 0, 0); LDA(At, 0, 0); STAGE_A(SA(1, 1), 1, nt - 1);
;       BAR; WAIT_L(0); MMA(0, 0, At, B0); BAR;
;       LDB(B1, 0, 1); BAR; WAIT_L(0); MMA(0, 1, At, B1); BAR;
;       LDA(At, 0, 1); WAIT_V(4); BAR; WAIT_L(0); MMA(1, 0, At, B0); MMA(1, 1, At, B1); BAR;
;     }
	s_cbranch_scc0 .LBB0_455
	s_setprio 0
	s_add_u32 s48, s48, 0x162b80
	s_addc_u32 s49, s49, 0
	v_add_u32_e32 v130, 0, v153
	v_add_u32_e32 v141, 0, v152
	s_mov_b32 m0, s70
	ds_read_b128 v[144:147], v130
	ds_read_b128 v[148:151], v130 offset:1024
	ds_read_b128 v[156:159], v130 offset:2048
	ds_read_b128 v[160:163], v130 offset:3072
	ds_read_b128 v[164:167], v141
	ds_read_b128 v[168:171], v141 offset:1024
	ds_read_b128 v[172:175], v141 offset:2048
	ds_read_b128 v[176:179], v141 offset:3072
	ds_read_b128 v[180:183], v141 offset:4096
	ds_read_b128 v[184:187], v141 offset:5120
	ds_read_b128 v[188:191], v141 offset:6144
	ds_read_b128 v[192:195], v141 offset:7168
	global_load_lds_dwordx4 v140, s[48:49]
	s_mov_b32 m0, s71
	s_nop 0
	global_load_lds_dwordx4 v142, s[48:49]
	s_waitcnt vmcnt(8)
	s_barrier
	s_waitcnt lgkmcnt(0)
	s_setprio 1
	s_waitcnt lgkmcnt(0)
	v_mfma_f32_16x16x32_bf16 v[126:129], v[144:147], v[164:167], v[126:129]
	v_mfma_f32_16x16x32_bf16 v[122:125], v[156:159], v[164:167], v[122:125]
	v_mfma_f32_16x16x32_bf16 v[114:117], v[156:159], v[172:175], v[114:117]
	v_mfma_f32_16x16x32_bf16 v[110:113], v[144:147], v[180:183], v[110:113]
	v_mfma_f32_16x16x32_bf16 v[102:105], v[144:147], v[188:191], v[102:105]
	v_mfma_f32_16x16x32_bf16 v[126:129], v[148:151], v[168:171], v[126:129]
	v_mfma_f32_16x16x32_bf16 v[122:125], v[160:163], v[168:171], v[122:125]
	v_mfma_f32_16x16x32_bf16 v[118:121], v[144:147], v[172:175], v[118:121]
	v_mfma_f32_16x16x32_bf16 v[114:117], v[160:163], v[176:179], v[114:117]
	v_mfma_f32_16x16x32_bf16 v[110:113], v[148:151], v[184:187], v[110:113]
	v_mfma_f32_16x16x32_bf16 v[106:109], v[156:159], v[180:183], v[106:109]
	v_mfma_f32_16x16x32_bf16 v[102:105], v[148:151], v[192:195], v[102:105]
	v_mfma_f32_16x16x32_bf16 v[98:101], v[156:159], v[188:191], v[98:101]
	v_mfma_f32_16x16x32_bf16 v[196:199], v[148:151], v[176:179], v[118:121]
	v_mfma_f32_16x16x32_bf16 v[200:203], v[160:163], v[184:187], v[106:109]
	v_mfma_f32_16x16x32_bf16 v[204:207], v[160:163], v[192:195], v[98:101]
	s_setprio 0
	s_barrier
	s_nop 2
	ds_read_b128 v[98:101], v130 offset:16384
	ds_read_b128 v[106:109], v130 offset:17408
	ds_read_b128 v[118:121], v130 offset:18432
	ds_read_b128 v[208:211], v130 offset:19456
	s_barrier
	s_waitcnt lgkmcnt(0)
	s_setprio 1
	s_waitcnt lgkmcnt(0)
	v_mfma_f32_16x16x32_bf16 v[86:89], v[98:101], v[164:167], v[86:89]
	v_mfma_f32_16x16x32_bf16 v[70:73], v[118:121], v[164:167], v[70:73]
	v_mfma_f32_16x16x32_bf16 v[54:57], v[98:101], v[172:175], v[54:57]
	v_mfma_f32_16x16x32_bf16 v[50:53], v[118:121], v[172:175], v[50:53]
	v_mfma_f32_16x16x32_bf16 v[46:49], v[98:101], v[180:183], v[46:49]
	v_mfma_f32_16x16x32_bf16 v[42:45], v[118:121], v[180:183], v[42:45]
	v_mfma_f32_16x16x32_bf16 v[38:41], v[98:101], v[188:191], v[38:41]
	v_mfma_f32_16x16x32_bf16 v[34:37], v[118:121], v[188:191], v[34:37]
	v_mfma_f32_16x16x32_bf16 v[86:89], v[106:109], v[168:171], v[86:89]
	v_mfma_f32_16x16x32_bf16 v[70:73], v[208:211], v[168:171], v[70:73]
	v_mfma_f32_16x16x32_bf16 v[54:57], v[106:109], v[176:179], v[54:57]
	v_mfma_f32_16x16x32_bf16 v[50:53], v[208:211], v[176:179], v[50:53]
	v_mfma_f32_16x16x32_bf16 v[46:49], v[106:109], v[184:187], v[46:49]
	v_mfma_f32_16x16x32_bf16 v[42:45], v[208:211], v[184:187], v[42:45]
	v_mfma_f32_16x16x32_bf16 v[38:41], v[106:109], v[192:195], v[38:41]
	v_mfma_f32_16x16x32_bf16 v[34:37], v[208:211], v[192:195], v[34:37]
	s_setprio 0
	s_barrier
	ds_read_b128 v[164:167], v141 offset:16384
	ds_read_b128 v[168:171], v141 offset:17408
	ds_read_b128 v[172:175], v141 offset:18432
	ds_read_b128 v[176:179], v141 offset:19456
	ds_read_b128 v[180:183], v141 offset:20480
	ds_read_b128 v[184:187], v141 offset:21504
	ds_read_b128 v[188:191], v141 offset:22528
	ds_read_b128 v[192:195], v141 offset:23552
	s_waitcnt vmcnt(4)
	s_barrier
	s_waitcnt lgkmcnt(0)
	s_setprio 1
	s_waitcnt lgkmcnt(0)
	v_mfma_f32_16x16x32_bf16 v[30:33], v[144:147], v[164:167], v[30:33]
	v_mfma_f32_16x16x32_bf16 v[26:29], v[156:159], v[164:167], v[26:29]
	v_mfma_f32_16x16x32_bf16 v[22:25], v[144:147], v[172:175], v[22:25]
	v_mfma_f32_16x16x32_bf16 v[18:21], v[156:159], v[172:175], v[18:21]
	v_mfma_f32_16x16x32_bf16 v[14:17], v[144:147], v[180:183], v[14:17]
	v_mfma_f32_16x16x32_bf16 v[10:13], v[156:159], v[180:183], v[10:13]
	v_mfma_f32_16x16x32_bf16 v[6:9], v[144:147], v[188:191], v[6:9]
	v_mfma_f32_16x16x32_bf16 v[2:5], v[156:159], v[188:191], v[2:5]
	v_mfma_f32_16x16x32_bf16 v[30:33], v[148:151], v[168:171], v[30:33]
	v_mfma_f32_16x16x32_bf16 v[26:29], v[160:163], v[168:171], v[26:29]
	v_mfma_f32_16x16x32_bf16 v[22:25], v[148:151], v[176:179], v[22:25]
	v_mfma_f32_16x16x32_bf16 v[18:21], v[160:163], v[176:179], v[18:21]
	v_mfma_f32_16x16x32_bf16 v[14:17], v[148:151], v[184:187], v[14:17]
	v_mfma_f32_16x16x32_bf16 v[10:13], v[160:163], v[184:187], v[10:13]
	v_mfma_f32_16x16x32_bf16 v[6:9], v[148:151], v[192:195], v[6:9]
	v_mfma_f32_16x16x32_bf16 v[2:5], v[160:163], v[192:195], v[2:5]
	s_setprio 0
	s_setprio 1
	v_mfma_f32_16x16x32_bf16 v[62:65], v[118:121], v[164:167], v[62:65]
	v_mfma_f32_16x16x32_bf16 v[144:147], v[208:211], v[168:171], v[62:65]
	v_mfma_f32_16x16x32_bf16 v[62:65], v[98:101], v[172:175], v[66:69]
	v_mfma_f32_16x16x32_bf16 v[148:151], v[106:109], v[176:179], v[62:65]
	v_mfma_f32_16x16x32_bf16 v[62:65], v[118:121], v[172:175], v[74:77]
	v_mfma_f32_16x16x32_bf16 v[156:159], v[208:211], v[176:179], v[62:65]
	v_mfma_f32_16x16x32_bf16 v[62:65], v[98:101], v[180:183], v[78:81]
	v_mfma_f32_16x16x32_bf16 v[160:163], v[106:109], v[184:187], v[62:65]
	v_mfma_f32_16x16x32_bf16 v[62:65], v[118:121], v[180:183], v[82:85]
	v_mfma_f32_16x16x32_bf16 v[58:61], v[98:101], v[164:167], v[58:61]
	v_mfma_f32_16x16x32_bf16 v[164:167], v[208:211], v[184:187], v[62:65]
	v_mfma_f32_16x16x32_bf16 v[62:65], v[98:101], v[188:191], v[90:93]
	v_mfma_f32_16x16x32_bf16 v[58:61], v[106:109], v[168:171], v[58:61]
	v_mfma_f32_16x16x32_bf16 v[168:171], v[106:109], v[192:195], v[62:65]
	v_mfma_f32_16x16x32_bf16 v[62:65], v[118:121], v[188:191], v[94:97]
	v_mfma_f32_16x16x32_bf16 v[172:175], v[208:211], v[192:195], v[62:65]
	s_setprio 0
	s_barrier
; #define LDA(dst, b, h)                                                                                     \
;   _Pragma("unroll") for (int m = 0; m < 4; ++m) _Pragma("unroll") for (int k = 0; k < 2; ++k) dst[m][k] = \
;       *reinterpret_cast<const bf16x8*>(shmc + aL + (((b) * 2 + (h)) * 16384 + (m * 2 + k) * 1024))
; #define LDB(dst, b, h)                                                                                     \
;   _Pragma("unroll") for (int n = 0; n < 2; ++n) _Pragma("unroll") for (int k = 0; k < 2; ++k) dst[n][k] = \
;       *reinterpret_cast<const bf16x8*>(shmc + bL + (((b) * 2 + (h)) * 16384 + (n * 2 + k) * 1024))
; #define WAIT_V(n) asm volatile("s_waitcnt vmcnt(" #n ")" ::: "memory")
; #define WAIT_L(n) asm volatile("s_waitcnt lgkmcnt(" #n ")" ::: "memory")
; #define BAR __builtin_amdgcn_s_barrier()
; template <int EPI>
; __device__ __forceinline__ void phase_gemm(const Params& p, const GemmDesc& d, char* shmc) {
;     ...
;     {
;       LDB(B0, 1, 0); LDA(At, 1, 0); WAIT_V(2); BAR; WAIT_L(0); MMA(0, 0, At, B0); BAR;
;       LDB(B1, 1, 1); WAIT_V(0); BAR; WAIT_L(0); MMA(0, 1, At, B1); BAR;
;       LDA(At, 1, 1); BAR; WAIT_L(0); MMA(1, 0, At, B0); MMA(1, 1, At, B1); BAR;
;     }
;     if (wr == 0) BAR;
	ds_read_b128 v[176:179], v130 offset:32768
	ds_read_b128 v[180:183], v130 offset:33792
	ds_read_b128 v[184:187], v130 offset:34816
	ds_read_b128 v[188:191], v130 offset:35840
	s_nop 0
	ds_read_b128 v[62:65], v141 offset:32768
	ds_read_b128 v[78:81], v141 offset:33792
	ds_read_b128 v[94:97], v141 offset:34816
	ds_read_b128 v[192:195], v141 offset:35840
	ds_read_b128 v[208:211], v141 offset:36864
	ds_read_b128 v[212:215], v141 offset:37888
	ds_read_b128 v[216:219], v141 offset:38912
	ds_read_b128 v[220:223], v141 offset:39936
	s_waitcnt vmcnt(2)
	s_barrier
	s_waitcnt lgkmcnt(0)
	s_setprio 1
	s_waitcnt lgkmcnt(0)
	v_mfma_f32_16x16x32_bf16 v[66:69], v[176:179], v[62:65], v[126:129]
	v_mfma_f32_16x16x32_bf16 v[126:129], v[180:183], v[78:81], v[66:69]
	v_mfma_f32_16x16x32_bf16 v[66:69], v[184:187], v[62:65], v[122:125]
	v_mfma_f32_16x16x32_bf16 v[118:121], v[188:191], v[78:81], v[66:69]
	v_mfma_f32_16x16x32_bf16 v[66:69], v[176:179], v[94:97], v[196:199]
	v_mfma_f32_16x16x32_bf16 v[106:109], v[180:183], v[192:195], v[66:69]
	v_mfma_f32_16x16x32_bf16 v[66:69], v[184:187], v[94:97], v[114:117]
	v_mfma_f32_16x16x32_bf16 v[98:101], v[188:191], v[192:195], v[66:69]
	v_mfma_f32_16x16x32_bf16 v[66:69], v[176:179], v[208:211], v[110:113]
	v_mfma_f32_16x16x32_bf16 v[90:93], v[180:183], v[212:215], v[66:69]
	v_mfma_f32_16x16x32_bf16 v[66:69], v[184:187], v[208:211], v[200:203]
	v_mfma_f32_16x16x32_bf16 v[82:85], v[188:191], v[212:215], v[66:69]
	v_mfma_f32_16x16x32_bf16 v[66:69], v[176:179], v[216:219], v[102:105]
	v_mfma_f32_16x16x32_bf16 v[74:77], v[180:183], v[220:223], v[66:69]
	v_mfma_f32_16x16x32_bf16 v[66:69], v[184:187], v[216:219], v[204:207]
	v_mfma_f32_16x16x32_bf16 v[66:69], v[188:191], v[220:223], v[66:69]
	s_setprio 0
	s_barrier
	ds_read_b128 v[196:199], v130 offset:49152
	ds_read_b128 v[200:203], v130 offset:50176
	ds_read_b128 v[204:207], v130 offset:51200
	ds_read_b128 v[224:227], v130 offset:52224
	s_waitcnt vmcnt(0)
	s_barrier
	s_waitcnt lgkmcnt(0)
	s_setprio 1
	s_waitcnt lgkmcnt(0)
	v_mfma_f32_16x16x32_bf16 v[86:89], v[196:199], v[62:65], v[86:89]
	v_mfma_f32_16x16x32_bf16 v[62:65], v[204:207], v[62:65], v[70:73]
	v_mfma_f32_16x16x32_bf16 v[54:57], v[196:199], v[94:97], v[54:57]
	v_mfma_f32_16x16x32_bf16 v[50:53], v[204:207], v[94:97], v[50:53]
	v_mfma_f32_16x16x32_bf16 v[46:49], v[196:199], v[208:211], v[46:49]
	v_mfma_f32_16x16x32_bf16 v[42:45], v[204:207], v[208:211], v[42:45]
	v_mfma_f32_16x16x32_bf16 v[38:41], v[196:199], v[216:219], v[38:41]
	v_mfma_f32_16x16x32_bf16 v[34:37], v[204:207], v[216:219], v[34:37]
	v_mfma_f32_16x16x32_bf16 v[122:125], v[200:203], v[78:81], v[86:89]
	v_mfma_f32_16x16x32_bf16 v[114:117], v[224:227], v[78:81], v[62:65]
	v_mfma_f32_16x16x32_bf16 v[110:113], v[200:203], v[192:195], v[54:57]
	v_mfma_f32_16x16x32_bf16 v[102:105], v[224:227], v[192:195], v[50:53]
	v_mfma_f32_16x16x32_bf16 v[94:97], v[200:203], v[212:215], v[46:49]
	v_mfma_f32_16x16x32_bf16 v[86:89], v[224:227], v[212:215], v[42:45]
	v_mfma_f32_16x16x32_bf16 v[78:81], v[200:203], v[220:223], v[38:41]
	v_mfma_f32_16x16x32_bf16 v[70:73], v[224:227], v[220:223], v[34:37]
	s_setprio 0
	s_barrier
	s_nop 0
	ds_read_b128 v[34:37], v141 offset:49152
	ds_read_b128 v[42:45], v141 offset:50176
	ds_read_b128 v[192:195], v141 offset:51200
	ds_read_b128 v[208:211], v141 offset:52224
	ds_read_b128 v[212:215], v141 offset:53248
	ds_read_b128 v[216:219], v141 offset:54272
	ds_read_b128 v[220:223], v141 offset:55296
	ds_read_b128 v[228:231], v141 offset:56320
	s_barrier
	s_waitcnt lgkmcnt(0)
	s_setprio 1
	s_waitcnt lgkmcnt(0)
	v_mfma_f32_16x16x32_bf16 v[30:33], v[176:179], v[34:37], v[30:33]
	v_mfma_f32_16x16x32_bf16 v[26:29], v[184:187], v[34:37], v[26:29]
	v_mfma_f32_16x16x32_bf16 v[22:25], v[176:179], v[192:195], v[22:25]
	v_mfma_f32_16x16x32_bf16 v[18:21], v[184:187], v[192:195], v[18:21]
	v_mfma_f32_16x16x32_bf16 v[14:17], v[176:179], v[212:215], v[14:17]
	v_mfma_f32_16x16x32_bf16 v[10:13], v[184:187], v[212:215], v[10:13]
	v_mfma_f32_16x16x32_bf16 v[6:9], v[176:179], v[220:223], v[6:9]
	v_mfma_f32_16x16x32_bf16 v[2:5], v[184:187], v[220:223], v[2:5]
	v_mfma_f32_16x16x32_bf16 v[62:65], v[180:183], v[42:45], v[30:33]
	v_mfma_f32_16x16x32_bf16 v[54:57], v[188:191], v[42:45], v[26:29]
	v_mfma_f32_16x16x32_bf16 v[46:49], v[180:183], v[208:211], v[22:25]
	v_mfma_f32_16x16x32_bf16 v[38:41], v[188:191], v[208:211], v[18:21]
	v_mfma_f32_16x16x32_bf16 v[30:33], v[180:183], v[216:219], v[14:17]
	v_mfma_f32_16x16x32_bf16 v[22:25], v[188:191], v[216:219], v[10:13]
	v_mfma_f32_16x16x32_bf16 v[14:17], v[180:183], v[228:231], v[6:9]
	v_mfma_f32_16x16x32_bf16 v[6:9], v[188:191], v[228:231], v[2:5]
	s_setprio 0
	s_setprio 1
	v_mfma_f32_16x16x32_bf16 v[2:5], v[196:199], v[34:37], v[58:61]
	v_mfma_f32_16x16x32_bf16 v[58:61], v[200:203], v[42:45], v[2:5]
	v_mfma_f32_16x16x32_bf16 v[2:5], v[204:207], v[34:37], v[144:147]
	v_mfma_f32_16x16x32_bf16 v[50:53], v[224:227], v[42:45], v[2:5]
	v_mfma_f32_16x16x32_bf16 v[2:5], v[196:199], v[192:195], v[148:151]
	v_mfma_f32_16x16x32_bf16 v[42:45], v[200:203], v[208:211], v[2:5]
	v_mfma_f32_16x16x32_bf16 v[2:5], v[204:207], v[192:195], v[156:159]
	v_mfma_f32_16x16x32_bf16 v[34:37], v[224:227], v[208:211], v[2:5]
	v_mfma_f32_16x16x32_bf16 v[2:5], v[196:199], v[212:215], v[160:163]
	v_mfma_f32_16x16x32_bf16 v[26:29], v[200:203], v[216:219], v[2:5]
	v_mfma_f32_16x16x32_bf16 v[2:5], v[204:207], v[212:215], v[164:167]
	v_mfma_f32_16x16x32_bf16 v[18:21], v[224:227], v[216:219], v[2:5]
	v_mfma_f32_16x16x32_bf16 v[2:5], v[196:199], v[220:223], v[168:171]
	v_mfma_f32_16x16x32_bf16 v[10:13], v[200:203], v[228:231], v[2:5]
	v_mfma_f32_16x16x32_bf16 v[2:5], v[204:207], v[220:223], v[172:175]
	v_mfma_f32_16x16x32_bf16 v[2:5], v[224:227], v[228:231], v[2:5]
	s_setprio 0
	s_barrier
	s_and_saveexec_b64 s[48:49], s[4:5]
	s_cbranch_execz .LBB0_458
	s_barrier

; #define WAIT_V(n) asm volatile("s_waitcnt vmcnt(" #n ")" ::: "memory")
; #define BAR __builtin_amdgcn_s_barrier()
; template <int EPI>
; __device__ __forceinline__ void phase_gemm(const Params& p, const GemmDesc& d, char* shmc) {
;     ...
;     f32x4 acc[2][2][4][2];
; #pragma unroll
;     for (int a = 0; a < 2; ++a)
; #pragma unroll
;       for (int b = 0; b < 2; ++b)
; #pragma unroll
;         for (int m = 0; m < 4; ++m)
; #pragma unroll
;           for (int n = 0; n < 2; ++n) acc[a][b][m][n] = f32x4{0.f, 0.f, 0.f, 0.f};
;     bf16x8 At[4][2], B0[2][2], B1[2][2];
;     if constexpr (EPI == EPI_UP || EPI == EPI_QKV) {
;       if (wid == 0)
;         __builtin_amdgcn_global_load_lds((const unsigned*)(p.rstd + brow + lane * 4), (unsigned*)(shmc + 143360), 16, 0, 0);
;     }
;     STAGE_B(SB(0, 0), 0, 0); STAGE_A(SA(0, 0), 0, 0);
;     STAGE_B(SB(0, 1), 1, 0); STAGE_A(SA(0, 1), 1, 0);
;     if (wr == 1) BAR;
;     WAIT_V(4); BAR;
;     STAGE_B(SB(1, 0), 0, 1); STAGE_A(SA(1, 0), 0, 1); STAGE_B(SB(1, 1), 1, 1);
;     WAIT_V(6); BAR;
;     for (int t = 0; t < nt - 2; t += 2) {
.LBB0_597:
	s_or_b64 exec, exec, s[78:79]
	v_lshl_add_u64 v[2:3], s[64:65], 0, v[162:163]
	v_mov_b32_e32 v175, v163
	s_add_i32 s61, s68, 0x18000
	v_lshl_add_u64 v[4:5], s[64:65], 0, v[174:175]
	v_lshl_add_u64 v[2:3], v[2:3], 0, s[10:11]
	s_mov_b32 m0, s61
	s_add_i32 s78, s68, 0x1a000
	v_lshl_add_u64 v[6:7], s[8:9], 0, v[162:163]
	v_mov_b32_e32 v10, 0
	v_mov_b32_e32 v11, 0
	v_mov_b32_e32 v12, 0
	v_mov_b32_e32 v13, 0
	v_mov_b32_e32 v14, 0
	v_mov_b32_e32 v15, 0
	v_mov_b32_e32 v16, 0
	v_mov_b32_e32 v17, 0
	v_mov_b32_e32 v18, 0
	v_mov_b32_e32 v19, 0
	v_mov_b32_e32 v20, 0
	v_mov_b32_e32 v21, 0
	v_mov_b32_e32 v22, 0
	v_mov_b32_e32 v23, 0
	v_mov_b32_e32 v24, 0
	v_mov_b32_e32 v25, 0
	v_mov_b32_e32 v26, 0
	v_mov_b32_e32 v27, 0
	v_mov_b32_e32 v28, 0
	v_mov_b32_e32 v29, 0
	v_mov_b32_e32 v30, 0
	v_mov_b32_e32 v31, 0
	v_mov_b32_e32 v32, 0
	v_mov_b32_e32 v33, 0
	v_mov_b32_e32 v34, 0
	v_mov_b32_e32 v35, 0
	v_mov_b32_e32 v36, 0
	v_mov_b32_e32 v37, 0
	v_mov_b32_e32 v38, 0
	v_mov_b32_e32 v39, 0
	v_mov_b32_e32 v40, 0
	v_mov_b32_e32 v41, 0
	v_mov_b32_e32 v42, 0
	v_mov_b32_e32 v43, 0
	v_mov_b32_e32 v44, 0
	v_mov_b32_e32 v45, 0
	v_mov_b32_e32 v50, 0
	v_mov_b32_e32 v51, 0
	v_mov_b32_e32 v52, 0
	v_mov_b32_e32 v53, 0
	v_mov_b32_e32 v94, 0
	v_mov_b32_e32 v95, 0
	v_mov_b32_e32 v96, 0
	v_mov_b32_e32 v97, 0
	v_mov_b32_e32 v102, 0
	v_mov_b32_e32 v103, 0
	v_mov_b32_e32 v104, 0
	v_mov_b32_e32 v105, 0
	v_mov_b32_e32 v106, 0
	v_mov_b32_e32 v107, 0
	v_mov_b32_e32 v108, 0
	v_mov_b32_e32 v109, 0
	v_mov_b32_e32 v110, 0
	v_mov_b32_e32 v111, 0
	v_mov_b32_e32 v112, 0
	v_mov_b32_e32 v113, 0
	v_mov_b32_e32 v114, 0
	v_mov_b32_e32 v115, 0
	v_mov_b32_e32 v116, 0
	v_mov_b32_e32 v117, 0
	v_mov_b32_e32 v118, 0
	v_mov_b32_e32 v119, 0
	v_mov_b32_e32 v120, 0
	v_mov_b32_e32 v121, 0
	v_mov_b32_e32 v122, 0
	v_mov_b32_e32 v123, 0
	v_mov_b32_e32 v124, 0
	v_mov_b32_e32 v125, 0
	v_mov_b32_e32 v126, 0
	v_mov_b32_e32 v127, 0
	v_mov_b32_e32 v128, 0
	v_mov_b32_e32 v129, 0
	v_mov_b32_e32 v46, 0
	v_mov_b32_e32 v47, 0
	v_mov_b32_e32 v48, 0
	v_mov_b32_e32 v49, 0
	v_mov_b32_e32 v54, 0
	v_mov_b32_e32 v55, 0
	v_mov_b32_e32 v56, 0
	v_mov_b32_e32 v57, 0
	v_mov_b32_e32 v58, 0
	v_mov_b32_e32 v59, 0
	v_mov_b32_e32 v60, 0
	v_mov_b32_e32 v61, 0
	v_mov_b32_e32 v62, 0
	v_mov_b32_e32 v63, 0
	v_mov_b32_e32 v64, 0
	v_mov_b32_e32 v65, 0
	v_mov_b32_e32 v66, 0
	v_mov_b32_e32 v67, 0
	v_mov_b32_e32 v68, 0
	v_mov_b32_e32 v69, 0
	v_mov_b32_e32 v70, 0
	v_mov_b32_e32 v71, 0
	v_mov_b32_e32 v72, 0
	v_mov_b32_e32 v73, 0
	v_mov_b32_e32 v74, 0
	v_mov_b32_e32 v75, 0
	v_mov_b32_e32 v76, 0
	v_mov_b32_e32 v77, 0
	v_mov_b32_e32 v78, 0
	v_mov_b32_e32 v79, 0
	v_mov_b32_e32 v80, 0
	v_mov_b32_e32 v81, 0
	v_mov_b32_e32 v82, 0
	v_mov_b32_e32 v83, 0
	v_mov_b32_e32 v84, 0
	v_mov_b32_e32 v85, 0
	v_mov_b32_e32 v86, 0
	v_mov_b32_e32 v87, 0
	v_mov_b32_e32 v88, 0
	v_mov_b32_e32 v89, 0
	v_mov_b32_e32 v90, 0
	v_mov_b32_e32 v91, 0
	v_mov_b32_e32 v92, 0
	v_mov_b32_e32 v93, 0
	v_mov_b32_e32 v98, 0
	v_mov_b32_e32 v99, 0
	v_mov_b32_e32 v100, 0
	v_mov_b32_e32 v101, 0
	s_waitcnt vmcnt(2)
	s_barrier
	global_load_lds_dwordx4 v[2:3], off
	v_lshl_add_u64 v[2:3], v[4:5], 0, s[10:11]
	s_mov_b32 m0, s78
	s_add_i32 s79, s68, 0x8000
	s_add_i32 s86, s68, 0xa000
	v_lshl_add_u64 v[8:9], s[8:9], 0, v[174:175]
	global_load_lds_dwordx4 v[2:3], off
	v_lshl_add_u64 v[2:3], v[6:7], 0, s[10:11]
	s_mov_b32 m0, s79
	s_add_u32 s72, s64, 0x80080
	global_load_lds_dwordx4 v[2:3], off
	v_lshl_add_u64 v[2:3], v[8:9], 0, s[10:11]
	s_mov_b32 m0, s86
	s_addc_u32 s73, s65, 0
	s_add_i32 s64, s68, 0x1c000
	global_load_lds_dwordx4 v[2:3], off
	s_mov_b32 m0, s64
	s_add_i32 s65, s68, 0x1e000
	global_load_lds_dwordx4 v162, s[72:73]
	s_mov_b32 m0, s65
	v_lshl_add_u64 v[130:131], v[166:167], 0, s[62:63]
	global_load_lds_dwordx4 v174, s[72:73]
	v_lshl_add_u64 v[132:133], v[168:169], 0, s[62:63]
	s_lshl_b32 s62, s87, 11
	s_lshl_b32 s63, s88, 8
	s_or_b32 s62, s62, s63
	s_waitcnt vmcnt(6)
	s_ashr_i32 s63, s62, 31
	s_lshl_b64 s[62:63], s[62:63], 12
	v_mov_b32_e32 v2, 0
	v_lshl_add_u64 v[134:135], v[170:171], 0, s[62:63]
	v_lshl_add_u64 v[136:137], v[172:173], 0, s[62:63]
	s_mov_b32 s87, -2
	s_mov_b64 s[62:63], 0
	v_mov_b32_e32 v3, v2
	v_mov_b32_e32 v4, v2
	v_mov_b32_e32 v5, v2
	v_mov_b32_e32 v6, v2
	v_mov_b32_e32 v7, v2
	v_mov_b32_e32 v8, v2
	v_mov_b32_e32 v9, v2
	s_barrier
	v_readfirstlane_b32 s98, v134
	v_readfirstlane_b32 s99, v135
	v_readfirstlane_b32 s100, v130
	v_readfirstlane_b32 s101, v131
	s_nop 3
	v_subrev_u32_e32 v222, s98, v134
	v_add_u32_e32 v222, s26, v222
	v_subrev_u32_e32 v223, s98, v136
	v_add_u32_e32 v223, s26, v223
	v_subrev_u32_e32 v224, s100, v130
	v_add_u32_e32 v224, s38, v224
	v_subrev_u32_e32 v225, s100, v132
	v_add_u32_e32 v225, s38, v225
	v_subrev_u32_e32 v226, s98, v134
	v_add_u32_e32 v226, s40, v226
	v_subrev_u32_e32 v227, s98, v136
	v_add_u32_e32 v227, s40, v227
	v_subrev_u32_e32 v228, s100, v130
	v_add_u32_e32 v228, s42, v228
	v_subrev_u32_e32 v229, s100, v132
	v_add_u32_e32 v229, s42, v229
	v_subrev_u32_e32 v230, s98, v134
	v_add_u32_e32 v230, s48, v230
	v_subrev_u32_e32 v231, s98, v136
	v_add_u32_e32 v231, s48, v231
	v_subrev_u32_e32 v232, s100, v130
	v_add_u32_e32 v232, s52, v232
	v_subrev_u32_e32 v233, s100, v132
	v_add_u32_e32 v233, s52, v233
	v_subrev_u32_e32 v234, s98, v134
	v_add_u32_e32 v234, s54, v234
	v_subrev_u32_e32 v235, s98, v136
	v_add_u32_e32 v235, s54, v235
	v_subrev_u32_e32 v236, s100, v130
	v_add_u32_e32 v236, s56, v236
	v_subrev_u32_e32 v237, s100, v132
	v_add_u32_e32 v237, s56, v237
	s_add_u32 s98, s98, s62
	s_addc_u32 s99, s99, s63
	s_add_u32 s100, s100, s62
	s_addc_u32 s101, s101, s63
; #define LDA(dst, b, h)                                                                                     \
;   _Pragma("unroll") for (int m = 0; m < 4; ++m) _Pragma("unroll") for (int k = 0; k < 2; ++k) dst[m][k] = \
;       *reinterpret_cast<const bf16x8*>(shmc + aL + (((b) * 2 + (h)) * 16384 + (m * 2 + k) * 1024))
; #define LDB(dst, b, h)                                                                                     \
;   _Pragma("unroll") for (int n = 0; n < 2; ++n) _Pragma("unroll") for (int k = 0; k < 2; ++k) dst[n][k] = \
;       *reinterpret_cast<const bf16x8*>(shmc + bL + (((b) * 2 + (h)) * 16384 + (n * 2 + k) * 1024))
; #define OPAQ asm volatile("" : "+v"(aL), "+v"(bL))
; #define WAIT_V(n) asm volatile("s_waitcnt vmcnt(" #n ")" ::: "memory")
; #define WAIT_L(n) asm volatile("s_waitcnt lgkmcnt(" #n ")" ::: "memory")
; #define BAR __builtin_amdgcn_s_barrier()
; #define SCHED __builtin_amdgcn_sched_barrier(0)
; template <int EPI>
; __device__ __forceinline__ void phase_gemm(const Params& p, const GemmDesc& d, char* shmc) {
;     ...
;     for (int t = 0; t < nt - 2; t += 2) {
;       OPAQ;
;       LDB(B0, 0, 0); SCHED; LDA(At, 0, 0); STAGE_A(SA(1, 1), 1, t + 1);
;       WAIT_L(8); BAR; WAIT_L(0); MMA(0, 0, At, B0); BAR; SCHED;
;       LDB(B1, 0, 1); STAGE_B(SB(0, 0), 0, t + 2);
;       BAR; WAIT_L(0); MMA(0, 1, At, B1); BAR;
;       LDA(At, 0, 1); STAGE_A(SA(0, 0), 0, t + 2);
;       BAR; WAIT_L(0); MMA(1, 0, At, B0); BAR; SCHED;
;       STAGE_B(SB(0, 1), 1, t + 2);
;       WAIT_V(6); BAR; MMA(1, 1, At, B1); BAR;
.LBB0_598:
	s_nop 0
	v_add_u32_e32 v175, 0, v179
	v_add_u32_e32 v176, 0, v177
	s_setprio 0
	ds_read_b128 v[138:141], v175
	ds_read_b128 v[142:145], v175 offset:1024
	ds_read_b128 v[146:149], v175 offset:2048
	ds_read_b128 v[150:153], v175 offset:3072
	ds_read_b128 v[206:209], v175 offset:16384
	ds_read_b128 v[210:213], v175 offset:17408
	ds_read_b128 v[214:217], v175 offset:18432
	ds_read_b128 v[218:221], v175 offset:19456
	ds_read_b128 v[154:157], v176
	ds_read_b128 v[158:161], v176 offset:1024
	ds_read_b128 v[182:185], v176 offset:2048
	ds_read_b128 v[186:189], v176 offset:3072
	ds_read_b128 v[190:193], v176 offset:4096
	ds_read_b128 v[194:197], v176 offset:5120
	ds_read_b128 v[198:201], v176 offset:6144
	ds_read_b128 v[202:205], v176 offset:7168
	s_add_i32 s88, s68, 0xc000
	s_mov_b32 m0, s88
	s_nop 0
	global_load_lds_dwordx4 v222, s[98:99]
	s_add_i32 s89, s68, 0xe000
	s_mov_b32 m0, s89
	s_nop 0
	global_load_lds_dwordx4 v223, s[98:99]
	s_waitcnt vmcnt(8)
	s_waitcnt lgkmcnt(0)
	s_setprio 1
	s_barrier
	v_mfma_f32_16x16x32_bf16 v[126:129], v[154:157], v[138:141], v[126:129]
	v_mfma_f32_16x16x32_bf16 v[122:125], v[154:157], v[146:149], v[122:125]
	v_mfma_f32_16x16x32_bf16 v[118:121], v[182:185], v[138:141], v[118:121]
	v_mfma_f32_16x16x32_bf16 v[114:117], v[182:185], v[146:149], v[114:117]
	v_mfma_f32_16x16x32_bf16 v[110:113], v[190:193], v[138:141], v[110:113]
	v_mfma_f32_16x16x32_bf16 v[106:109], v[190:193], v[146:149], v[106:109]
	v_mfma_f32_16x16x32_bf16 v[102:105], v[198:201], v[138:141], v[102:105]
	v_mfma_f32_16x16x32_bf16 v[94:97], v[198:201], v[146:149], v[94:97]
	v_mfma_f32_16x16x32_bf16 v[126:129], v[158:161], v[142:145], v[126:129]
	v_mfma_f32_16x16x32_bf16 v[122:125], v[158:161], v[150:153], v[122:125]
	v_mfma_f32_16x16x32_bf16 v[118:121], v[186:189], v[142:145], v[118:121]
	v_mfma_f32_16x16x32_bf16 v[114:117], v[186:189], v[150:153], v[114:117]
	v_mfma_f32_16x16x32_bf16 v[110:113], v[194:197], v[142:145], v[110:113]
	v_mfma_f32_16x16x32_bf16 v[106:109], v[194:197], v[150:153], v[106:109]
	v_mfma_f32_16x16x32_bf16 v[102:105], v[202:205], v[142:145], v[102:105]
	v_mfma_f32_16x16x32_bf16 v[94:97], v[202:205], v[150:153], v[94:97]
	v_mfma_f32_16x16x32_bf16 v[50:53], v[154:157], v[206:209], v[50:53]
	v_mfma_f32_16x16x32_bf16 v[42:45], v[154:157], v[214:217], v[42:45]
	v_mfma_f32_16x16x32_bf16 v[38:41], v[182:185], v[206:209], v[38:41]
	v_mfma_f32_16x16x32_bf16 v[34:37], v[182:185], v[214:217], v[34:37]
	v_mfma_f32_16x16x32_bf16 v[30:33], v[190:193], v[206:209], v[30:33]
	v_mfma_f32_16x16x32_bf16 v[26:29], v[190:193], v[214:217], v[26:29]
	v_mfma_f32_16x16x32_bf16 v[22:25], v[198:201], v[206:209], v[22:25]
	v_mfma_f32_16x16x32_bf16 v[18:21], v[198:201], v[214:217], v[18:21]
	v_mfma_f32_16x16x32_bf16 v[50:53], v[158:161], v[210:213], v[50:53]
	v_mfma_f32_16x16x32_bf16 v[42:45], v[158:161], v[218:221], v[42:45]
	v_mfma_f32_16x16x32_bf16 v[38:41], v[186:189], v[210:213], v[38:41]
	v_mfma_f32_16x16x32_bf16 v[34:37], v[186:189], v[218:221], v[34:37]
	v_mfma_f32_16x16x32_bf16 v[30:33], v[194:197], v[210:213], v[30:33]
	v_mfma_f32_16x16x32_bf16 v[26:29], v[194:197], v[218:221], v[26:29]
	v_mfma_f32_16x16x32_bf16 v[22:25], v[202:205], v[210:213], v[22:25]
	v_mfma_f32_16x16x32_bf16 v[18:21], v[202:205], v[218:221], v[18:21]
	s_barrier
	s_setprio 0
	ds_read_b128 v[154:157], v176 offset:16384
	ds_read_b128 v[158:161], v176 offset:17408
	ds_read_b128 v[182:185], v176 offset:18432
	ds_read_b128 v[186:189], v176 offset:19456
	ds_read_b128 v[190:193], v176 offset:20480
	ds_read_b128 v[194:197], v176 offset:21504
	ds_read_b128 v[198:201], v176 offset:22528
	ds_read_b128 v[202:205], v176 offset:23552
	s_mov_b32 m0, s69
	s_nop 0
	global_load_lds_dwordx4 v224, s[100:101]
	s_mov_b32 m0, s70
	s_nop 0
	global_load_lds_dwordx4 v225, s[100:101]
	s_mov_b32 m0, s68
	s_nop 0
	global_load_lds_dwordx4 v226, s[98:99]
	s_mov_b32 m0, s71
	s_nop 0
	global_load_lds_dwordx4 v227, s[98:99]
	s_mov_b32 m0, s76
	s_nop 0
	global_load_lds_dwordx4 v228, s[100:101]
	s_mov_b32 m0, s77
	s_nop 0
	global_load_lds_dwordx4 v229, s[100:101]
	s_waitcnt vmcnt(8)
	s_waitcnt lgkmcnt(0)
	s_setprio 1
	s_barrier
	v_mfma_f32_16x16x32_bf16 v[14:17], v[154:157], v[138:141], v[14:17]
	v_mfma_f32_16x16x32_bf16 v[10:13], v[154:157], v[146:149], v[10:13]
	v_mfma_f32_16x16x32_bf16 v[6:9], v[182:185], v[138:141], v[6:9]
	v_mfma_f32_16x16x32_bf16 v[2:5], v[182:185], v[146:149], v[2:5]
	v_mfma_f32_16x16x32_bf16 v[46:49], v[190:193], v[138:141], v[46:49]
	v_mfma_f32_16x16x32_bf16 v[54:57], v[190:193], v[146:149], v[54:57]
	v_mfma_f32_16x16x32_bf16 v[58:61], v[198:201], v[138:141], v[58:61]
	v_mfma_f32_16x16x32_bf16 v[62:65], v[198:201], v[146:149], v[62:65]
	v_mfma_f32_16x16x32_bf16 v[14:17], v[158:161], v[142:145], v[14:17]
	v_mfma_f32_16x16x32_bf16 v[10:13], v[158:161], v[150:153], v[10:13]
	v_mfma_f32_16x16x32_bf16 v[6:9], v[186:189], v[142:145], v[6:9]
	v_mfma_f32_16x16x32_bf16 v[2:5], v[186:189], v[150:153], v[2:5]
	v_mfma_f32_16x16x32_bf16 v[46:49], v[194:197], v[142:145], v[46:49]
	v_mfma_f32_16x16x32_bf16 v[54:57], v[194:197], v[150:153], v[54:57]
	v_mfma_f32_16x16x32_bf16 v[58:61], v[202:205], v[142:145], v[58:61]
	v_mfma_f32_16x16x32_bf16 v[62:65], v[202:205], v[150:153], v[62:65]
	v_mfma_f32_16x16x32_bf16 v[66:69], v[154:157], v[206:209], v[66:69]
	v_mfma_f32_16x16x32_bf16 v[70:73], v[154:157], v[214:217], v[70:73]
	v_mfma_f32_16x16x32_bf16 v[74:77], v[182:185], v[206:209], v[74:77]
	v_mfma_f32_16x16x32_bf16 v[78:81], v[182:185], v[214:217], v[78:81]
	v_mfma_f32_16x16x32_bf16 v[82:85], v[190:193], v[206:209], v[82:85]
	v_mfma_f32_16x16x32_bf16 v[86:89], v[190:193], v[214:217], v[86:89]
	v_mfma_f32_16x16x32_bf16 v[90:93], v[198:201], v[206:209], v[90:93]
	v_mfma_f32_16x16x32_bf16 v[98:101], v[198:201], v[214:217], v[98:101]
	v_mfma_f32_16x16x32_bf16 v[66:69], v[158:161], v[210:213], v[66:69]
	v_mfma_f32_16x16x32_bf16 v[70:73], v[158:161], v[218:221], v[70:73]
	v_mfma_f32_16x16x32_bf16 v[74:77], v[186:189], v[210:213], v[74:77]
	v_mfma_f32_16x16x32_bf16 v[78:81], v[186:189], v[218:221], v[78:81]
	v_mfma_f32_16x16x32_bf16 v[82:85], v[194:197], v[210:213], v[82:85]
	v_mfma_f32_16x16x32_bf16 v[86:89], v[194:197], v[218:221], v[86:89]
	v_mfma_f32_16x16x32_bf16 v[90:93], v[202:205], v[210:213], v[90:93]
	v_mfma_f32_16x16x32_bf16 v[98:101], v[202:205], v[218:221], v[98:101]
	s_barrier
; #define LDA(dst, b, h)                                                                                     \
;   _Pragma("unroll") for (int m = 0; m < 4; ++m) _Pragma("unroll") for (int k = 0; k < 2; ++k) dst[m][k] = \
;       *reinterpret_cast<const bf16x8*>(shmc + aL + (((b) * 2 + (h)) * 16384 + (m * 2 + k) * 1024))
; #define LDB(dst, b, h)                                                                                     \
;   _Pragma("unroll") for (int n = 0; n < 2; ++n) _Pragma("unroll") for (int k = 0; k < 2; ++k) dst[n][k] = \
;       *reinterpret_cast<const bf16x8*>(shmc + bL + (((b) * 2 + (h)) * 16384 + (n * 2 + k) * 1024))
; #define WAIT_V(n) asm volatile("s_waitcnt vmcnt(" #n ")" ::: "memory")
; #define WAIT_L(n) asm volatile("s_waitcnt lgkmcnt(" #n ")" ::: "memory")
; #define BAR __builtin_amdgcn_s_barrier()
; #define SCHED __builtin_amdgcn_sched_barrier(0)
; template <int EPI>
; __device__ __forceinline__ void phase_gemm(const Params& p, const GemmDesc& d, char* shmc) {
;     ...
;       LDB(B0, 1, 0); SCHED; LDA(At, 1, 0); STAGE_A(SA(0, 1), 1, t + 2);
;       WAIT_L(8); BAR; WAIT_L(0); MMA(0, 0, At, B0); BAR; SCHED;
;       LDB(B1, 1, 1); STAGE_B(SB(1, 0), 0, t + 3);
;       BAR; WAIT_L(0); MMA(0, 1, At, B1); BAR;
;       LDA(At, 1, 1); STAGE_A(SA(1, 0), 0, t + 3);
;       BAR; WAIT_L(0); MMA(1, 0, At, B0); BAR; SCHED;
;       STAGE_B(SB(1, 1), 1, t + 3);
;       WAIT_V(6); BAR; MMA(1, 1, At, B1); BAR;
;     }
	s_setprio 0
	ds_read_b128 v[138:141], v175 offset:32768
	ds_read_b128 v[142:145], v175 offset:33792
	ds_read_b128 v[146:149], v175 offset:34816
	ds_read_b128 v[150:153], v175 offset:35840
	ds_read_b128 v[206:209], v175 offset:49152
	ds_read_b128 v[210:213], v175 offset:50176
	ds_read_b128 v[214:217], v175 offset:51200
	ds_read_b128 v[218:221], v175 offset:52224
	ds_read_b128 v[154:157], v176 offset:32768
	ds_read_b128 v[158:161], v176 offset:33792
	ds_read_b128 v[182:185], v176 offset:34816
	ds_read_b128 v[186:189], v176 offset:35840
	ds_read_b128 v[190:193], v176 offset:36864
	ds_read_b128 v[194:197], v176 offset:37888
	ds_read_b128 v[198:201], v176 offset:38912
	ds_read_b128 v[202:205], v176 offset:39936
	s_mov_b32 m0, s80
	s_nop 0
	global_load_lds_dwordx4 v230, s[98:99]
	s_mov_b32 m0, s81
	s_nop 0
	global_load_lds_dwordx4 v231, s[98:99]
	s_waitcnt vmcnt(8)
	s_waitcnt lgkmcnt(0)
	s_setprio 1
	s_barrier
	v_mfma_f32_16x16x32_bf16 v[126:129], v[154:157], v[138:141], v[126:129]
	v_mfma_f32_16x16x32_bf16 v[122:125], v[154:157], v[146:149], v[122:125]
	v_mfma_f32_16x16x32_bf16 v[118:121], v[182:185], v[138:141], v[118:121]
	v_mfma_f32_16x16x32_bf16 v[114:117], v[182:185], v[146:149], v[114:117]
	v_mfma_f32_16x16x32_bf16 v[110:113], v[190:193], v[138:141], v[110:113]
	v_mfma_f32_16x16x32_bf16 v[106:109], v[190:193], v[146:149], v[106:109]
	v_mfma_f32_16x16x32_bf16 v[102:105], v[198:201], v[138:141], v[102:105]
	v_mfma_f32_16x16x32_bf16 v[94:97], v[198:201], v[146:149], v[94:97]
	v_mfma_f32_16x16x32_bf16 v[126:129], v[158:161], v[142:145], v[126:129]
	v_mfma_f32_16x16x32_bf16 v[122:125], v[158:161], v[150:153], v[122:125]
	v_mfma_f32_16x16x32_bf16 v[118:121], v[186:189], v[142:145], v[118:121]
	v_mfma_f32_16x16x32_bf16 v[114:117], v[186:189], v[150:153], v[114:117]
	v_mfma_f32_16x16x32_bf16 v[110:113], v[194:197], v[142:145], v[110:113]
	v_mfma_f32_16x16x32_bf16 v[106:109], v[194:197], v[150:153], v[106:109]
	v_mfma_f32_16x16x32_bf16 v[102:105], v[202:205], v[142:145], v[102:105]
	v_mfma_f32_16x16x32_bf16 v[94:97], v[202:205], v[150:153], v[94:97]
	v_mfma_f32_16x16x32_bf16 v[50:53], v[154:157], v[206:209], v[50:53]
	v_mfma_f32_16x16x32_bf16 v[42:45], v[154:157], v[214:217], v[42:45]
	v_mfma_f32_16x16x32_bf16 v[38:41], v[182:185], v[206:209], v[38:41]
	v_mfma_f32_16x16x32_bf16 v[34:37], v[182:185], v[214:217], v[34:37]
	v_mfma_f32_16x16x32_bf16 v[30:33], v[190:193], v[206:209], v[30:33]
	v_mfma_f32_16x16x32_bf16 v[26:29], v[190:193], v[214:217], v[26:29]
	v_mfma_f32_16x16x32_bf16 v[22:25], v[198:201], v[206:209], v[22:25]
	v_mfma_f32_16x16x32_bf16 v[18:21], v[198:201], v[214:217], v[18:21]
	v_mfma_f32_16x16x32_bf16 v[50:53], v[158:161], v[210:213], v[50:53]
	v_mfma_f32_16x16x32_bf16 v[42:45], v[158:161], v[218:221], v[42:45]
	v_mfma_f32_16x16x32_bf16 v[38:41], v[186:189], v[210:213], v[38:41]
	v_mfma_f32_16x16x32_bf16 v[34:37], v[186:189], v[218:221], v[34:37]
	v_mfma_f32_16x16x32_bf16 v[30:33], v[194:197], v[210:213], v[30:33]
	v_mfma_f32_16x16x32_bf16 v[26:29], v[194:197], v[218:221], v[26:29]
	v_mfma_f32_16x16x32_bf16 v[22:25], v[202:205], v[210:213], v[22:25]
	v_mfma_f32_16x16x32_bf16 v[18:21], v[202:205], v[218:221], v[18:21]
	s_barrier
	s_setprio 0
	ds_read_b128 v[154:157], v176 offset:49152
	ds_read_b128 v[158:161], v176 offset:50176
	ds_read_b128 v[182:185], v176 offset:51200
	ds_read_b128 v[186:189], v176 offset:52224
	ds_read_b128 v[190:193], v176 offset:53248
	ds_read_b128 v[194:197], v176 offset:54272
	ds_read_b128 v[198:201], v176 offset:55296
	ds_read_b128 v[202:205], v176 offset:56320
	s_mov_b32 m0, s61
	s_nop 0
	global_load_lds_dwordx4 v232, s[100:101]
	s_mov_b32 m0, s78
	s_nop 0
	global_load_lds_dwordx4 v233, s[100:101]
	s_mov_b32 m0, s79
	s_nop 0
	global_load_lds_dwordx4 v234, s[98:99]
	s_mov_b32 m0, s86
	s_nop 0
	global_load_lds_dwordx4 v235, s[98:99]
	s_mov_b32 m0, s64
	s_nop 0
	global_load_lds_dwordx4 v236, s[100:101]
	s_mov_b32 m0, s65
	s_nop 0
	global_load_lds_dwordx4 v237, s[100:101]
	s_add_i32 s87, s87, 2
	s_add_u32 s62, s62, 0x100
	s_addc_u32 s63, s63, 0
	s_add_u32 s98, s98, 0x100
	s_addc_u32 s99, s99, 0
	s_add_u32 s100, s100, 0x100
	s_addc_u32 s101, s101, 0
	s_cmp_gt_u32 s87, 27
	s_waitcnt vmcnt(8)
	s_waitcnt lgkmcnt(0)
	s_setprio 1
	s_barrier
	v_mfma_f32_16x16x32_bf16 v[14:17], v[154:157], v[138:141], v[14:17]
	v_mfma_f32_16x16x32_bf16 v[10:13], v[154:157], v[146:149], v[10:13]
	v_mfma_f32_16x16x32_bf16 v[6:9], v[182:185], v[138:141], v[6:9]
	v_mfma_f32_16x16x32_bf16 v[2:5], v[182:185], v[146:149], v[2:5]
	v_mfma_f32_16x16x32_bf16 v[46:49], v[190:193], v[138:141], v[46:49]
	v_mfma_f32_16x16x32_bf16 v[54:57], v[190:193], v[146:149], v[54:57]
	v_mfma_f32_16x16x32_bf16 v[58:61], v[198:201], v[138:141], v[58:61]
	v_mfma_f32_16x16x32_bf16 v[62:65], v[198:201], v[146:149], v[62:65]
	v_mfma_f32_16x16x32_bf16 v[14:17], v[158:161], v[142:145], v[14:17]
	v_mfma_f32_16x16x32_bf16 v[10:13], v[158:161], v[150:153], v[10:13]
	v_mfma_f32_16x16x32_bf16 v[6:9], v[186:189], v[142:145], v[6:9]
	v_mfma_f32_16x16x32_bf16 v[2:5], v[186:189], v[150:153], v[2:5]
	v_mfma_f32_16x16x32_bf16 v[46:49], v[194:197], v[142:145], v[46:49]
	v_mfma_f32_16x16x32_bf16 v[54:57], v[194:197], v[150:153], v[54:57]
	v_mfma_f32_16x16x32_bf16 v[58:61], v[202:205], v[142:145], v[58:61]
	v_mfma_f32_16x16x32_bf16 v[62:65], v[202:205], v[150:153], v[62:65]
	v_mfma_f32_16x16x32_bf16 v[66:69], v[154:157], v[206:209], v[66:69]
	v_mfma_f32_16x16x32_bf16 v[70:73], v[154:157], v[214:217], v[70:73]
	v_mfma_f32_16x16x32_bf16 v[74:77], v[182:185], v[206:209], v[74:77]
	v_mfma_f32_16x16x32_bf16 v[78:81], v[182:185], v[214:217], v[78:81]
	v_mfma_f32_16x16x32_bf16 v[82:85], v[190:193], v[206:209], v[82:85]
	v_mfma_f32_16x16x32_bf16 v[86:89], v[190:193], v[214:217], v[86:89]
	v_mfma_f32_16x16x32_bf16 v[90:93], v[198:201], v[206:209], v[90:93]
	v_mfma_f32_16x16x32_bf16 v[98:101], v[198:201], v[214:217], v[98:101]
	v_mfma_f32_16x16x32_bf16 v[66:69], v[158:161], v[210:213], v[66:69]
	v_mfma_f32_16x16x32_bf16 v[70:73], v[158:161], v[218:221], v[70:73]
	v_mfma_f32_16x16x32_bf16 v[74:77], v[186:189], v[210:213], v[74:77]
	v_mfma_f32_16x16x32_bf16 v[78:81], v[186:189], v[218:221], v[78:81]
	v_mfma_f32_16x16x32_bf16 v[82:85], v[194:197], v[210:213], v[82:85]
	v_mfma_f32_16x16x32_bf16 v[86:89], v[194:197], v[218:221], v[86:89]
	v_mfma_f32_16x16x32_bf16 v[90:93], v[202:205], v[210:213], v[90:93]
	v_mfma_f32_16x16x32_bf16 v[98:101], v[202:205], v[218:221], v[98:101]
	s_barrier
; #define LDA(dst, b, h)                                                                                     \
;   _Pragma("unroll") for (int m = 0; m < 4; ++m) _Pragma("unroll") for (int k = 0; k < 2; ++k) dst[m][k] = \
;       *reinterpret_cast<const bf16x8*>(shmc + aL + (((b) * 2 + (h)) * 16384 + (m * 2 + k) * 1024))
; #define LDB(dst, b, h)                                                                                     \
;   _Pragma("unroll") for (int n = 0; n < 2; ++n) _Pragma("unroll") for (int k = 0; k < 2; ++k) dst[n][k] = \
;       *reinterpret_cast<const bf16x8*>(shmc + bL + (((b) * 2 + (h)) * 16384 + (n * 2 + k) * 1024))
; #define OPAQ asm volatile("" : "+v"(aL), "+v"(bL))
; #define WAIT_V(n) asm volatile("s_waitcnt vmcnt(" #n ")" ::: "memory")
; #define WAIT_L(n) asm volatile("s_waitcnt lgkmcnt(" #n ")" ::: "memory")
; #define BAR __builtin_amdgcn_s_barrier()
; template <int EPI>
; __device__ __forceinline__ void phase_gemm(const Params& p, const GemmDesc& d, char* shmc) {
;     ...
;     {
;       OPAQ;
;       LDB(B0, 0, 0); LDA(At, 0, 0); STAGE_A(SA(1, 1), 1, nt - 1);
;       BAR; WAIT_L(0); MMA(0, 0, At, B0); BAR;
;       LDB(B1, 0, 1); BAR; WAIT_L(0); MMA(0, 1, At, B1); BAR;
;       LDA(At, 0, 1); WAIT_V(4); BAR; WAIT_L(0); MMA(1, 0, At, B0); MMA(1, 1, At, B1); BAR;
	s_cbranch_scc0 .LBB0_598
	s_setprio 0
	s_add_u32 s8, s8, 0x80f80
	s_addc_u32 s9, s9, 0
	v_add_u32_e32 v175, 0, v179
	v_add_u32_e32 v176, 0, v177
	s_mov_b32 m0, s88
	ds_read_b128 v[130:133], v175
	ds_read_b128 v[134:137], v175 offset:1024
	ds_read_b128 v[138:141], v175 offset:2048
	ds_read_b128 v[142:145], v175 offset:3072
	ds_read_b128 v[146:149], v176
	ds_read_b128 v[150:153], v176 offset:1024
	ds_read_b128 v[154:157], v176 offset:2048
	ds_read_b128 v[158:161], v176 offset:3072
	ds_read_b128 v[182:185], v176 offset:4096
	ds_read_b128 v[186:189], v176 offset:5120
	ds_read_b128 v[190:193], v176 offset:6144
	ds_read_b128 v[194:197], v176 offset:7168
	global_load_lds_dwordx4 v162, s[8:9]
	s_mov_b32 m0, s89
	s_nop 0
	global_load_lds_dwordx4 v174, s[8:9]
	s_waitcnt vmcnt(8)
	s_barrier
	s_waitcnt lgkmcnt(0)
	s_setprio 1
	s_waitcnt lgkmcnt(0)
	v_mfma_f32_16x16x32_bf16 v[126:129], v[146:149], v[130:133], v[126:129]
	v_mfma_f32_16x16x32_bf16 v[122:125], v[146:149], v[138:141], v[122:125]
	v_mfma_f32_16x16x32_bf16 v[114:117], v[154:157], v[138:141], v[114:117]
	v_mfma_f32_16x16x32_bf16 v[110:113], v[182:185], v[130:133], v[110:113]
	v_mfma_f32_16x16x32_bf16 v[126:129], v[150:153], v[134:137], v[126:129]
	v_mfma_f32_16x16x32_bf16 v[122:125], v[150:153], v[142:145], v[122:125]
	v_mfma_f32_16x16x32_bf16 v[118:121], v[154:157], v[130:133], v[118:121]
	v_mfma_f32_16x16x32_bf16 v[114:117], v[158:161], v[142:145], v[114:117]
	v_mfma_f32_16x16x32_bf16 v[110:113], v[186:189], v[134:137], v[110:113]
	v_mfma_f32_16x16x32_bf16 v[106:109], v[182:185], v[138:141], v[106:109]
	v_mfma_f32_16x16x32_bf16 v[102:105], v[190:193], v[130:133], v[102:105]
	v_mfma_f32_16x16x32_bf16 v[94:97], v[190:193], v[138:141], v[94:97]
	v_mfma_f32_16x16x32_bf16 v[118:121], v[158:161], v[134:137], v[118:121]
	v_mfma_f32_16x16x32_bf16 v[106:109], v[186:189], v[142:145], v[106:109]
	v_mfma_f32_16x16x32_bf16 v[102:105], v[194:197], v[134:137], v[102:105]
	v_mfma_f32_16x16x32_bf16 v[94:97], v[194:197], v[142:145], v[94:97]
	s_setprio 0
	s_barrier
	ds_read_b128 v[198:201], v175 offset:16384
	ds_read_b128 v[202:205], v175 offset:17408
	ds_read_b128 v[206:209], v175 offset:18432
	ds_read_b128 v[210:213], v175 offset:19456
	s_barrier
	s_waitcnt lgkmcnt(0)
	s_setprio 1
	s_waitcnt lgkmcnt(0)
	v_mfma_f32_16x16x32_bf16 v[50:53], v[146:149], v[198:201], v[50:53]
	v_mfma_f32_16x16x32_bf16 v[42:45], v[146:149], v[206:209], v[42:45]
	v_mfma_f32_16x16x32_bf16 v[38:41], v[154:157], v[198:201], v[38:41]
	v_mfma_f32_16x16x32_bf16 v[30:33], v[182:185], v[198:201], v[30:33]
	v_mfma_f32_16x16x32_bf16 v[22:25], v[190:193], v[198:201], v[22:25]
	v_mfma_f32_16x16x32_bf16 v[50:53], v[150:153], v[202:205], v[50:53]
	v_mfma_f32_16x16x32_bf16 v[42:45], v[150:153], v[210:213], v[42:45]
	v_mfma_f32_16x16x32_bf16 v[38:41], v[158:161], v[202:205], v[38:41]
	v_mfma_f32_16x16x32_bf16 v[34:37], v[154:157], v[206:209], v[34:37]
	v_mfma_f32_16x16x32_bf16 v[30:33], v[186:189], v[202:205], v[30:33]
	v_mfma_f32_16x16x32_bf16 v[26:29], v[182:185], v[206:209], v[26:29]
	v_mfma_f32_16x16x32_bf16 v[22:25], v[194:197], v[202:205], v[22:25]
	v_mfma_f32_16x16x32_bf16 v[18:21], v[190:193], v[206:209], v[18:21]
	v_mfma_f32_16x16x32_bf16 v[34:37], v[158:161], v[210:213], v[34:37]
	v_mfma_f32_16x16x32_bf16 v[26:29], v[186:189], v[210:213], v[26:29]
	v_mfma_f32_16x16x32_bf16 v[18:21], v[194:197], v[210:213], v[18:21]
	s_setprio 0
	s_barrier
	ds_read_b128 v[146:149], v176 offset:16384
	ds_read_b128 v[150:153], v176 offset:17408
	ds_read_b128 v[154:157], v176 offset:18432
	ds_read_b128 v[158:161], v176 offset:19456
	ds_read_b128 v[182:185], v176 offset:20480
	ds_read_b128 v[186:189], v176 offset:21504
	ds_read_b128 v[190:193], v176 offset:22528
	ds_read_b128 v[194:197], v176 offset:23552
	s_waitcnt vmcnt(4)
	s_barrier
	s_waitcnt lgkmcnt(0)
	s_setprio 1
	s_waitcnt lgkmcnt(0)
	v_mfma_f32_16x16x32_bf16 v[14:17], v[146:149], v[130:133], v[14:17]
	v_mfma_f32_16x16x32_bf16 v[6:9], v[154:157], v[130:133], v[6:9]
	v_mfma_f32_16x16x32_bf16 v[2:5], v[154:157], v[138:141], v[2:5]
	v_mfma_f32_16x16x32_bf16 v[46:49], v[182:185], v[130:133], v[46:49]
	v_mfma_f32_16x16x32_bf16 v[54:57], v[182:185], v[138:141], v[54:57]
	v_mfma_f32_16x16x32_bf16 v[58:61], v[190:193], v[130:133], v[58:61]
	v_mfma_f32_16x16x32_bf16 v[14:17], v[150:153], v[134:137], v[14:17]
	v_mfma_f32_16x16x32_bf16 v[10:13], v[146:149], v[138:141], v[10:13]
	v_mfma_f32_16x16x32_bf16 v[6:9], v[158:161], v[134:137], v[6:9]
	v_mfma_f32_16x16x32_bf16 v[2:5], v[158:161], v[142:145], v[2:5]
	v_mfma_f32_16x16x32_bf16 v[46:49], v[186:189], v[134:137], v[46:49]
	v_mfma_f32_16x16x32_bf16 v[54:57], v[186:189], v[142:145], v[54:57]
	v_mfma_f32_16x16x32_bf16 v[214:217], v[194:197], v[134:137], v[58:61]
	v_mfma_f32_16x16x32_bf16 v[58:61], v[190:193], v[138:141], v[62:65]
	v_mfma_f32_16x16x32_bf16 v[10:13], v[150:153], v[142:145], v[10:13]
	v_mfma_f32_16x16x32_bf16 v[218:221], v[194:197], v[142:145], v[58:61]
	s_setprio 0
	s_setprio 1
	v_mfma_f32_16x16x32_bf16 v[58:61], v[146:149], v[198:201], v[66:69]
	v_mfma_f32_16x16x32_bf16 v[222:225], v[150:153], v[202:205], v[58:61]
	v_mfma_f32_16x16x32_bf16 v[58:61], v[146:149], v[206:209], v[70:73]
	v_mfma_f32_16x16x32_bf16 v[226:229], v[150:153], v[210:213], v[58:61]
	v_mfma_f32_16x16x32_bf16 v[58:61], v[154:157], v[198:201], v[74:77]
	v_mfma_f32_16x16x32_bf16 v[230:233], v[158:161], v[202:205], v[58:61]
	v_mfma_f32_16x16x32_bf16 v[58:61], v[154:157], v[206:209], v[78:81]
	v_mfma_f32_16x16x32_bf16 v[234:237], v[158:161], v[210:213], v[58:61]
	v_mfma_f32_16x16x32_bf16 v[58:61], v[182:185], v[198:201], v[82:85]
	v_mfma_f32_16x16x32_bf16 v[238:241], v[186:189], v[202:205], v[58:61]
	v_mfma_f32_16x16x32_bf16 v[58:61], v[182:185], v[206:209], v[86:89]
	v_mfma_f32_16x16x32_bf16 v[182:185], v[186:189], v[210:213], v[58:61]
	v_mfma_f32_16x16x32_bf16 v[58:61], v[190:193], v[198:201], v[90:93]
	v_mfma_f32_16x16x32_bf16 v[186:189], v[194:197], v[202:205], v[58:61]
	v_mfma_f32_16x16x32_bf16 v[58:61], v[190:193], v[206:209], v[98:101]
	v_mfma_f32_16x16x32_bf16 v[190:193], v[194:197], v[210:213], v[58:61]
	s_setprio 0
	s_barrier
; #define LDA(dst, b, h)                                                                                     \
;   _Pragma("unroll") for (int m = 0; m < 4; ++m) _Pragma("unroll") for (int k = 0; k < 2; ++k) dst[m][k] = \
;       *reinterpret_cast<const bf16x8*>(shmc + aL + (((b) * 2 + (h)) * 16384 + (m * 2 + k) * 1024))
; #define LDB(dst, b, h)                                                                                     \
;   _Pragma("unroll") for (int n = 0; n < 2; ++n) _Pragma("unroll") for (int k = 0; k < 2; ++k) dst[n][k] = \
;       *reinterpret_cast<const bf16x8*>(shmc + bL + (((b) * 2 + (h)) * 16384 + (n * 2 + k) * 1024))
; #define WAIT_V(n) asm volatile("s_waitcnt vmcnt(" #n ")" ::: "memory")
; #define WAIT_L(n) asm volatile("s_waitcnt lgkmcnt(" #n ")" ::: "memory")
; #define BAR __builtin_amdgcn_s_barrier()
; template <int EPI>
; __device__ __forceinline__ void phase_gemm(const Params& p, const GemmDesc& d, char* shmc) {
;     ...
;     {
;       LDB(B0, 1, 0); LDA(At, 1, 0); WAIT_V(2); BAR; WAIT_L(0); MMA(0, 0, At, B0); BAR;
;       LDB(B1, 1, 1); WAIT_V(0); BAR; WAIT_L(0); MMA(0, 1, At, B1); BAR;
;       LDA(At, 1, 1); BAR; WAIT_L(0); MMA(1, 0, At, B0); MMA(1, 1, At, B1); BAR;
;     }
;     if (wr == 0) BAR;
	ds_read_b128 v[66:69], v175 offset:32768
	ds_read_b128 v[194:197], v175 offset:33792
	ds_read_b128 v[198:201], v175 offset:34816
	ds_read_b128 v[202:205], v175 offset:35840
	s_nop 0
	ds_read_b128 v[58:61], v176 offset:32768
	ds_read_b128 v[62:65], v176 offset:33792
	ds_read_b128 v[70:73], v176 offset:34816
	ds_read_b128 v[74:77], v176 offset:35840
	ds_read_b128 v[78:81], v176 offset:36864
	ds_read_b128 v[82:85], v176 offset:37888
	ds_read_b128 v[206:209], v176 offset:38912
	ds_read_b128 v[210:213], v176 offset:39936
	s_waitcnt vmcnt(2)
	s_barrier
	s_waitcnt lgkmcnt(0)
	s_setprio 1
	s_waitcnt lgkmcnt(0)
	v_mfma_f32_16x16x32_bf16 v[86:89], v[58:61], v[66:69], v[126:129]
	v_mfma_f32_16x16x32_bf16 v[158:161], v[62:65], v[194:197], v[86:89]
	v_mfma_f32_16x16x32_bf16 v[86:89], v[58:61], v[198:201], v[122:125]
	v_mfma_f32_16x16x32_bf16 v[142:145], v[62:65], v[202:205], v[86:89]
	v_mfma_f32_16x16x32_bf16 v[86:89], v[70:73], v[66:69], v[118:121]
	v_mfma_f32_16x16x32_bf16 v[154:157], v[74:77], v[194:197], v[86:89]
	v_mfma_f32_16x16x32_bf16 v[86:89], v[70:73], v[198:201], v[114:117]
	v_mfma_f32_16x16x32_bf16 v[138:141], v[74:77], v[202:205], v[86:89]
	v_mfma_f32_16x16x32_bf16 v[86:89], v[78:81], v[66:69], v[110:113]
	v_mfma_f32_16x16x32_bf16 v[150:153], v[82:85], v[194:197], v[86:89]
	v_mfma_f32_16x16x32_bf16 v[86:89], v[78:81], v[198:201], v[106:109]
	v_mfma_f32_16x16x32_bf16 v[134:137], v[82:85], v[202:205], v[86:89]
	v_mfma_f32_16x16x32_bf16 v[86:89], v[206:209], v[66:69], v[102:105]
	v_mfma_f32_16x16x32_bf16 v[146:149], v[210:213], v[194:197], v[86:89]
	v_mfma_f32_16x16x32_bf16 v[86:89], v[206:209], v[198:201], v[94:97]
	v_mfma_f32_16x16x32_bf16 v[130:133], v[210:213], v[202:205], v[86:89]
	s_setprio 0
	s_barrier
	ds_read_b128 v[94:97], v175 offset:49152
	ds_read_b128 v[102:105], v175 offset:50176
	ds_read_b128 v[106:109], v175 offset:51200
	ds_read_b128 v[118:121], v175 offset:52224
	s_waitcnt vmcnt(0)
	s_barrier
	s_waitcnt lgkmcnt(0)
	s_setprio 1
	s_waitcnt lgkmcnt(0)
	v_mfma_f32_16x16x32_bf16 v[50:53], v[58:61], v[94:97], v[50:53]
	v_mfma_f32_16x16x32_bf16 v[42:45], v[58:61], v[106:109], v[42:45]
	v_mfma_f32_16x16x32_bf16 v[38:41], v[70:73], v[94:97], v[38:41]
	v_mfma_f32_16x16x32_bf16 v[34:37], v[70:73], v[106:109], v[34:37]
	v_mfma_f32_16x16x32_bf16 v[30:33], v[78:81], v[94:97], v[30:33]
	v_mfma_f32_16x16x32_bf16 v[26:29], v[78:81], v[106:109], v[26:29]
	v_mfma_f32_16x16x32_bf16 v[22:25], v[206:209], v[94:97], v[22:25]
	v_mfma_f32_16x16x32_bf16 v[18:21], v[206:209], v[106:109], v[18:21]
	v_mfma_f32_16x16x32_bf16 v[126:129], v[62:65], v[102:105], v[50:53]
	v_mfma_f32_16x16x32_bf16 v[98:101], v[62:65], v[118:121], v[42:45]
	v_mfma_f32_16x16x32_bf16 v[122:125], v[74:77], v[102:105], v[38:41]
	v_mfma_f32_16x16x32_bf16 v[90:93], v[74:77], v[118:121], v[34:37]
	v_mfma_f32_16x16x32_bf16 v[114:117], v[82:85], v[102:105], v[30:33]
	v_mfma_f32_16x16x32_bf16 v[86:89], v[82:85], v[118:121], v[26:29]
	v_mfma_f32_16x16x32_bf16 v[110:113], v[210:213], v[102:105], v[22:25]
	v_mfma_f32_16x16x32_bf16 v[82:85], v[210:213], v[118:121], v[18:21]
	s_setprio 0
	s_barrier
	s_nop 0
	ds_read_b128 v[18:21], v176 offset:49152
	ds_read_b128 v[22:25], v176 offset:50176
	ds_read_b128 v[26:29], v176 offset:51200
	ds_read_b128 v[30:33], v176 offset:52224
	ds_read_b128 v[34:37], v176 offset:53248
	ds_read_b128 v[206:209], v176 offset:54272
	ds_read_b128 v[210:213], v176 offset:55296
	ds_read_b128 v[242:245], v176 offset:56320
	s_barrier
	s_waitcnt lgkmcnt(0)
	s_setprio 1
	s_waitcnt lgkmcnt(0)
	v_mfma_f32_16x16x32_bf16 v[2:5], v[26:29], v[198:201], v[2:5]
	v_mfma_f32_16x16x32_bf16 v[58:61], v[30:33], v[202:205], v[2:5]
	v_mfma_f32_16x16x32_bf16 v[2:5], v[34:37], v[66:69], v[46:49]
	v_mfma_f32_16x16x32_bf16 v[70:73], v[206:209], v[194:197], v[2:5]
	v_mfma_f32_16x16x32_bf16 v[2:5], v[34:37], v[198:201], v[54:57]
	v_mfma_f32_16x16x32_bf16 v[54:57], v[206:209], v[202:205], v[2:5]
	v_mfma_f32_16x16x32_bf16 v[2:5], v[210:213], v[66:69], v[214:217]
	v_mfma_f32_16x16x32_bf16 v[14:17], v[18:21], v[66:69], v[14:17]
	v_mfma_f32_16x16x32_bf16 v[10:13], v[18:21], v[198:201], v[10:13]
	v_mfma_f32_16x16x32_bf16 v[6:9], v[26:29], v[66:69], v[6:9]
	v_mfma_f32_16x16x32_bf16 v[66:69], v[242:245], v[194:197], v[2:5]
	v_mfma_f32_16x16x32_bf16 v[2:5], v[210:213], v[198:201], v[218:221]
	v_mfma_f32_16x16x32_bf16 v[78:81], v[22:25], v[194:197], v[14:17]
	v_mfma_f32_16x16x32_bf16 v[62:65], v[22:25], v[202:205], v[10:13]
	v_mfma_f32_16x16x32_bf16 v[74:77], v[30:33], v[194:197], v[6:9]
	v_mfma_f32_16x16x32_bf16 v[50:53], v[242:245], v[202:205], v[2:5]
	s_setprio 0
	s_setprio 1
	v_mfma_f32_16x16x32_bf16 v[2:5], v[18:21], v[94:97], v[222:225]
	v_mfma_f32_16x16x32_bf16 v[46:49], v[22:25], v[102:105], v[2:5]
	v_mfma_f32_16x16x32_bf16 v[2:5], v[18:21], v[106:109], v[226:229]
	v_mfma_f32_16x16x32_bf16 v[22:25], v[22:25], v[118:121], v[2:5]
	v_mfma_f32_16x16x32_bf16 v[2:5], v[26:29], v[94:97], v[230:233]
	v_mfma_f32_16x16x32_bf16 v[42:45], v[30:33], v[102:105], v[2:5]
	v_mfma_f32_16x16x32_bf16 v[2:5], v[26:29], v[106:109], v[234:237]
	v_mfma_f32_16x16x32_bf16 v[14:17], v[30:33], v[118:121], v[2:5]
	v_mfma_f32_16x16x32_bf16 v[2:5], v[34:37], v[94:97], v[238:241]
	v_mfma_f32_16x16x32_bf16 v[38:41], v[206:209], v[102:105], v[2:5]
	v_mfma_f32_16x16x32_bf16 v[2:5], v[34:37], v[106:109], v[182:185]
	v_mfma_f32_16x16x32_bf16 v[6:9], v[206:209], v[118:121], v[2:5]
	v_mfma_f32_16x16x32_bf16 v[2:5], v[210:213], v[94:97], v[186:189]
	v_mfma_f32_16x16x32_bf16 v[30:33], v[242:245], v[102:105], v[2:5]
	v_mfma_f32_16x16x32_bf16 v[2:5], v[210:213], v[106:109], v[190:193]
	v_mfma_f32_16x16x32_bf16 v[2:5], v[242:245], v[118:121], v[2:5]
	s_setprio 0
	s_barrier
	s_and_saveexec_b64 s[8:9], s[6:7]
	s_cbranch_execz .LBB0_601
	s_barrier

; #define WAIT_V(n) asm volatile("s_waitcnt vmcnt(" #n ")" ::: "memory")
; #define BAR __builtin_amdgcn_s_barrier()
; template <int EPI>
; __device__ __forceinline__ void phase_gemm(const Params& p, const GemmDesc& d, char* shmc) {
;     ...
;     f32x4 acc[2][2][4][2];
; #pragma unroll
;     for (int a = 0; a < 2; ++a)
; #pragma unroll
;       for (int b = 0; b < 2; ++b)
; #pragma unroll
;         for (int m = 0; m < 4; ++m)
; #pragma unroll
;           for (int n = 0; n < 2; ++n) acc[a][b][m][n] = f32x4{0.f, 0.f, 0.f, 0.f};
;     bf16x8 At[4][2], B0[2][2], B1[2][2];
;     if constexpr (EPI == EPI_UP || EPI == EPI_QKV) {
;       if (wid == 0)
;         __builtin_amdgcn_global_load_lds((const unsigned*)(p.rstd + brow + lane * 4), (unsigned*)(shmc + 143360), 16, 0, 0);
;     }
;     STAGE_B(SB(0, 0), 0, 0); STAGE_A(SA(0, 0), 0, 0);
;     STAGE_B(SB(0, 1), 1, 0); STAGE_A(SA(0, 1), 1, 0);
;     if (wr == 1) BAR;
;     WAIT_V(4); BAR;
;     STAGE_B(SB(1, 0), 0, 1); STAGE_A(SA(1, 0), 0, 1); STAGE_B(SB(1, 1), 1, 1);
;     WAIT_V(6); BAR;
;     for (int t = 0; t < nt - 2; t += 2) {
.LBB0_1009:
	s_or_b64 exec, exec, s[62:63]
	v_mov_b32_e32 v141, v131
	s_waitcnt lgkmcnt(0)
	v_lshl_add_u64 v[2:3], s[60:61], 0, v[140:141]
	v_mov_b32_e32 v143, v131
	s_mov_b32 m0, s70
	v_lshl_add_u64 v[4:5], s[60:61], 0, v[142:143]
	v_lshl_add_u64 v[2:3], v[2:3], 0, s[8:9]
	v_lshl_add_u64 v[6:7], s[56:57], 0, v[140:141]
	v_mov_b32_e32 v10, 0
	v_mov_b32_e32 v11, 0
	v_mov_b32_e32 v12, 0
	v_mov_b32_e32 v13, 0
	v_mov_b32_e32 v14, 0
	v_mov_b32_e32 v15, 0
	v_mov_b32_e32 v16, 0
	v_mov_b32_e32 v17, 0
	v_mov_b32_e32 v18, 0
	v_mov_b32_e32 v19, 0
	v_mov_b32_e32 v20, 0
	v_mov_b32_e32 v21, 0
	v_mov_b32_e32 v22, 0
	v_mov_b32_e32 v23, 0
	v_mov_b32_e32 v24, 0
	v_mov_b32_e32 v25, 0
	v_mov_b32_e32 v26, 0
	v_mov_b32_e32 v27, 0
	v_mov_b32_e32 v28, 0
	v_mov_b32_e32 v29, 0
	v_mov_b32_e32 v30, 0
	v_mov_b32_e32 v31, 0
	v_mov_b32_e32 v32, 0
	v_mov_b32_e32 v33, 0
	v_mov_b32_e32 v34, 0
	v_mov_b32_e32 v35, 0
	v_mov_b32_e32 v36, 0
	v_mov_b32_e32 v37, 0
	v_mov_b32_e32 v38, 0
	v_mov_b32_e32 v39, 0
	v_mov_b32_e32 v40, 0
	v_mov_b32_e32 v41, 0
	v_mov_b32_e32 v42, 0
	v_mov_b32_e32 v43, 0
	v_mov_b32_e32 v44, 0
	v_mov_b32_e32 v45, 0
	v_mov_b32_e32 v46, 0
	v_mov_b32_e32 v47, 0
	v_mov_b32_e32 v48, 0
	v_mov_b32_e32 v49, 0
	v_mov_b32_e32 v50, 0
	v_mov_b32_e32 v51, 0
	v_mov_b32_e32 v52, 0
	v_mov_b32_e32 v53, 0
	v_mov_b32_e32 v54, 0
	v_mov_b32_e32 v55, 0
	v_mov_b32_e32 v56, 0
	v_mov_b32_e32 v57, 0
	v_mov_b32_e32 v70, 0
	v_mov_b32_e32 v71, 0
	v_mov_b32_e32 v72, 0
	v_mov_b32_e32 v73, 0
	v_mov_b32_e32 v86, 0
	v_mov_b32_e32 v87, 0
	v_mov_b32_e32 v88, 0
	v_mov_b32_e32 v89, 0
	v_mov_b32_e32 v98, 0
	v_mov_b32_e32 v99, 0
	v_mov_b32_e32 v100, 0
	v_mov_b32_e32 v101, 0
	v_mov_b32_e32 v102, 0
	v_mov_b32_e32 v103, 0
	v_mov_b32_e32 v104, 0
	v_mov_b32_e32 v105, 0
	v_mov_b32_e32 v106, 0
	v_mov_b32_e32 v107, 0
	v_mov_b32_e32 v108, 0
	v_mov_b32_e32 v109, 0
	v_mov_b32_e32 v110, 0
	v_mov_b32_e32 v111, 0
	v_mov_b32_e32 v112, 0
	v_mov_b32_e32 v113, 0
	v_mov_b32_e32 v114, 0
	v_mov_b32_e32 v115, 0
	v_mov_b32_e32 v116, 0
	v_mov_b32_e32 v117, 0
	v_mov_b32_e32 v118, 0
	v_mov_b32_e32 v119, 0
	v_mov_b32_e32 v120, 0
	v_mov_b32_e32 v121, 0
	v_mov_b32_e32 v122, 0
	v_mov_b32_e32 v123, 0
	v_mov_b32_e32 v124, 0
	v_mov_b32_e32 v125, 0
	v_mov_b32_e32 v126, 0
	v_mov_b32_e32 v127, 0
	v_mov_b32_e32 v128, 0
	v_mov_b32_e32 v129, 0
	v_mov_b32_e32 v58, 0
	v_mov_b32_e32 v59, 0
	v_mov_b32_e32 v60, 0
	v_mov_b32_e32 v61, 0
	v_mov_b32_e32 v62, 0
	v_mov_b32_e32 v63, 0
	v_mov_b32_e32 v64, 0
	v_mov_b32_e32 v65, 0
	v_mov_b32_e32 v66, 0
	v_mov_b32_e32 v67, 0
	v_mov_b32_e32 v68, 0
	v_mov_b32_e32 v69, 0
	v_mov_b32_e32 v74, 0
	v_mov_b32_e32 v75, 0
	v_mov_b32_e32 v76, 0
	v_mov_b32_e32 v77, 0
	v_mov_b32_e32 v78, 0
	v_mov_b32_e32 v79, 0
	v_mov_b32_e32 v80, 0
	v_mov_b32_e32 v81, 0
	v_mov_b32_e32 v82, 0
	v_mov_b32_e32 v83, 0
	v_mov_b32_e32 v84, 0
	v_mov_b32_e32 v85, 0
	v_mov_b32_e32 v90, 0
	v_mov_b32_e32 v91, 0
	v_mov_b32_e32 v92, 0
	v_mov_b32_e32 v93, 0
	v_mov_b32_e32 v94, 0
	v_mov_b32_e32 v95, 0
	v_mov_b32_e32 v96, 0
	v_mov_b32_e32 v97, 0
	s_waitcnt vmcnt(2)
	s_barrier
	global_load_lds_dwordx4 v[2:3], off
	v_lshl_add_u64 v[2:3], v[4:5], 0, s[8:9]
	s_mov_b32 m0, s71
	v_lshl_add_u64 v[8:9], s[56:57], 0, v[142:143]
	global_load_lds_dwordx4 v[2:3], off
	v_lshl_add_u64 v[2:3], v[6:7], 0, s[8:9]
	s_mov_b32 m0, s76
	s_add_u32 s60, s60, 0x80080
	global_load_lds_dwordx4 v[2:3], off
	v_lshl_add_u64 v[2:3], v[8:9], 0, s[8:9]
	s_mov_b32 m0, s77
	s_addc_u32 s61, s61, 0
	global_load_lds_dwordx4 v[2:3], off
	s_mov_b32 m0, s78
	v_lshl_add_u64 v[144:145], v[132:133], 0, s[58:59]
	global_load_lds_dwordx4 v140, s[60:61]
	s_mov_b32 m0, s79
	v_lshl_add_u64 v[146:147], v[134:135], 0, s[58:59]
	global_load_lds_dwordx4 v142, s[60:61]
	s_add_i32 s58, s83, s84
	s_waitcnt vmcnt(6)
	s_ashr_i32 s59, s58, 31
	s_lshl_b64 s[58:59], s[58:59], 12
	v_mov_b32_e32 v2, 0
	v_lshl_add_u64 v[148:149], v[136:137], 0, s[58:59]
	v_lshl_add_u64 v[150:151], v[138:139], 0, s[58:59]
	s_mov_b32 s53, -2
	s_mov_b64 s[58:59], 0
	v_mov_b32_e32 v3, v2
	v_mov_b32_e32 v4, v2
	v_mov_b32_e32 v5, v2
	v_mov_b32_e32 v6, v2
	v_mov_b32_e32 v7, v2
	v_mov_b32_e32 v8, v2
	v_mov_b32_e32 v9, v2
	s_barrier
	v_readfirstlane_b32 s98, v148
	v_readfirstlane_b32 s99, v149
	v_readfirstlane_b32 s100, v144
	v_readfirstlane_b32 s101, v145
	s_nop 3
	v_subrev_u32_e32 v220, s98, v148
	v_add_u32_e32 v220, s10, v220
	v_subrev_u32_e32 v221, s98, v150
	v_add_u32_e32 v221, s10, v221
	v_subrev_u32_e32 v222, s100, v144
	v_add_u32_e32 v222, s22, v222
	v_subrev_u32_e32 v223, s100, v146
	v_add_u32_e32 v223, s22, v223
	v_subrev_u32_e32 v224, s98, v148
	v_add_u32_e32 v224, s26, v224
	v_subrev_u32_e32 v225, s98, v150
	v_add_u32_e32 v225, s26, v225
	v_subrev_u32_e32 v226, s100, v144
	v_add_u32_e32 v226, s36, v226
	v_subrev_u32_e32 v227, s100, v146
	v_add_u32_e32 v227, s36, v227
	v_subrev_u32_e32 v228, s98, v148
	v_add_u32_e32 v228, s38, v228
	v_subrev_u32_e32 v229, s98, v150
	v_add_u32_e32 v229, s38, v229
	v_subrev_u32_e32 v232, s100, v144
	v_add_u32_e32 v232, s40, v232
	v_subrev_u32_e32 v233, s100, v146
	v_add_u32_e32 v233, s40, v233
	v_subrev_u32_e32 v234, s98, v148
	v_add_u32_e32 v234, s42, v234
	v_subrev_u32_e32 v235, s98, v150
	v_add_u32_e32 v235, s42, v235
	v_subrev_u32_e32 v236, s100, v144
	v_add_u32_e32 v236, s48, v236
	v_subrev_u32_e32 v237, s100, v146
	v_add_u32_e32 v237, s48, v237
	s_add_u32 s98, s98, s58
	s_addc_u32 s99, s99, s59
	s_add_u32 s100, s100, s58
	s_addc_u32 s101, s101, s59
; #define LDA(dst, b, h)                                                                                     \
;   _Pragma("unroll") for (int m = 0; m < 4; ++m) _Pragma("unroll") for (int k = 0; k < 2; ++k) dst[m][k] = \
;       *reinterpret_cast<const bf16x8*>(shmc + aL + (((b) * 2 + (h)) * 16384 + (m * 2 + k) * 1024))
; #define LDB(dst, b, h)                                                                                     \
;   _Pragma("unroll") for (int n = 0; n < 2; ++n) _Pragma("unroll") for (int k = 0; k < 2; ++k) dst[n][k] = \
;       *reinterpret_cast<const bf16x8*>(shmc + bL + (((b) * 2 + (h)) * 16384 + (n * 2 + k) * 1024))
; #define OPAQ asm volatile("" : "+v"(aL), "+v"(bL))
; #define WAIT_V(n) asm volatile("s_waitcnt vmcnt(" #n ")" ::: "memory")
; #define WAIT_L(n) asm volatile("s_waitcnt lgkmcnt(" #n ")" ::: "memory")
; #define BAR __builtin_amdgcn_s_barrier()
; #define SCHED __builtin_amdgcn_sched_barrier(0)
; template <int EPI>
; __device__ __forceinline__ void phase_gemm(const Params& p, const GemmDesc& d, char* shmc) {
;     ...
;     for (int t = 0; t < nt - 2; t += 2) {
;       OPAQ;
;       LDB(B0, 0, 0); SCHED; LDA(At, 0, 0); STAGE_A(SA(1, 1), 1, t + 1);
;       WAIT_L(8); BAR; WAIT_L(0); MMA(0, 0, At, B0); BAR; SCHED;
;       LDB(B1, 0, 1); STAGE_B(SB(0, 0), 0, t + 2);
;       BAR; WAIT_L(0); MMA(0, 1, At, B1); BAR;
;       LDA(At, 0, 1); STAGE_A(SA(0, 0), 0, t + 2);
;       BAR; WAIT_L(0); MMA(1, 0, At, B0); BAR; SCHED;
;       STAGE_B(SB(0, 1), 1, t + 2);
;       WAIT_V(6); BAR; MMA(1, 1, At, B1); BAR;
.LBB0_1010:
	s_nop 0
	v_add_u32_e32 v130, 0, v153
	v_add_u32_e32 v141, 0, v152
	s_setprio 0
	ds_read_b128 v[156:159], v130
	ds_read_b128 v[160:163], v130 offset:1024
	ds_read_b128 v[164:167], v130 offset:2048
	ds_read_b128 v[168:171], v130 offset:3072
	ds_read_b128 v[204:207], v130 offset:16384
	ds_read_b128 v[208:211], v130 offset:17408
	ds_read_b128 v[212:215], v130 offset:18432
	ds_read_b128 v[216:219], v130 offset:19456
	ds_read_b128 v[172:175], v141
	ds_read_b128 v[176:179], v141 offset:1024
	ds_read_b128 v[180:183], v141 offset:2048
	ds_read_b128 v[184:187], v141 offset:3072
	ds_read_b128 v[188:191], v141 offset:4096
	ds_read_b128 v[192:195], v141 offset:5120
	ds_read_b128 v[196:199], v141 offset:6144
	ds_read_b128 v[200:203], v141 offset:7168
	s_mov_b32 m0, s80
	s_nop 0
	global_load_lds_dwordx4 v220, s[98:99]
	s_mov_b32 m0, s81
	s_nop 0
	global_load_lds_dwordx4 v221, s[98:99]
	s_waitcnt vmcnt(8)
	s_waitcnt lgkmcnt(0)
	s_setprio 1
	s_barrier
	v_mfma_f32_16x16x32_bf16 v[126:129], v[156:159], v[172:175], v[126:129]
	v_mfma_f32_16x16x32_bf16 v[122:125], v[164:167], v[172:175], v[122:125]
	v_mfma_f32_16x16x32_bf16 v[118:121], v[156:159], v[180:183], v[118:121]
	v_mfma_f32_16x16x32_bf16 v[114:117], v[164:167], v[180:183], v[114:117]
	v_mfma_f32_16x16x32_bf16 v[110:113], v[156:159], v[188:191], v[110:113]
	v_mfma_f32_16x16x32_bf16 v[106:109], v[164:167], v[188:191], v[106:109]
	v_mfma_f32_16x16x32_bf16 v[102:105], v[156:159], v[196:199], v[102:105]
	v_mfma_f32_16x16x32_bf16 v[98:101], v[164:167], v[196:199], v[98:101]
	v_mfma_f32_16x16x32_bf16 v[126:129], v[160:163], v[176:179], v[126:129]
	v_mfma_f32_16x16x32_bf16 v[122:125], v[168:171], v[176:179], v[122:125]
	v_mfma_f32_16x16x32_bf16 v[118:121], v[160:163], v[184:187], v[118:121]
	v_mfma_f32_16x16x32_bf16 v[114:117], v[168:171], v[184:187], v[114:117]
	v_mfma_f32_16x16x32_bf16 v[110:113], v[160:163], v[192:195], v[110:113]
	v_mfma_f32_16x16x32_bf16 v[106:109], v[168:171], v[192:195], v[106:109]
	v_mfma_f32_16x16x32_bf16 v[102:105], v[160:163], v[200:203], v[102:105]
	v_mfma_f32_16x16x32_bf16 v[98:101], v[168:171], v[200:203], v[98:101]
	v_mfma_f32_16x16x32_bf16 v[86:89], v[204:207], v[172:175], v[86:89]
	v_mfma_f32_16x16x32_bf16 v[70:73], v[212:215], v[172:175], v[70:73]
	v_mfma_f32_16x16x32_bf16 v[54:57], v[204:207], v[180:183], v[54:57]
	v_mfma_f32_16x16x32_bf16 v[50:53], v[212:215], v[180:183], v[50:53]
	v_mfma_f32_16x16x32_bf16 v[46:49], v[204:207], v[188:191], v[46:49]
	v_mfma_f32_16x16x32_bf16 v[42:45], v[212:215], v[188:191], v[42:45]
	v_mfma_f32_16x16x32_bf16 v[38:41], v[204:207], v[196:199], v[38:41]
	v_mfma_f32_16x16x32_bf16 v[34:37], v[212:215], v[196:199], v[34:37]
	v_mfma_f32_16x16x32_bf16 v[86:89], v[208:211], v[176:179], v[86:89]
	v_mfma_f32_16x16x32_bf16 v[70:73], v[216:219], v[176:179], v[70:73]
	v_mfma_f32_16x16x32_bf16 v[54:57], v[208:211], v[184:187], v[54:57]
	v_mfma_f32_16x16x32_bf16 v[50:53], v[216:219], v[184:187], v[50:53]
	v_mfma_f32_16x16x32_bf16 v[46:49], v[208:211], v[192:195], v[46:49]
	v_mfma_f32_16x16x32_bf16 v[42:45], v[216:219], v[192:195], v[42:45]
	v_mfma_f32_16x16x32_bf16 v[38:41], v[208:211], v[200:203], v[38:41]
	v_mfma_f32_16x16x32_bf16 v[34:37], v[216:219], v[200:203], v[34:37]
	s_barrier
	s_setprio 0
	ds_read_b128 v[172:175], v141 offset:16384
	ds_read_b128 v[176:179], v141 offset:17408
	ds_read_b128 v[180:183], v141 offset:18432
	ds_read_b128 v[184:187], v141 offset:19456
	ds_read_b128 v[188:191], v141 offset:20480
	ds_read_b128 v[192:195], v141 offset:21504
	ds_read_b128 v[196:199], v141 offset:22528
	ds_read_b128 v[200:203], v141 offset:23552
	s_mov_b32 m0, s35
	s_nop 0
	global_load_lds_dwordx4 v222, s[100:101]
	s_mov_b32 m0, s64
	s_nop 0
	global_load_lds_dwordx4 v223, s[100:101]
	s_mov_b32 m0, s34
	s_nop 0
	global_load_lds_dwordx4 v224, s[98:99]
	s_mov_b32 m0, s65
	s_nop 0
	global_load_lds_dwordx4 v225, s[98:99]
	s_mov_b32 m0, s66
	s_nop 0
	global_load_lds_dwordx4 v226, s[100:101]
	s_mov_b32 m0, s67
	s_nop 0
	global_load_lds_dwordx4 v227, s[100:101]
	s_waitcnt vmcnt(8)
	s_waitcnt lgkmcnt(0)
	s_setprio 1
	s_barrier
	v_mfma_f32_16x16x32_bf16 v[30:33], v[156:159], v[172:175], v[30:33]
	v_mfma_f32_16x16x32_bf16 v[26:29], v[164:167], v[172:175], v[26:29]
	v_mfma_f32_16x16x32_bf16 v[22:25], v[156:159], v[180:183], v[22:25]
	v_mfma_f32_16x16x32_bf16 v[18:21], v[164:167], v[180:183], v[18:21]
	v_mfma_f32_16x16x32_bf16 v[14:17], v[156:159], v[188:191], v[14:17]
	v_mfma_f32_16x16x32_bf16 v[10:13], v[164:167], v[188:191], v[10:13]
	v_mfma_f32_16x16x32_bf16 v[6:9], v[156:159], v[196:199], v[6:9]
	v_mfma_f32_16x16x32_bf16 v[2:5], v[164:167], v[196:199], v[2:5]
	v_mfma_f32_16x16x32_bf16 v[30:33], v[160:163], v[176:179], v[30:33]
	v_mfma_f32_16x16x32_bf16 v[26:29], v[168:171], v[176:179], v[26:29]
	v_mfma_f32_16x16x32_bf16 v[22:25], v[160:163], v[184:187], v[22:25]
	v_mfma_f32_16x16x32_bf16 v[18:21], v[168:171], v[184:187], v[18:21]
	v_mfma_f32_16x16x32_bf16 v[14:17], v[160:163], v[192:195], v[14:17]
	v_mfma_f32_16x16x32_bf16 v[10:13], v[168:171], v[192:195], v[10:13]
	v_mfma_f32_16x16x32_bf16 v[6:9], v[160:163], v[200:203], v[6:9]
	v_mfma_f32_16x16x32_bf16 v[2:5], v[168:171], v[200:203], v[2:5]
	v_mfma_f32_16x16x32_bf16 v[58:61], v[204:207], v[172:175], v[58:61]
	v_mfma_f32_16x16x32_bf16 v[62:65], v[212:215], v[172:175], v[62:65]
	v_mfma_f32_16x16x32_bf16 v[66:69], v[204:207], v[180:183], v[66:69]
	v_mfma_f32_16x16x32_bf16 v[74:77], v[212:215], v[180:183], v[74:77]
	v_mfma_f32_16x16x32_bf16 v[78:81], v[204:207], v[188:191], v[78:81]
	v_mfma_f32_16x16x32_bf16 v[82:85], v[212:215], v[188:191], v[82:85]
	v_mfma_f32_16x16x32_bf16 v[90:93], v[204:207], v[196:199], v[90:93]
	v_mfma_f32_16x16x32_bf16 v[94:97], v[212:215], v[196:199], v[94:97]
	v_mfma_f32_16x16x32_bf16 v[58:61], v[208:211], v[176:179], v[58:61]
	v_mfma_f32_16x16x32_bf16 v[62:65], v[216:219], v[176:179], v[62:65]
	v_mfma_f32_16x16x32_bf16 v[66:69], v[208:211], v[184:187], v[66:69]
	v_mfma_f32_16x16x32_bf16 v[74:77], v[216:219], v[184:187], v[74:77]
	v_mfma_f32_16x16x32_bf16 v[78:81], v[208:211], v[192:195], v[78:81]
	v_mfma_f32_16x16x32_bf16 v[82:85], v[216:219], v[192:195], v[82:85]
	v_mfma_f32_16x16x32_bf16 v[90:93], v[208:211], v[200:203], v[90:93]
	v_mfma_f32_16x16x32_bf16 v[94:97], v[216:219], v[200:203], v[94:97]
	s_barrier
; #define LDA(dst, b, h)                                                                                     \
;   _Pragma("unroll") for (int m = 0; m < 4; ++m) _Pragma("unroll") for (int k = 0; k < 2; ++k) dst[m][k] = \
;       *reinterpret_cast<const bf16x8*>(shmc + aL + (((b) * 2 + (h)) * 16384 + (m * 2 + k) * 1024))
; #define LDB(dst, b, h)                                                                                     \
;   _Pragma("unroll") for (int n = 0; n < 2; ++n) _Pragma("unroll") for (int k = 0; k < 2; ++k) dst[n][k] = \
;       *reinterpret_cast<const bf16x8*>(shmc + bL + (((b) * 2 + (h)) * 16384 + (n * 2 + k) * 1024))
; #define WAIT_V(n) asm volatile("s_waitcnt vmcnt(" #n ")" ::: "memory")
; #define WAIT_L(n) asm volatile("s_waitcnt lgkmcnt(" #n ")" ::: "memory")
; #define BAR __builtin_amdgcn_s_barrier()
; #define SCHED __builtin_amdgcn_sched_barrier(0)
; template <int EPI>
; __device__ __forceinline__ void phase_gemm(const Params& p, const GemmDesc& d, char* shmc) {
;     ...
;       LDB(B0, 1, 0); SCHED; LDA(At, 1, 0); STAGE_A(SA(0, 1), 1, t + 2);
;       WAIT_L(8); BAR; WAIT_L(0); MMA(0, 0, At, B0); BAR; SCHED;
;       LDB(B1, 1, 1); STAGE_B(SB(1, 0), 0, t + 3);
;       BAR; WAIT_L(0); MMA(0, 1, At, B1); BAR;
;       LDA(At, 1, 1); STAGE_A(SA(1, 0), 0, t + 3);
;       BAR; WAIT_L(0); MMA(1, 0, At, B0); BAR; SCHED;
;       STAGE_B(SB(1, 1), 1, t + 3);
;       WAIT_V(6); BAR; MMA(1, 1, At, B1); BAR;
;     }
	s_setprio 0
	ds_read_b128 v[156:159], v130 offset:32768
	ds_read_b128 v[160:163], v130 offset:33792
	ds_read_b128 v[164:167], v130 offset:34816
	ds_read_b128 v[168:171], v130 offset:35840
	ds_read_b128 v[204:207], v130 offset:49152
	ds_read_b128 v[208:211], v130 offset:50176
	ds_read_b128 v[212:215], v130 offset:51200
	ds_read_b128 v[216:219], v130 offset:52224
	ds_read_b128 v[172:175], v141 offset:32768
	ds_read_b128 v[176:179], v141 offset:33792
	ds_read_b128 v[180:183], v141 offset:34816
	ds_read_b128 v[184:187], v141 offset:35840
	ds_read_b128 v[188:191], v141 offset:36864
	ds_read_b128 v[192:195], v141 offset:37888
	ds_read_b128 v[196:199], v141 offset:38912
	ds_read_b128 v[200:203], v141 offset:39936
	s_mov_b32 m0, s68
	s_nop 0
	global_load_lds_dwordx4 v228, s[98:99]
	s_mov_b32 m0, s69
	s_nop 0
	global_load_lds_dwordx4 v229, s[98:99]
	s_waitcnt vmcnt(8)
	s_waitcnt lgkmcnt(0)
	s_setprio 1
	s_barrier
	v_mfma_f32_16x16x32_bf16 v[126:129], v[156:159], v[172:175], v[126:129]
	v_mfma_f32_16x16x32_bf16 v[122:125], v[164:167], v[172:175], v[122:125]
	v_mfma_f32_16x16x32_bf16 v[118:121], v[156:159], v[180:183], v[118:121]
	v_mfma_f32_16x16x32_bf16 v[114:117], v[164:167], v[180:183], v[114:117]
	v_mfma_f32_16x16x32_bf16 v[110:113], v[156:159], v[188:191], v[110:113]
	v_mfma_f32_16x16x32_bf16 v[106:109], v[164:167], v[188:191], v[106:109]
	v_mfma_f32_16x16x32_bf16 v[102:105], v[156:159], v[196:199], v[102:105]
	v_mfma_f32_16x16x32_bf16 v[98:101], v[164:167], v[196:199], v[98:101]
	v_mfma_f32_16x16x32_bf16 v[126:129], v[160:163], v[176:179], v[126:129]
	v_mfma_f32_16x16x32_bf16 v[122:125], v[168:171], v[176:179], v[122:125]
	v_mfma_f32_16x16x32_bf16 v[118:121], v[160:163], v[184:187], v[118:121]
	v_mfma_f32_16x16x32_bf16 v[114:117], v[168:171], v[184:187], v[114:117]
	v_mfma_f32_16x16x32_bf16 v[110:113], v[160:163], v[192:195], v[110:113]
	v_mfma_f32_16x16x32_bf16 v[106:109], v[168:171], v[192:195], v[106:109]
	v_mfma_f32_16x16x32_bf16 v[102:105], v[160:163], v[200:203], v[102:105]
	v_mfma_f32_16x16x32_bf16 v[98:101], v[168:171], v[200:203], v[98:101]
	v_mfma_f32_16x16x32_bf16 v[86:89], v[204:207], v[172:175], v[86:89]
	v_mfma_f32_16x16x32_bf16 v[70:73], v[212:215], v[172:175], v[70:73]
	v_mfma_f32_16x16x32_bf16 v[54:57], v[204:207], v[180:183], v[54:57]
	v_mfma_f32_16x16x32_bf16 v[50:53], v[212:215], v[180:183], v[50:53]
	v_mfma_f32_16x16x32_bf16 v[46:49], v[204:207], v[188:191], v[46:49]
	v_mfma_f32_16x16x32_bf16 v[42:45], v[212:215], v[188:191], v[42:45]
	v_mfma_f32_16x16x32_bf16 v[38:41], v[204:207], v[196:199], v[38:41]
	v_mfma_f32_16x16x32_bf16 v[34:37], v[212:215], v[196:199], v[34:37]
	v_mfma_f32_16x16x32_bf16 v[86:89], v[208:211], v[176:179], v[86:89]
	v_mfma_f32_16x16x32_bf16 v[70:73], v[216:219], v[176:179], v[70:73]
	v_mfma_f32_16x16x32_bf16 v[54:57], v[208:211], v[184:187], v[54:57]
	v_mfma_f32_16x16x32_bf16 v[50:53], v[216:219], v[184:187], v[50:53]
	v_mfma_f32_16x16x32_bf16 v[46:49], v[208:211], v[192:195], v[46:49]
	v_mfma_f32_16x16x32_bf16 v[42:45], v[216:219], v[192:195], v[42:45]
	v_mfma_f32_16x16x32_bf16 v[38:41], v[208:211], v[200:203], v[38:41]
	v_mfma_f32_16x16x32_bf16 v[34:37], v[216:219], v[200:203], v[34:37]
	s_barrier
	s_setprio 0
	ds_read_b128 v[172:175], v141 offset:49152
	ds_read_b128 v[176:179], v141 offset:50176
	ds_read_b128 v[180:183], v141 offset:51200
	ds_read_b128 v[184:187], v141 offset:52224
	ds_read_b128 v[188:191], v141 offset:53248
	ds_read_b128 v[192:195], v141 offset:54272
	ds_read_b128 v[196:199], v141 offset:55296
	ds_read_b128 v[200:203], v141 offset:56320
	s_mov_b32 m0, s70
	s_nop 0
	global_load_lds_dwordx4 v232, s[100:101]
	s_mov_b32 m0, s71
	s_nop 0
	global_load_lds_dwordx4 v233, s[100:101]
	s_mov_b32 m0, s76
	s_nop 0
	global_load_lds_dwordx4 v234, s[98:99]
	s_mov_b32 m0, s77
	s_nop 0
	global_load_lds_dwordx4 v235, s[98:99]
	s_mov_b32 m0, s78
	s_nop 0
	global_load_lds_dwordx4 v236, s[100:101]
	s_mov_b32 m0, s79
	s_nop 0
	global_load_lds_dwordx4 v237, s[100:101]
	s_add_i32 s53, s53, 2
	s_add_u32 s58, s58, 0x100
	s_addc_u32 s59, s59, 0
	s_add_u32 s98, s98, 0x100
	s_addc_u32 s99, s99, 0
	s_add_u32 s100, s100, 0x100
	s_addc_u32 s101, s101, 0
	s_cmp_gt_u32 s53, 27
	s_waitcnt vmcnt(8)
	s_waitcnt lgkmcnt(0)
	s_setprio 1
	s_barrier
	v_mfma_f32_16x16x32_bf16 v[30:33], v[156:159], v[172:175], v[30:33]
	v_mfma_f32_16x16x32_bf16 v[26:29], v[164:167], v[172:175], v[26:29]
	v_mfma_f32_16x16x32_bf16 v[22:25], v[156:159], v[180:183], v[22:25]
	v_mfma_f32_16x16x32_bf16 v[18:21], v[164:167], v[180:183], v[18:21]
	v_mfma_f32_16x16x32_bf16 v[14:17], v[156:159], v[188:191], v[14:17]
	v_mfma_f32_16x16x32_bf16 v[10:13], v[164:167], v[188:191], v[10:13]
	v_mfma_f32_16x16x32_bf16 v[6:9], v[156:159], v[196:199], v[6:9]
	v_mfma_f32_16x16x32_bf16 v[2:5], v[164:167], v[196:199], v[2:5]
	v_mfma_f32_16x16x32_bf16 v[30:33], v[160:163], v[176:179], v[30:33]
	v_mfma_f32_16x16x32_bf16 v[26:29], v[168:171], v[176:179], v[26:29]
	v_mfma_f32_16x16x32_bf16 v[22:25], v[160:163], v[184:187], v[22:25]
	v_mfma_f32_16x16x32_bf16 v[18:21], v[168:171], v[184:187], v[18:21]
	v_mfma_f32_16x16x32_bf16 v[14:17], v[160:163], v[192:195], v[14:17]
	v_mfma_f32_16x16x32_bf16 v[10:13], v[168:171], v[192:195], v[10:13]
	v_mfma_f32_16x16x32_bf16 v[6:9], v[160:163], v[200:203], v[6:9]
	v_mfma_f32_16x16x32_bf16 v[2:5], v[168:171], v[200:203], v[2:5]
	v_mfma_f32_16x16x32_bf16 v[58:61], v[204:207], v[172:175], v[58:61]
	v_mfma_f32_16x16x32_bf16 v[62:65], v[212:215], v[172:175], v[62:65]
	v_mfma_f32_16x16x32_bf16 v[66:69], v[204:207], v[180:183], v[66:69]
	v_mfma_f32_16x16x32_bf16 v[74:77], v[212:215], v[180:183], v[74:77]
	v_mfma_f32_16x16x32_bf16 v[78:81], v[204:207], v[188:191], v[78:81]
	v_mfma_f32_16x16x32_bf16 v[82:85], v[212:215], v[188:191], v[82:85]
	v_mfma_f32_16x16x32_bf16 v[90:93], v[204:207], v[196:199], v[90:93]
	v_mfma_f32_16x16x32_bf16 v[94:97], v[212:215], v[196:199], v[94:97]
	v_mfma_f32_16x16x32_bf16 v[58:61], v[208:211], v[176:179], v[58:61]
	v_mfma_f32_16x16x32_bf16 v[62:65], v[216:219], v[176:179], v[62:65]
	v_mfma_f32_16x16x32_bf16 v[66:69], v[208:211], v[184:187], v[66:69]
	v_mfma_f32_16x16x32_bf16 v[74:77], v[216:219], v[184:187], v[74:77]
	v_mfma_f32_16x16x32_bf16 v[78:81], v[208:211], v[192:195], v[78:81]
	v_mfma_f32_16x16x32_bf16 v[82:85], v[216:219], v[192:195], v[82:85]
	v_mfma_f32_16x16x32_bf16 v[90:93], v[208:211], v[200:203], v[90:93]
	v_mfma_f32_16x16x32_bf16 v[94:97], v[216:219], v[200:203], v[94:97]
	s_barrier
; #define LDA(dst, b, h)                                                                                     \
;   _Pragma("unroll") for (int m = 0; m < 4; ++m) _Pragma("unroll") for (int k = 0; k < 2; ++k) dst[m][k] = \
;       *reinterpret_cast<const bf16x8*>(shmc + aL + (((b) * 2 + (h)) * 16384 + (m * 2 + k) * 1024))
; #define LDB(dst, b, h)                                                                                     \
;   _Pragma("unroll") for (int n = 0; n < 2; ++n) _Pragma("unroll") for (int k = 0; k < 2; ++k) dst[n][k] = \
;       *reinterpret_cast<const bf16x8*>(shmc + bL + (((b) * 2 + (h)) * 16384 + (n * 2 + k) * 1024))
; #define OPAQ asm volatile("" : "+v"(aL), "+v"(bL))
; #define WAIT_V(n) asm volatile("s_waitcnt vmcnt(" #n ")" ::: "memory")
; #define WAIT_L(n) asm volatile("s_waitcnt lgkmcnt(" #n ")" ::: "memory")
; #define BAR __builtin_amdgcn_s_barrier()
; template <int EPI>
; __device__ __forceinline__ void phase_gemm(const Params& p, const GemmDesc& d, char* shmc) {
;     ...
;     {
;       OPAQ;
;       LDB(B0, 0, 0); LDA(At, 0, 0); STAGE_A(SA(1, 1), 1, nt - 1);
;       BAR; WAIT_L(0); MMA(0, 0, At, B0); BAR;
;       LDB(B1, 0, 1); BAR; WAIT_L(0); MMA(0, 1, At, B1); BAR;
;       LDA(At, 0, 1); WAIT_V(4); BAR; WAIT_L(0); MMA(1, 0, At, B0); MMA(1, 1, At, B1); BAR;
	s_cbranch_scc0 .LBB0_1010
	s_setprio 0
	s_add_u32 s56, s56, 0x80f80
	s_addc_u32 s57, s57, 0
	v_add_u32_e32 v130, 0, v153
	v_add_u32_e32 v141, 0, v152
	s_mov_b32 m0, s80
	ds_read_b128 v[144:147], v130
	ds_read_b128 v[148:151], v130 offset:1024
	ds_read_b128 v[156:159], v130 offset:2048
	ds_read_b128 v[160:163], v130 offset:3072
	ds_read_b128 v[164:167], v141
	ds_read_b128 v[168:171], v141 offset:1024
	ds_read_b128 v[172:175], v141 offset:2048
	ds_read_b128 v[176:179], v141 offset:3072
	ds_read_b128 v[180:183], v141 offset:4096
	ds_read_b128 v[184:187], v141 offset:5120
	ds_read_b128 v[188:191], v141 offset:6144
	ds_read_b128 v[192:195], v141 offset:7168
	global_load_lds_dwordx4 v140, s[56:57]
	s_mov_b32 m0, s81
	s_nop 0
	global_load_lds_dwordx4 v142, s[56:57]
	s_waitcnt vmcnt(8)
	s_barrier
	s_waitcnt lgkmcnt(0)
	s_setprio 1
	s_waitcnt lgkmcnt(0)
	v_mfma_f32_16x16x32_bf16 v[126:129], v[144:147], v[164:167], v[126:129]
	v_mfma_f32_16x16x32_bf16 v[122:125], v[156:159], v[164:167], v[122:125]
	v_mfma_f32_16x16x32_bf16 v[114:117], v[156:159], v[172:175], v[114:117]
	v_mfma_f32_16x16x32_bf16 v[110:113], v[144:147], v[180:183], v[110:113]
	v_mfma_f32_16x16x32_bf16 v[102:105], v[144:147], v[188:191], v[102:105]
	v_mfma_f32_16x16x32_bf16 v[126:129], v[148:151], v[168:171], v[126:129]
	v_mfma_f32_16x16x32_bf16 v[122:125], v[160:163], v[168:171], v[122:125]
	v_mfma_f32_16x16x32_bf16 v[118:121], v[144:147], v[172:175], v[118:121]
	v_mfma_f32_16x16x32_bf16 v[114:117], v[160:163], v[176:179], v[114:117]
	v_mfma_f32_16x16x32_bf16 v[110:113], v[148:151], v[184:187], v[110:113]
	v_mfma_f32_16x16x32_bf16 v[106:109], v[156:159], v[180:183], v[106:109]
	v_mfma_f32_16x16x32_bf16 v[102:105], v[148:151], v[192:195], v[102:105]
	v_mfma_f32_16x16x32_bf16 v[98:101], v[156:159], v[188:191], v[98:101]
	v_mfma_f32_16x16x32_bf16 v[196:199], v[148:151], v[176:179], v[118:121]
	v_mfma_f32_16x16x32_bf16 v[200:203], v[160:163], v[184:187], v[106:109]
	v_mfma_f32_16x16x32_bf16 v[204:207], v[160:163], v[192:195], v[98:101]
	s_setprio 0
	s_barrier
	s_nop 2
	ds_read_b128 v[98:101], v130 offset:16384
	ds_read_b128 v[106:109], v130 offset:17408
	ds_read_b128 v[118:121], v130 offset:18432
	ds_read_b128 v[208:211], v130 offset:19456
	s_barrier
	s_waitcnt lgkmcnt(0)
	s_setprio 1
	s_waitcnt lgkmcnt(0)
	v_mfma_f32_16x16x32_bf16 v[86:89], v[98:101], v[164:167], v[86:89]
	v_mfma_f32_16x16x32_bf16 v[70:73], v[118:121], v[164:167], v[70:73]
	v_mfma_f32_16x16x32_bf16 v[54:57], v[98:101], v[172:175], v[54:57]
	v_mfma_f32_16x16x32_bf16 v[50:53], v[118:121], v[172:175], v[50:53]
	v_mfma_f32_16x16x32_bf16 v[46:49], v[98:101], v[180:183], v[46:49]
	v_mfma_f32_16x16x32_bf16 v[42:45], v[118:121], v[180:183], v[42:45]
	v_mfma_f32_16x16x32_bf16 v[38:41], v[98:101], v[188:191], v[38:41]
	v_mfma_f32_16x16x32_bf16 v[34:37], v[118:121], v[188:191], v[34:37]
	v_mfma_f32_16x16x32_bf16 v[86:89], v[106:109], v[168:171], v[86:89]
	v_mfma_f32_16x16x32_bf16 v[70:73], v[208:211], v[168:171], v[70:73]
	v_mfma_f32_16x16x32_bf16 v[54:57], v[106:109], v[176:179], v[54:57]
	v_mfma_f32_16x16x32_bf16 v[50:53], v[208:211], v[176:179], v[50:53]
	v_mfma_f32_16x16x32_bf16 v[46:49], v[106:109], v[184:187], v[46:49]
	v_mfma_f32_16x16x32_bf16 v[42:45], v[208:211], v[184:187], v[42:45]
	v_mfma_f32_16x16x32_bf16 v[38:41], v[106:109], v[192:195], v[38:41]
	v_mfma_f32_16x16x32_bf16 v[34:37], v[208:211], v[192:195], v[34:37]
	s_setprio 0
	s_barrier
	ds_read_b128 v[164:167], v141 offset:16384
	ds_read_b128 v[168:171], v141 offset:17408
	ds_read_b128 v[172:175], v141 offset:18432
	ds_read_b128 v[176:179], v141 offset:19456
	ds_read_b128 v[180:183], v141 offset:20480
	ds_read_b128 v[184:187], v141 offset:21504
	ds_read_b128 v[188:191], v141 offset:22528
	ds_read_b128 v[192:195], v141 offset:23552
	s_waitcnt vmcnt(4)
	s_barrier
	s_waitcnt lgkmcnt(0)
	s_setprio 1
	s_waitcnt lgkmcnt(0)
	v_mfma_f32_16x16x32_bf16 v[30:33], v[144:147], v[164:167], v[30:33]
	v_mfma_f32_16x16x32_bf16 v[26:29], v[156:159], v[164:167], v[26:29]
	v_mfma_f32_16x16x32_bf16 v[22:25], v[144:147], v[172:175], v[22:25]
	v_mfma_f32_16x16x32_bf16 v[18:21], v[156:159], v[172:175], v[18:21]
	v_mfma_f32_16x16x32_bf16 v[14:17], v[144:147], v[180:183], v[14:17]
	v_mfma_f32_16x16x32_bf16 v[10:13], v[156:159], v[180:183], v[10:13]
	v_mfma_f32_16x16x32_bf16 v[6:9], v[144:147], v[188:191], v[6:9]
	v_mfma_f32_16x16x32_bf16 v[2:5], v[156:159], v[188:191], v[2:5]
	v_mfma_f32_16x16x32_bf16 v[30:33], v[148:151], v[168:171], v[30:33]
	v_mfma_f32_16x16x32_bf16 v[26:29], v[160:163], v[168:171], v[26:29]
	v_mfma_f32_16x16x32_bf16 v[22:25], v[148:151], v[176:179], v[22:25]
	v_mfma_f32_16x16x32_bf16 v[18:21], v[160:163], v[176:179], v[18:21]
	v_mfma_f32_16x16x32_bf16 v[14:17], v[148:151], v[184:187], v[14:17]
	v_mfma_f32_16x16x32_bf16 v[10:13], v[160:163], v[184:187], v[10:13]
	v_mfma_f32_16x16x32_bf16 v[6:9], v[148:151], v[192:195], v[6:9]
	v_mfma_f32_16x16x32_bf16 v[2:5], v[160:163], v[192:195], v[2:5]
	s_setprio 0
	s_setprio 1
	v_mfma_f32_16x16x32_bf16 v[62:65], v[118:121], v[164:167], v[62:65]
	v_mfma_f32_16x16x32_bf16 v[144:147], v[208:211], v[168:171], v[62:65]
	v_mfma_f32_16x16x32_bf16 v[62:65], v[98:101], v[172:175], v[66:69]
	v_mfma_f32_16x16x32_bf16 v[148:151], v[106:109], v[176:179], v[62:65]
	v_mfma_f32_16x16x32_bf16 v[62:65], v[118:121], v[172:175], v[74:77]
	v_mfma_f32_16x16x32_bf16 v[156:159], v[208:211], v[176:179], v[62:65]
	v_mfma_f32_16x16x32_bf16 v[62:65], v[98:101], v[180:183], v[78:81]
	v_mfma_f32_16x16x32_bf16 v[160:163], v[106:109], v[184:187], v[62:65]
	v_mfma_f32_16x16x32_bf16 v[62:65], v[118:121], v[180:183], v[82:85]
	v_mfma_f32_16x16x32_bf16 v[58:61], v[98:101], v[164:167], v[58:61]
	v_mfma_f32_16x16x32_bf16 v[164:167], v[208:211], v[184:187], v[62:65]
	v_mfma_f32_16x16x32_bf16 v[62:65], v[98:101], v[188:191], v[90:93]
	v_mfma_f32_16x16x32_bf16 v[58:61], v[106:109], v[168:171], v[58:61]
	v_mfma_f32_16x16x32_bf16 v[168:171], v[106:109], v[192:195], v[62:65]
	v_mfma_f32_16x16x32_bf16 v[62:65], v[118:121], v[188:191], v[94:97]
	v_mfma_f32_16x16x32_bf16 v[172:175], v[208:211], v[192:195], v[62:65]
	s_setprio 0
	s_barrier
; #define LDA(dst, b, h)                                                                                     \
;   _Pragma("unroll") for (int m = 0; m < 4; ++m) _Pragma("unroll") for (int k = 0; k < 2; ++k) dst[m][k] = \
;       *reinterpret_cast<const bf16x8*>(shmc + aL + (((b) * 2 + (h)) * 16384 + (m * 2 + k) * 1024))
; #define LDB(dst, b, h)                                                                                     \
;   _Pragma("unroll") for (int n = 0; n < 2; ++n) _Pragma("unroll") for (int k = 0; k < 2; ++k) dst[n][k] = \
;       *reinterpret_cast<const bf16x8*>(shmc + bL + (((b) * 2 + (h)) * 16384 + (n * 2 + k) * 1024))
; #define WAIT_V(n) asm volatile("s_waitcnt vmcnt(" #n ")" ::: "memory")
; #define WAIT_L(n) asm volatile("s_waitcnt lgkmcnt(" #n ")" ::: "memory")
; #define BAR __builtin_amdgcn_s_barrier()
; template <int EPI>
; __device__ __forceinline__ void phase_gemm(const Params& p, const GemmDesc& d, char* shmc) {
;     ...
;     {
;       LDB(B0, 1, 0); LDA(At, 1, 0); WAIT_V(2); BAR; WAIT_L(0); MMA(0, 0, At, B0); BAR;
;       LDB(B1, 1, 1); WAIT_V(0); BAR; WAIT_L(0); MMA(0, 1, At, B1); BAR;
;       LDA(At, 1, 1); BAR; WAIT_L(0); MMA(1, 0, At, B0); MMA(1, 1, At, B1); BAR;
;     }
;     if (wr == 0) BAR;
	ds_read_b128 v[176:179], v130 offset:32768
	ds_read_b128 v[180:183], v130 offset:33792
	ds_read_b128 v[184:187], v130 offset:34816
	ds_read_b128 v[188:191], v130 offset:35840
	s_nop 0
	ds_read_b128 v[62:65], v141 offset:32768
	ds_read_b128 v[78:81], v141 offset:33792
	ds_read_b128 v[94:97], v141 offset:34816
	ds_read_b128 v[192:195], v141 offset:35840
	ds_read_b128 v[208:211], v141 offset:36864
	ds_read_b128 v[212:215], v141 offset:37888
	ds_read_b128 v[216:219], v141 offset:38912
	ds_read_b128 v[220:223], v141 offset:39936
	s_waitcnt vmcnt(2)
	s_barrier
	s_waitcnt lgkmcnt(0)
	s_setprio 1
	s_waitcnt lgkmcnt(0)
	v_mfma_f32_16x16x32_bf16 v[66:69], v[176:179], v[62:65], v[126:129]
	v_mfma_f32_16x16x32_bf16 v[126:129], v[180:183], v[78:81], v[66:69]
	v_mfma_f32_16x16x32_bf16 v[66:69], v[184:187], v[62:65], v[122:125]
	v_mfma_f32_16x16x32_bf16 v[118:121], v[188:191], v[78:81], v[66:69]
	v_mfma_f32_16x16x32_bf16 v[66:69], v[176:179], v[94:97], v[196:199]
	v_mfma_f32_16x16x32_bf16 v[106:109], v[180:183], v[192:195], v[66:69]
	v_mfma_f32_16x16x32_bf16 v[66:69], v[184:187], v[94:97], v[114:117]
	v_mfma_f32_16x16x32_bf16 v[98:101], v[188:191], v[192:195], v[66:69]
	v_mfma_f32_16x16x32_bf16 v[66:69], v[176:179], v[208:211], v[110:113]
	v_mfma_f32_16x16x32_bf16 v[90:93], v[180:183], v[212:215], v[66:69]
	v_mfma_f32_16x16x32_bf16 v[66:69], v[184:187], v[208:211], v[200:203]
	v_mfma_f32_16x16x32_bf16 v[82:85], v[188:191], v[212:215], v[66:69]
	v_mfma_f32_16x16x32_bf16 v[66:69], v[176:179], v[216:219], v[102:105]
	v_mfma_f32_16x16x32_bf16 v[74:77], v[180:183], v[220:223], v[66:69]
	v_mfma_f32_16x16x32_bf16 v[66:69], v[184:187], v[216:219], v[204:207]
	v_mfma_f32_16x16x32_bf16 v[66:69], v[188:191], v[220:223], v[66:69]
	s_setprio 0
	s_barrier
	ds_read_b128 v[196:199], v130 offset:49152
	ds_read_b128 v[200:203], v130 offset:50176
	ds_read_b128 v[204:207], v130 offset:51200
	ds_read_b128 v[224:227], v130 offset:52224
	s_waitcnt vmcnt(0)
	s_barrier
	s_waitcnt lgkmcnt(0)
	s_setprio 1
	s_waitcnt lgkmcnt(0)
	v_mfma_f32_16x16x32_bf16 v[86:89], v[196:199], v[62:65], v[86:89]
	v_mfma_f32_16x16x32_bf16 v[62:65], v[204:207], v[62:65], v[70:73]
	v_mfma_f32_16x16x32_bf16 v[54:57], v[196:199], v[94:97], v[54:57]
	v_mfma_f32_16x16x32_bf16 v[50:53], v[204:207], v[94:97], v[50:53]
	v_mfma_f32_16x16x32_bf16 v[46:49], v[196:199], v[208:211], v[46:49]
	v_mfma_f32_16x16x32_bf16 v[42:45], v[204:207], v[208:211], v[42:45]
	v_mfma_f32_16x16x32_bf16 v[38:41], v[196:199], v[216:219], v[38:41]
	v_mfma_f32_16x16x32_bf16 v[34:37], v[204:207], v[216:219], v[34:37]
	v_mfma_f32_16x16x32_bf16 v[122:125], v[200:203], v[78:81], v[86:89]
	v_mfma_f32_16x16x32_bf16 v[114:117], v[224:227], v[78:81], v[62:65]
	v_mfma_f32_16x16x32_bf16 v[110:113], v[200:203], v[192:195], v[54:57]
	v_mfma_f32_16x16x32_bf16 v[102:105], v[224:227], v[192:195], v[50:53]
	v_mfma_f32_16x16x32_bf16 v[94:97], v[200:203], v[212:215], v[46:49]
	v_mfma_f32_16x16x32_bf16 v[86:89], v[224:227], v[212:215], v[42:45]
	v_mfma_f32_16x16x32_bf16 v[78:81], v[200:203], v[220:223], v[38:41]
	v_mfma_f32_16x16x32_bf16 v[70:73], v[224:227], v[220:223], v[34:37]
	s_setprio 0
	s_barrier
	s_nop 0
	ds_read_b128 v[34:37], v141 offset:49152
	ds_read_b128 v[42:45], v141 offset:50176
	ds_read_b128 v[192:195], v141 offset:51200
	ds_read_b128 v[208:211], v141 offset:52224
	ds_read_b128 v[212:215], v141 offset:53248
	ds_read_b128 v[216:219], v141 offset:54272
	ds_read_b128 v[220:223], v141 offset:55296
	ds_read_b128 v[228:231], v141 offset:56320
	s_barrier
	s_waitcnt lgkmcnt(0)
	s_setprio 1
	s_waitcnt lgkmcnt(0)
	v_mfma_f32_16x16x32_bf16 v[30:33], v[176:179], v[34:37], v[30:33]
	v_mfma_f32_16x16x32_bf16 v[26:29], v[184:187], v[34:37], v[26:29]
	v_mfma_f32_16x16x32_bf16 v[22:25], v[176:179], v[192:195], v[22:25]
	v_mfma_f32_16x16x32_bf16 v[18:21], v[184:187], v[192:195], v[18:21]
	v_mfma_f32_16x16x32_bf16 v[14:17], v[176:179], v[212:215], v[14:17]
	v_mfma_f32_16x16x32_bf16 v[10:13], v[184:187], v[212:215], v[10:13]
	v_mfma_f32_16x16x32_bf16 v[6:9], v[176:179], v[220:223], v[6:9]
	v_mfma_f32_16x16x32_bf16 v[2:5], v[184:187], v[220:223], v[2:5]
	v_mfma_f32_16x16x32_bf16 v[62:65], v[180:183], v[42:45], v[30:33]
	v_mfma_f32_16x16x32_bf16 v[54:57], v[188:191], v[42:45], v[26:29]
	v_mfma_f32_16x16x32_bf16 v[46:49], v[180:183], v[208:211], v[22:25]
	v_mfma_f32_16x16x32_bf16 v[38:41], v[188:191], v[208:211], v[18:21]
	v_mfma_f32_16x16x32_bf16 v[30:33], v[180:183], v[216:219], v[14:17]
	v_mfma_f32_16x16x32_bf16 v[22:25], v[188:191], v[216:219], v[10:13]
	v_mfma_f32_16x16x32_bf16 v[14:17], v[180:183], v[228:231], v[6:9]
	v_mfma_f32_16x16x32_bf16 v[6:9], v[188:191], v[228:231], v[2:5]
	s_setprio 0
	s_setprio 1
	v_mfma_f32_16x16x32_bf16 v[2:5], v[196:199], v[34:37], v[58:61]
	v_mfma_f32_16x16x32_bf16 v[58:61], v[200:203], v[42:45], v[2:5]
	v_mfma_f32_16x16x32_bf16 v[2:5], v[204:207], v[34:37], v[144:147]
	v_mfma_f32_16x16x32_bf16 v[50:53], v[224:227], v[42:45], v[2:5]
	v_mfma_f32_16x16x32_bf16 v[2:5], v[196:199], v[192:195], v[148:151]
	v_mfma_f32_16x16x32_bf16 v[42:45], v[200:203], v[208:211], v[2:5]
	v_mfma_f32_16x16x32_bf16 v[2:5], v[204:207], v[192:195], v[156:159]
	v_mfma_f32_16x16x32_bf16 v[34:37], v[224:227], v[208:211], v[2:5]
	v_mfma_f32_16x16x32_bf16 v[2:5], v[196:199], v[212:215], v[160:163]
	v_mfma_f32_16x16x32_bf16 v[26:29], v[200:203], v[216:219], v[2:5]
	v_mfma_f32_16x16x32_bf16 v[2:5], v[204:207], v[212:215], v[164:167]
	v_mfma_f32_16x16x32_bf16 v[18:21], v[224:227], v[216:219], v[2:5]
	v_mfma_f32_16x16x32_bf16 v[2:5], v[196:199], v[220:223], v[168:171]
	v_mfma_f32_16x16x32_bf16 v[10:13], v[200:203], v[228:231], v[2:5]
	v_mfma_f32_16x16x32_bf16 v[2:5], v[204:207], v[220:223], v[172:175]
	v_mfma_f32_16x16x32_bf16 v[2:5], v[224:227], v[228:231], v[2:5]
	s_setprio 0
	s_barrier
	s_and_saveexec_b64 s[56:57], s[4:5]
	s_cbranch_execz .LBB0_1013
	s_barrier

; #define WAIT_V(n) asm volatile("s_waitcnt vmcnt(" #n ")" ::: "memory")
; #define BAR __builtin_amdgcn_s_barrier()
; template <int EPI>
; __device__ __forceinline__ void phase_gemm(const Params& p, const GemmDesc& d, char* shmc) {
;     ...
;     f32x4 acc[2][2][4][2];
; #pragma unroll
;     for (int a = 0; a < 2; ++a)
; #pragma unroll
;       for (int b = 0; b < 2; ++b)
; #pragma unroll
;         for (int m = 0; m < 4; ++m)
; #pragma unroll
;           for (int n = 0; n < 2; ++n) acc[a][b][m][n] = f32x4{0.f, 0.f, 0.f, 0.f};
;     bf16x8 At[4][2], B0[2][2], B1[2][2];
;     if constexpr (EPI == EPI_UP || EPI == EPI_QKV) {
;       if (wid == 0)
;         __builtin_amdgcn_global_load_lds((const unsigned*)(p.rstd + brow + lane * 4), (unsigned*)(shmc + 143360), 16, 0, 0);
;     }
;     STAGE_B(SB(0, 0), 0, 0); STAGE_A(SA(0, 0), 0, 0);
;     STAGE_B(SB(0, 1), 1, 0); STAGE_A(SA(0, 1), 1, 0);
;     if (wr == 1) BAR;
;     WAIT_V(4); BAR;
;     STAGE_B(SB(1, 0), 0, 1); STAGE_A(SA(1, 0), 0, 1); STAGE_B(SB(1, 1), 1, 1);
;     WAIT_V(6); BAR;
;     for (int t = 0; t < nt - 2; t += 2) {
.LBB0_1152:
	s_or_b64 exec, exec, s[56:57]
	v_mov_b32_e32 v175, v163
	v_lshl_add_u64 v[2:3], s[54:55], 0, v[174:175]
	v_mov_b32_e32 v177, v163
	s_add_i32 s35, s64, 0x18000
	v_lshl_add_u64 v[4:5], s[54:55], 0, v[176:177]
	v_lshl_add_u64 v[2:3], v[2:3], 0, s[18:19]
	s_mov_b32 m0, s35
	s_add_i32 s53, s64, 0x1a000
	v_lshl_add_u64 v[6:7], s[8:9], 0, v[174:175]
	v_mov_b32_e32 v10, 0
	v_mov_b32_e32 v11, 0
	v_mov_b32_e32 v12, 0
	v_mov_b32_e32 v13, 0
	v_mov_b32_e32 v18, 0
	v_mov_b32_e32 v19, 0
	v_mov_b32_e32 v20, 0
	v_mov_b32_e32 v21, 0
	v_mov_b32_e32 v30, 0
	v_mov_b32_e32 v31, 0
	v_mov_b32_e32 v32, 0
	v_mov_b32_e32 v33, 0
	v_mov_b32_e32 v42, 0
	v_mov_b32_e32 v43, 0
	v_mov_b32_e32 v44, 0
	v_mov_b32_e32 v45, 0
	v_mov_b32_e32 v54, 0
	v_mov_b32_e32 v55, 0
	v_mov_b32_e32 v56, 0
	v_mov_b32_e32 v57, 0
	v_mov_b32_e32 v66, 0
	v_mov_b32_e32 v67, 0
	v_mov_b32_e32 v68, 0
	v_mov_b32_e32 v69, 0
	v_mov_b32_e32 v14, 0
	v_mov_b32_e32 v15, 0
	v_mov_b32_e32 v16, 0
	v_mov_b32_e32 v17, 0
	v_mov_b32_e32 v22, 0
	v_mov_b32_e32 v23, 0
	v_mov_b32_e32 v24, 0
	v_mov_b32_e32 v25, 0
	v_mov_b32_e32 v34, 0
	v_mov_b32_e32 v35, 0
	v_mov_b32_e32 v36, 0
	v_mov_b32_e32 v37, 0
	v_mov_b32_e32 v46, 0
	v_mov_b32_e32 v47, 0
	v_mov_b32_e32 v48, 0
	v_mov_b32_e32 v49, 0
	v_mov_b32_e32 v58, 0
	v_mov_b32_e32 v59, 0
	v_mov_b32_e32 v60, 0
	v_mov_b32_e32 v61, 0
	v_mov_b32_e32 v70, 0
	v_mov_b32_e32 v71, 0
	v_mov_b32_e32 v72, 0
	v_mov_b32_e32 v73, 0
	v_mov_b32_e32 v78, 0
	v_mov_b32_e32 v79, 0
	v_mov_b32_e32 v80, 0
	v_mov_b32_e32 v81, 0
	v_mov_b32_e32 v86, 0
	v_mov_b32_e32 v87, 0
	v_mov_b32_e32 v88, 0
	v_mov_b32_e32 v89, 0
	v_mov_b32_e32 v26, 0
	v_mov_b32_e32 v27, 0
	v_mov_b32_e32 v28, 0
	v_mov_b32_e32 v29, 0
	v_mov_b32_e32 v38, 0
	v_mov_b32_e32 v39, 0
	v_mov_b32_e32 v40, 0
	v_mov_b32_e32 v41, 0
	v_mov_b32_e32 v50, 0
	v_mov_b32_e32 v51, 0
	v_mov_b32_e32 v52, 0
	v_mov_b32_e32 v53, 0
	v_mov_b32_e32 v62, 0
	v_mov_b32_e32 v63, 0
	v_mov_b32_e32 v64, 0
	v_mov_b32_e32 v65, 0
	v_mov_b32_e32 v74, 0
	v_mov_b32_e32 v75, 0
	v_mov_b32_e32 v76, 0
	v_mov_b32_e32 v77, 0
	v_mov_b32_e32 v82, 0
	v_mov_b32_e32 v83, 0
	v_mov_b32_e32 v84, 0
	v_mov_b32_e32 v85, 0
	v_mov_b32_e32 v90, 0
	v_mov_b32_e32 v91, 0
	v_mov_b32_e32 v92, 0
	v_mov_b32_e32 v93, 0
	v_mov_b32_e32 v94, 0
	v_mov_b32_e32 v95, 0
	v_mov_b32_e32 v96, 0
	v_mov_b32_e32 v97, 0
	v_mov_b32_e32 v98, 0
	v_mov_b32_e32 v99, 0
	v_mov_b32_e32 v100, 0
	v_mov_b32_e32 v101, 0
	v_mov_b32_e32 v102, 0
	v_mov_b32_e32 v103, 0
	v_mov_b32_e32 v104, 0
	v_mov_b32_e32 v105, 0
	v_mov_b32_e32 v106, 0
	v_mov_b32_e32 v107, 0
	v_mov_b32_e32 v108, 0
	v_mov_b32_e32 v109, 0
	v_mov_b32_e32 v110, 0
	v_mov_b32_e32 v111, 0
	v_mov_b32_e32 v112, 0
	v_mov_b32_e32 v113, 0
	v_mov_b32_e32 v114, 0
	v_mov_b32_e32 v115, 0
	v_mov_b32_e32 v116, 0
	v_mov_b32_e32 v117, 0
	v_mov_b32_e32 v118, 0
	v_mov_b32_e32 v119, 0
	v_mov_b32_e32 v120, 0
	v_mov_b32_e32 v121, 0
	v_mov_b32_e32 v122, 0
	v_mov_b32_e32 v123, 0
	v_mov_b32_e32 v124, 0
	v_mov_b32_e32 v125, 0
	v_mov_b32_e32 v126, 0
	v_mov_b32_e32 v127, 0
	v_mov_b32_e32 v128, 0
	v_mov_b32_e32 v129, 0
	s_waitcnt vmcnt(2)
	s_barrier
	global_load_lds_dwordx4 v[2:3], off
	v_lshl_add_u64 v[2:3], v[4:5], 0, s[18:19]
	s_mov_b32 m0, s53
	s_add_i32 s56, s64, 0x8000
	s_add_i32 s57, s64, 0xa000
	v_lshl_add_u64 v[8:9], s[8:9], 0, v[176:177]
	global_load_lds_dwordx4 v[2:3], off
	v_lshl_add_u64 v[2:3], v[6:7], 0, s[18:19]
	s_mov_b32 m0, s56
	s_add_u32 s68, s54, 0x80080
	global_load_lds_dwordx4 v[2:3], off
	v_lshl_add_u64 v[2:3], v[8:9], 0, s[18:19]
	s_mov_b32 m0, s57
	s_addc_u32 s69, s55, 0
	s_add_i32 s54, s64, 0x1c000
	global_load_lds_dwordx4 v[2:3], off
	s_mov_b32 m0, s54
	s_add_i32 s55, s64, 0x1e000
	global_load_lds_dwordx4 v174, s[68:69]
	s_mov_b32 m0, s55
	v_lshl_add_u64 v[130:131], v[166:167], 0, s[10:11]
	global_load_lds_dwordx4 v176, s[68:69]
	v_lshl_add_u64 v[132:133], v[168:169], 0, s[10:11]
	s_lshl_b32 s10, s58, 11
	s_lshl_b32 s11, s59, 8
	s_or_b32 s10, s10, s11
	s_waitcnt vmcnt(6)
	s_ashr_i32 s11, s10, 31
	s_lshl_b64 s[10:11], s[10:11], 12
	v_mov_b32_e32 v2, 0
	v_lshl_add_u64 v[134:135], v[170:171], 0, s[10:11]
	v_lshl_add_u64 v[136:137], v[172:173], 0, s[10:11]
	s_mov_b32 s58, -2
	s_mov_b64 s[10:11], 0
	v_mov_b32_e32 v3, v2
	v_mov_b32_e32 v4, v2
	v_mov_b32_e32 v5, v2
	v_mov_b32_e32 v6, v2
	v_mov_b32_e32 v7, v2
	v_mov_b32_e32 v8, v2
	v_mov_b32_e32 v9, v2
	s_barrier
	v_readfirstlane_b32 s98, v134
	v_readfirstlane_b32 s99, v135
	v_readfirstlane_b32 s100, v130
	v_readfirstlane_b32 s101, v131
	s_nop 3
	v_subrev_u32_e32 v202, s98, v134
	v_add_u32_e32 v202, s26, v202
	v_subrev_u32_e32 v203, s98, v136
	v_add_u32_e32 v203, s26, v203
	v_subrev_u32_e32 v224, s100, v130
	v_add_u32_e32 v224, s30, v224
	v_subrev_u32_e32 v225, s100, v132
	v_add_u32_e32 v225, s30, v225
	v_subrev_u32_e32 v226, s98, v134
	v_add_u32_e32 v226, s36, v226
	v_subrev_u32_e32 v227, s98, v136
	v_add_u32_e32 v227, s36, v227
	v_subrev_u32_e32 v228, s100, v130
	v_add_u32_e32 v228, s38, v228
	v_subrev_u32_e32 v229, s100, v132
	v_add_u32_e32 v229, s38, v229
	v_subrev_u32_e32 v230, s98, v134
	v_add_u32_e32 v230, s40, v230
	v_subrev_u32_e32 v231, s98, v136
	v_add_u32_e32 v231, s40, v231
	v_subrev_u32_e32 v232, s100, v130
	v_add_u32_e32 v232, s42, v232
	v_subrev_u32_e32 v233, s100, v132
	v_add_u32_e32 v233, s42, v233
	v_subrev_u32_e32 v234, s98, v134
	v_add_u32_e32 v234, s46, v234
	v_subrev_u32_e32 v235, s98, v136
	v_add_u32_e32 v235, s46, v235
	v_subrev_u32_e32 v236, s100, v130
	v_add_u32_e32 v236, s48, v236
	v_subrev_u32_e32 v237, s100, v132
	v_add_u32_e32 v237, s48, v237
	s_add_u32 s98, s98, s10
	s_addc_u32 s99, s99, s11
	s_add_u32 s100, s100, s10
	s_addc_u32 s101, s101, s11
; #define LDA(dst, b, h)                                                                                     \
;   _Pragma("unroll") for (int m = 0; m < 4; ++m) _Pragma("unroll") for (int k = 0; k < 2; ++k) dst[m][k] = \
;       *reinterpret_cast<const bf16x8*>(shmc + aL + (((b) * 2 + (h)) * 16384 + (m * 2 + k) * 1024))
; #define LDB(dst, b, h)                                                                                     \
;   _Pragma("unroll") for (int n = 0; n < 2; ++n) _Pragma("unroll") for (int k = 0; k < 2; ++k) dst[n][k] = \
;       *reinterpret_cast<const bf16x8*>(shmc + bL + (((b) * 2 + (h)) * 16384 + (n * 2 + k) * 1024))
; #define OPAQ asm volatile("" : "+v"(aL), "+v"(bL))
; #define WAIT_V(n) asm volatile("s_waitcnt vmcnt(" #n ")" ::: "memory")
; #define WAIT_L(n) asm volatile("s_waitcnt lgkmcnt(" #n ")" ::: "memory")
; #define BAR __builtin_amdgcn_s_barrier()
; #define SCHED __builtin_amdgcn_sched_barrier(0)
; template <int EPI>
; __device__ __forceinline__ void phase_gemm(const Params& p, const GemmDesc& d, char* shmc) {
;     ...
;     for (int t = 0; t < nt - 2; t += 2) {
;       OPAQ;
;       LDB(B0, 0, 0); SCHED; LDA(At, 0, 0); STAGE_A(SA(1, 1), 1, t + 1);
;       WAIT_L(8); BAR; WAIT_L(0); MMA(0, 0, At, B0); BAR; SCHED;
;       LDB(B1, 0, 1); STAGE_B(SB(0, 0), 0, t + 2);
;       BAR; WAIT_L(0); MMA(0, 1, At, B1); BAR;
;       LDA(At, 0, 1); STAGE_A(SA(0, 0), 0, t + 2);
;       BAR; WAIT_L(0); MMA(1, 0, At, B0); BAR; SCHED;
;       STAGE_B(SB(0, 1), 1, t + 2);
;       WAIT_V(6); BAR; MMA(1, 1, At, B1); BAR;
.LBB0_1153:
	s_nop 0
	v_add_u32_e32 v162, 0, v205
	v_add_u32_e32 v175, 0, v204
	s_setprio 0
	ds_read_b128 v[138:141], v162
	ds_read_b128 v[142:145], v162 offset:1024
	ds_read_b128 v[146:149], v162 offset:2048
	ds_read_b128 v[150:153], v162 offset:3072
	ds_read_b128 v[208:211], v162 offset:16384
	ds_read_b128 v[212:215], v162 offset:17408
	ds_read_b128 v[216:219], v162 offset:18432
	ds_read_b128 v[220:223], v162 offset:19456
	ds_read_b128 v[154:157], v175
	ds_read_b128 v[158:161], v175 offset:1024
	ds_read_b128 v[178:181], v175 offset:2048
	ds_read_b128 v[182:185], v175 offset:3072
	ds_read_b128 v[186:189], v175 offset:4096
	ds_read_b128 v[190:193], v175 offset:5120
	ds_read_b128 v[194:197], v175 offset:6144
	ds_read_b128 v[198:201], v175 offset:7168
	s_add_i32 s59, s64, 0xc000
	s_mov_b32 m0, s59
	s_nop 0
	global_load_lds_dwordx4 v202, s[98:99]
	s_add_i32 s68, s64, 0xe000
	s_mov_b32 m0, s68
	s_nop 0
	global_load_lds_dwordx4 v203, s[98:99]
	s_waitcnt vmcnt(8)
	s_waitcnt lgkmcnt(0)
	s_setprio 1
	s_barrier
	v_mfma_f32_16x16x32_bf16 v[2:5], v[154:157], v[138:141], v[2:5]
	v_mfma_f32_16x16x32_bf16 v[6:9], v[154:157], v[146:149], v[6:9]
	v_mfma_f32_16x16x32_bf16 v[10:13], v[178:181], v[138:141], v[10:13]
	v_mfma_f32_16x16x32_bf16 v[18:21], v[178:181], v[146:149], v[18:21]
	v_mfma_f32_16x16x32_bf16 v[30:33], v[186:189], v[138:141], v[30:33]
	v_mfma_f32_16x16x32_bf16 v[42:45], v[186:189], v[146:149], v[42:45]
	v_mfma_f32_16x16x32_bf16 v[54:57], v[194:197], v[138:141], v[54:57]
	v_mfma_f32_16x16x32_bf16 v[66:69], v[194:197], v[146:149], v[66:69]
	v_mfma_f32_16x16x32_bf16 v[2:5], v[158:161], v[142:145], v[2:5]
	v_mfma_f32_16x16x32_bf16 v[6:9], v[158:161], v[150:153], v[6:9]
	v_mfma_f32_16x16x32_bf16 v[10:13], v[182:185], v[142:145], v[10:13]
	v_mfma_f32_16x16x32_bf16 v[18:21], v[182:185], v[150:153], v[18:21]
	v_mfma_f32_16x16x32_bf16 v[30:33], v[190:193], v[142:145], v[30:33]
	v_mfma_f32_16x16x32_bf16 v[42:45], v[190:193], v[150:153], v[42:45]
	v_mfma_f32_16x16x32_bf16 v[54:57], v[198:201], v[142:145], v[54:57]
	v_mfma_f32_16x16x32_bf16 v[66:69], v[198:201], v[150:153], v[66:69]
	v_mfma_f32_16x16x32_bf16 v[14:17], v[154:157], v[208:211], v[14:17]
	v_mfma_f32_16x16x32_bf16 v[22:25], v[154:157], v[216:219], v[22:25]
	v_mfma_f32_16x16x32_bf16 v[34:37], v[178:181], v[208:211], v[34:37]
	v_mfma_f32_16x16x32_bf16 v[46:49], v[178:181], v[216:219], v[46:49]
	v_mfma_f32_16x16x32_bf16 v[58:61], v[186:189], v[208:211], v[58:61]
	v_mfma_f32_16x16x32_bf16 v[70:73], v[186:189], v[216:219], v[70:73]
	v_mfma_f32_16x16x32_bf16 v[78:81], v[194:197], v[208:211], v[78:81]
	v_mfma_f32_16x16x32_bf16 v[86:89], v[194:197], v[216:219], v[86:89]
	v_mfma_f32_16x16x32_bf16 v[14:17], v[158:161], v[212:215], v[14:17]
	v_mfma_f32_16x16x32_bf16 v[22:25], v[158:161], v[220:223], v[22:25]
	v_mfma_f32_16x16x32_bf16 v[34:37], v[182:185], v[212:215], v[34:37]
	v_mfma_f32_16x16x32_bf16 v[46:49], v[182:185], v[220:223], v[46:49]
	v_mfma_f32_16x16x32_bf16 v[58:61], v[190:193], v[212:215], v[58:61]
	v_mfma_f32_16x16x32_bf16 v[70:73], v[190:193], v[220:223], v[70:73]
	v_mfma_f32_16x16x32_bf16 v[78:81], v[198:201], v[212:215], v[78:81]
	v_mfma_f32_16x16x32_bf16 v[86:89], v[198:201], v[220:223], v[86:89]
	s_barrier
	s_setprio 0
	ds_read_b128 v[154:157], v175 offset:16384
	ds_read_b128 v[158:161], v175 offset:17408
	ds_read_b128 v[178:181], v175 offset:18432
	ds_read_b128 v[182:185], v175 offset:19456
	ds_read_b128 v[186:189], v175 offset:20480
	ds_read_b128 v[190:193], v175 offset:21504
	ds_read_b128 v[194:197], v175 offset:22528
	ds_read_b128 v[198:201], v175 offset:23552
	s_mov_b32 m0, s65
	s_nop 0
	global_load_lds_dwordx4 v224, s[100:101]
	s_mov_b32 m0, s66
	s_nop 0
	global_load_lds_dwordx4 v225, s[100:101]
	s_mov_b32 m0, s64
	s_nop 0
	global_load_lds_dwordx4 v226, s[98:99]
	s_mov_b32 m0, s67
	s_nop 0
	global_load_lds_dwordx4 v227, s[98:99]
	s_mov_b32 m0, s71
	s_nop 0
	global_load_lds_dwordx4 v228, s[100:101]
	s_mov_b32 m0, s76
	s_nop 0
	global_load_lds_dwordx4 v229, s[100:101]
	s_waitcnt vmcnt(8)
	s_waitcnt lgkmcnt(0)
	s_setprio 1
	s_barrier
	v_mfma_f32_16x16x32_bf16 v[26:29], v[154:157], v[138:141], v[26:29]
	v_mfma_f32_16x16x32_bf16 v[38:41], v[154:157], v[146:149], v[38:41]
	v_mfma_f32_16x16x32_bf16 v[50:53], v[178:181], v[138:141], v[50:53]
	v_mfma_f32_16x16x32_bf16 v[62:65], v[178:181], v[146:149], v[62:65]
	v_mfma_f32_16x16x32_bf16 v[74:77], v[186:189], v[138:141], v[74:77]
	v_mfma_f32_16x16x32_bf16 v[82:85], v[186:189], v[146:149], v[82:85]
	v_mfma_f32_16x16x32_bf16 v[90:93], v[194:197], v[138:141], v[90:93]
	v_mfma_f32_16x16x32_bf16 v[94:97], v[194:197], v[146:149], v[94:97]
	v_mfma_f32_16x16x32_bf16 v[26:29], v[158:161], v[142:145], v[26:29]
	v_mfma_f32_16x16x32_bf16 v[38:41], v[158:161], v[150:153], v[38:41]
	v_mfma_f32_16x16x32_bf16 v[50:53], v[182:185], v[142:145], v[50:53]
	v_mfma_f32_16x16x32_bf16 v[62:65], v[182:185], v[150:153], v[62:65]
	v_mfma_f32_16x16x32_bf16 v[74:77], v[190:193], v[142:145], v[74:77]
	v_mfma_f32_16x16x32_bf16 v[82:85], v[190:193], v[150:153], v[82:85]
	v_mfma_f32_16x16x32_bf16 v[90:93], v[198:201], v[142:145], v[90:93]
	v_mfma_f32_16x16x32_bf16 v[94:97], v[198:201], v[150:153], v[94:97]
	v_mfma_f32_16x16x32_bf16 v[98:101], v[154:157], v[208:211], v[98:101]
	v_mfma_f32_16x16x32_bf16 v[102:105], v[154:157], v[216:219], v[102:105]
	v_mfma_f32_16x16x32_bf16 v[106:109], v[178:181], v[208:211], v[106:109]
	v_mfma_f32_16x16x32_bf16 v[110:113], v[178:181], v[216:219], v[110:113]
	v_mfma_f32_16x16x32_bf16 v[114:117], v[186:189], v[208:211], v[114:117]
	v_mfma_f32_16x16x32_bf16 v[118:121], v[186:189], v[216:219], v[118:121]
	v_mfma_f32_16x16x32_bf16 v[122:125], v[194:197], v[208:211], v[122:125]
	v_mfma_f32_16x16x32_bf16 v[126:129], v[194:197], v[216:219], v[126:129]
	v_mfma_f32_16x16x32_bf16 v[98:101], v[158:161], v[212:215], v[98:101]
	v_mfma_f32_16x16x32_bf16 v[102:105], v[158:161], v[220:223], v[102:105]
	v_mfma_f32_16x16x32_bf16 v[106:109], v[182:185], v[212:215], v[106:109]
	v_mfma_f32_16x16x32_bf16 v[110:113], v[182:185], v[220:223], v[110:113]
	v_mfma_f32_16x16x32_bf16 v[114:117], v[190:193], v[212:215], v[114:117]
	v_mfma_f32_16x16x32_bf16 v[118:121], v[190:193], v[220:223], v[118:121]
	v_mfma_f32_16x16x32_bf16 v[122:125], v[198:201], v[212:215], v[122:125]
	v_mfma_f32_16x16x32_bf16 v[126:129], v[198:201], v[220:223], v[126:129]
	s_barrier
; #define LDA(dst, b, h)                                                                                     \
;   _Pragma("unroll") for (int m = 0; m < 4; ++m) _Pragma("unroll") for (int k = 0; k < 2; ++k) dst[m][k] = \
;       *reinterpret_cast<const bf16x8*>(shmc + aL + (((b) * 2 + (h)) * 16384 + (m * 2 + k) * 1024))
; #define LDB(dst, b, h)                                                                                     \
;   _Pragma("unroll") for (int n = 0; n < 2; ++n) _Pragma("unroll") for (int k = 0; k < 2; ++k) dst[n][k] = \
;       *reinterpret_cast<const bf16x8*>(shmc + bL + (((b) * 2 + (h)) * 16384 + (n * 2 + k) * 1024))
; #define WAIT_V(n) asm volatile("s_waitcnt vmcnt(" #n ")" ::: "memory")
; #define WAIT_L(n) asm volatile("s_waitcnt lgkmcnt(" #n ")" ::: "memory")
; #define BAR __builtin_amdgcn_s_barrier()
; #define SCHED __builtin_amdgcn_sched_barrier(0)
; template <int EPI>
; __device__ __forceinline__ void phase_gemm(const Params& p, const GemmDesc& d, char* shmc) {
;     ...
;       LDB(B0, 1, 0); SCHED; LDA(At, 1, 0); STAGE_A(SA(0, 1), 1, t + 2);
;       WAIT_L(8); BAR; WAIT_L(0); MMA(0, 0, At, B0); BAR; SCHED;
;       LDB(B1, 1, 1); STAGE_B(SB(1, 0), 0, t + 3);
;       BAR; WAIT_L(0); MMA(0, 1, At, B1); BAR;
;       LDA(At, 1, 1); STAGE_A(SA(1, 0), 0, t + 3);
;       BAR; WAIT_L(0); MMA(1, 0, At, B0); BAR; SCHED;
;       STAGE_B(SB(1, 1), 1, t + 3);
;       WAIT_V(6); BAR; MMA(1, 1, At, B1); BAR;
;     }
	s_setprio 0
	ds_read_b128 v[138:141], v162 offset:32768
	ds_read_b128 v[142:145], v162 offset:33792
	ds_read_b128 v[146:149], v162 offset:34816
	ds_read_b128 v[150:153], v162 offset:35840
	ds_read_b128 v[208:211], v162 offset:49152
	ds_read_b128 v[212:215], v162 offset:50176
	ds_read_b128 v[216:219], v162 offset:51200
	ds_read_b128 v[220:223], v162 offset:52224
	ds_read_b128 v[154:157], v175 offset:32768
	ds_read_b128 v[158:161], v175 offset:33792
	ds_read_b128 v[178:181], v175 offset:34816
	ds_read_b128 v[182:185], v175 offset:35840
	ds_read_b128 v[186:189], v175 offset:36864
	ds_read_b128 v[190:193], v175 offset:37888
	ds_read_b128 v[194:197], v175 offset:38912
	ds_read_b128 v[198:201], v175 offset:39936
	s_mov_b32 m0, s77
	s_nop 0
	global_load_lds_dwordx4 v230, s[98:99]
	s_mov_b32 m0, s78
	s_nop 0
	global_load_lds_dwordx4 v231, s[98:99]
	s_waitcnt vmcnt(8)
	s_waitcnt lgkmcnt(0)
	s_setprio 1
	s_barrier
	v_mfma_f32_16x16x32_bf16 v[2:5], v[154:157], v[138:141], v[2:5]
	v_mfma_f32_16x16x32_bf16 v[6:9], v[154:157], v[146:149], v[6:9]
	v_mfma_f32_16x16x32_bf16 v[10:13], v[178:181], v[138:141], v[10:13]
	v_mfma_f32_16x16x32_bf16 v[18:21], v[178:181], v[146:149], v[18:21]
	v_mfma_f32_16x16x32_bf16 v[30:33], v[186:189], v[138:141], v[30:33]
	v_mfma_f32_16x16x32_bf16 v[42:45], v[186:189], v[146:149], v[42:45]
	v_mfma_f32_16x16x32_bf16 v[54:57], v[194:197], v[138:141], v[54:57]
	v_mfma_f32_16x16x32_bf16 v[66:69], v[194:197], v[146:149], v[66:69]
	v_mfma_f32_16x16x32_bf16 v[2:5], v[158:161], v[142:145], v[2:5]
	v_mfma_f32_16x16x32_bf16 v[6:9], v[158:161], v[150:153], v[6:9]
	v_mfma_f32_16x16x32_bf16 v[10:13], v[182:185], v[142:145], v[10:13]
	v_mfma_f32_16x16x32_bf16 v[18:21], v[182:185], v[150:153], v[18:21]
	v_mfma_f32_16x16x32_bf16 v[30:33], v[190:193], v[142:145], v[30:33]
	v_mfma_f32_16x16x32_bf16 v[42:45], v[190:193], v[150:153], v[42:45]
	v_mfma_f32_16x16x32_bf16 v[54:57], v[198:201], v[142:145], v[54:57]
	v_mfma_f32_16x16x32_bf16 v[66:69], v[198:201], v[150:153], v[66:69]
	v_mfma_f32_16x16x32_bf16 v[14:17], v[154:157], v[208:211], v[14:17]
	v_mfma_f32_16x16x32_bf16 v[22:25], v[154:157], v[216:219], v[22:25]
	v_mfma_f32_16x16x32_bf16 v[34:37], v[178:181], v[208:211], v[34:37]
	v_mfma_f32_16x16x32_bf16 v[46:49], v[178:181], v[216:219], v[46:49]
	v_mfma_f32_16x16x32_bf16 v[58:61], v[186:189], v[208:211], v[58:61]
	v_mfma_f32_16x16x32_bf16 v[70:73], v[186:189], v[216:219], v[70:73]
	v_mfma_f32_16x16x32_bf16 v[78:81], v[194:197], v[208:211], v[78:81]
	v_mfma_f32_16x16x32_bf16 v[86:89], v[194:197], v[216:219], v[86:89]
	v_mfma_f32_16x16x32_bf16 v[14:17], v[158:161], v[212:215], v[14:17]
	v_mfma_f32_16x16x32_bf16 v[22:25], v[158:161], v[220:223], v[22:25]
	v_mfma_f32_16x16x32_bf16 v[34:37], v[182:185], v[212:215], v[34:37]
	v_mfma_f32_16x16x32_bf16 v[46:49], v[182:185], v[220:223], v[46:49]
	v_mfma_f32_16x16x32_bf16 v[58:61], v[190:193], v[212:215], v[58:61]
	v_mfma_f32_16x16x32_bf16 v[70:73], v[190:193], v[220:223], v[70:73]
	v_mfma_f32_16x16x32_bf16 v[78:81], v[198:201], v[212:215], v[78:81]
	v_mfma_f32_16x16x32_bf16 v[86:89], v[198:201], v[220:223], v[86:89]
	s_barrier
	s_setprio 0
	ds_read_b128 v[154:157], v175 offset:49152
	ds_read_b128 v[158:161], v175 offset:50176
	ds_read_b128 v[178:181], v175 offset:51200
	ds_read_b128 v[182:185], v175 offset:52224
	ds_read_b128 v[186:189], v175 offset:53248
	ds_read_b128 v[190:193], v175 offset:54272
	ds_read_b128 v[194:197], v175 offset:55296
	ds_read_b128 v[198:201], v175 offset:56320
	s_mov_b32 m0, s35
	s_nop 0
	global_load_lds_dwordx4 v232, s[100:101]
	s_mov_b32 m0, s53
	s_nop 0
	global_load_lds_dwordx4 v233, s[100:101]
	s_mov_b32 m0, s56
	s_nop 0
	global_load_lds_dwordx4 v234, s[98:99]
	s_mov_b32 m0, s57
	s_nop 0
	global_load_lds_dwordx4 v235, s[98:99]
	s_mov_b32 m0, s54
	s_nop 0
	global_load_lds_dwordx4 v236, s[100:101]
	s_mov_b32 m0, s55
	s_nop 0
	global_load_lds_dwordx4 v237, s[100:101]
	s_add_i32 s58, s58, 2
	s_add_u32 s10, s10, 0x100
	s_addc_u32 s11, s11, 0
	s_add_u32 s98, s98, 0x100
	s_addc_u32 s99, s99, 0
	s_add_u32 s100, s100, 0x100
	s_addc_u32 s101, s101, 0
	s_cmp_gt_u32 s58, 27
	s_waitcnt vmcnt(8)
	s_waitcnt lgkmcnt(0)
	s_setprio 1
	s_barrier
	v_mfma_f32_16x16x32_bf16 v[26:29], v[154:157], v[138:141], v[26:29]
	v_mfma_f32_16x16x32_bf16 v[38:41], v[154:157], v[146:149], v[38:41]
	v_mfma_f32_16x16x32_bf16 v[50:53], v[178:181], v[138:141], v[50:53]
	v_mfma_f32_16x16x32_bf16 v[62:65], v[178:181], v[146:149], v[62:65]
	v_mfma_f32_16x16x32_bf16 v[74:77], v[186:189], v[138:141], v[74:77]
	v_mfma_f32_16x16x32_bf16 v[82:85], v[186:189], v[146:149], v[82:85]
	v_mfma_f32_16x16x32_bf16 v[90:93], v[194:197], v[138:141], v[90:93]
	v_mfma_f32_16x16x32_bf16 v[94:97], v[194:197], v[146:149], v[94:97]
	v_mfma_f32_16x16x32_bf16 v[26:29], v[158:161], v[142:145], v[26:29]
	v_mfma_f32_16x16x32_bf16 v[38:41], v[158:161], v[150:153], v[38:41]
	v_mfma_f32_16x16x32_bf16 v[50:53], v[182:185], v[142:145], v[50:53]
	v_mfma_f32_16x16x32_bf16 v[62:65], v[182:185], v[150:153], v[62:65]
	v_mfma_f32_16x16x32_bf16 v[74:77], v[190:193], v[142:145], v[74:77]
	v_mfma_f32_16x16x32_bf16 v[82:85], v[190:193], v[150:153], v[82:85]
	v_mfma_f32_16x16x32_bf16 v[90:93], v[198:201], v[142:145], v[90:93]
	v_mfma_f32_16x16x32_bf16 v[94:97], v[198:201], v[150:153], v[94:97]
	v_mfma_f32_16x16x32_bf16 v[98:101], v[154:157], v[208:211], v[98:101]
	v_mfma_f32_16x16x32_bf16 v[102:105], v[154:157], v[216:219], v[102:105]
	v_mfma_f32_16x16x32_bf16 v[106:109], v[178:181], v[208:211], v[106:109]
	v_mfma_f32_16x16x32_bf16 v[110:113], v[178:181], v[216:219], v[110:113]
	v_mfma_f32_16x16x32_bf16 v[114:117], v[186:189], v[208:211], v[114:117]
	v_mfma_f32_16x16x32_bf16 v[118:121], v[186:189], v[216:219], v[118:121]
	v_mfma_f32_16x16x32_bf16 v[122:125], v[194:197], v[208:211], v[122:125]
	v_mfma_f32_16x16x32_bf16 v[126:129], v[194:197], v[216:219], v[126:129]
	v_mfma_f32_16x16x32_bf16 v[98:101], v[158:161], v[212:215], v[98:101]
	v_mfma_f32_16x16x32_bf16 v[102:105], v[158:161], v[220:223], v[102:105]
	v_mfma_f32_16x16x32_bf16 v[106:109], v[182:185], v[212:215], v[106:109]
	v_mfma_f32_16x16x32_bf16 v[110:113], v[182:185], v[220:223], v[110:113]
	v_mfma_f32_16x16x32_bf16 v[114:117], v[190:193], v[212:215], v[114:117]
	v_mfma_f32_16x16x32_bf16 v[118:121], v[190:193], v[220:223], v[118:121]
	v_mfma_f32_16x16x32_bf16 v[122:125], v[198:201], v[212:215], v[122:125]
	v_mfma_f32_16x16x32_bf16 v[126:129], v[198:201], v[220:223], v[126:129]
	s_barrier
; #define LDA(dst, b, h)                                                                                     \
;   _Pragma("unroll") for (int m = 0; m < 4; ++m) _Pragma("unroll") for (int k = 0; k < 2; ++k) dst[m][k] = \
;       *reinterpret_cast<const bf16x8*>(shmc + aL + (((b) * 2 + (h)) * 16384 + (m * 2 + k) * 1024))
; #define LDB(dst, b, h)                                                                                     \
;   _Pragma("unroll") for (int n = 0; n < 2; ++n) _Pragma("unroll") for (int k = 0; k < 2; ++k) dst[n][k] = \
;       *reinterpret_cast<const bf16x8*>(shmc + bL + (((b) * 2 + (h)) * 16384 + (n * 2 + k) * 1024))
; #define OPAQ asm volatile("" : "+v"(aL), "+v"(bL))
; #define WAIT_V(n) asm volatile("s_waitcnt vmcnt(" #n ")" ::: "memory")
; #define WAIT_L(n) asm volatile("s_waitcnt lgkmcnt(" #n ")" ::: "memory")
; #define BAR __builtin_amdgcn_s_barrier()
; template <int EPI>
; __device__ __forceinline__ void phase_gemm(const Params& p, const GemmDesc& d, char* shmc) {
;     ...
;     {
;       OPAQ;
;       LDB(B0, 0, 0); LDA(At, 0, 0); STAGE_A(SA(1, 1), 1, nt - 1);
;       BAR; WAIT_L(0); MMA(0, 0, At, B0); BAR;
;       LDB(B1, 0, 1); BAR; WAIT_L(0); MMA(0, 1, At, B1); BAR;
;       LDA(At, 0, 1); WAIT_V(4); BAR; WAIT_L(0); MMA(1, 0, At, B0); MMA(1, 1, At, B1); BAR;
	s_cbranch_scc0 .LBB0_1153
	s_setprio 0
	s_add_u32 s8, s8, 0x80f80
	s_addc_u32 s9, s9, 0
	v_add_u32_e32 v162, 0, v205
	v_add_u32_e32 v175, 0, v204
	s_mov_b32 m0, s59
	ds_read_b128 v[130:133], v162
	ds_read_b128 v[134:137], v162 offset:1024
	ds_read_b128 v[138:141], v162 offset:2048
	ds_read_b128 v[142:145], v162 offset:3072
	ds_read_b128 v[146:149], v175
	ds_read_b128 v[150:153], v175 offset:1024
	ds_read_b128 v[154:157], v175 offset:2048
	ds_read_b128 v[158:161], v175 offset:3072
	ds_read_b128 v[178:181], v175 offset:4096
	ds_read_b128 v[182:185], v175 offset:5120
	ds_read_b128 v[186:189], v175 offset:6144
	ds_read_b128 v[190:193], v175 offset:7168
	global_load_lds_dwordx4 v174, s[8:9]
	s_mov_b32 m0, s68
	s_nop 0
	global_load_lds_dwordx4 v176, s[8:9]
	s_waitcnt vmcnt(8)
	s_barrier
	s_waitcnt lgkmcnt(0)
	s_setprio 1
	s_waitcnt lgkmcnt(0)
	v_mfma_f32_16x16x32_bf16 v[2:5], v[146:149], v[130:133], v[2:5]
	v_mfma_f32_16x16x32_bf16 v[6:9], v[146:149], v[138:141], v[6:9]
	v_mfma_f32_16x16x32_bf16 v[10:13], v[154:157], v[130:133], v[10:13]
	v_mfma_f32_16x16x32_bf16 v[18:21], v[154:157], v[138:141], v[18:21]
	v_mfma_f32_16x16x32_bf16 v[66:69], v[186:189], v[138:141], v[66:69]
	v_mfma_f32_16x16x32_bf16 v[2:5], v[150:153], v[134:137], v[2:5]
	v_mfma_f32_16x16x32_bf16 v[6:9], v[150:153], v[142:145], v[6:9]
	v_mfma_f32_16x16x32_bf16 v[10:13], v[158:161], v[134:137], v[10:13]
	v_mfma_f32_16x16x32_bf16 v[18:21], v[158:161], v[142:145], v[18:21]
	v_mfma_f32_16x16x32_bf16 v[30:33], v[178:181], v[130:133], v[30:33]
	v_mfma_f32_16x16x32_bf16 v[42:45], v[178:181], v[138:141], v[42:45]
	v_mfma_f32_16x16x32_bf16 v[54:57], v[186:189], v[130:133], v[54:57]
	v_mfma_f32_16x16x32_bf16 v[66:69], v[190:193], v[142:145], v[66:69]
	v_mfma_f32_16x16x32_bf16 v[30:33], v[182:185], v[134:137], v[30:33]
	v_mfma_f32_16x16x32_bf16 v[42:45], v[182:185], v[142:145], v[42:45]
	v_mfma_f32_16x16x32_bf16 v[54:57], v[190:193], v[134:137], v[54:57]
	s_setprio 0
	s_barrier
	ds_read_b128 v[194:197], v162 offset:16384
	ds_read_b128 v[198:201], v162 offset:17408
	ds_read_b128 v[208:211], v162 offset:18432
	ds_read_b128 v[212:215], v162 offset:19456
	s_barrier
	s_waitcnt lgkmcnt(0)
	s_setprio 1
	s_waitcnt lgkmcnt(0)
	v_mfma_f32_16x16x32_bf16 v[14:17], v[146:149], v[194:197], v[14:17]
	v_mfma_f32_16x16x32_bf16 v[22:25], v[146:149], v[208:211], v[22:25]
	v_mfma_f32_16x16x32_bf16 v[58:61], v[178:181], v[194:197], v[58:61]
	v_mfma_f32_16x16x32_bf16 v[14:17], v[150:153], v[198:201], v[14:17]
	v_mfma_f32_16x16x32_bf16 v[22:25], v[150:153], v[212:215], v[22:25]
	v_mfma_f32_16x16x32_bf16 v[150:153], v[182:185], v[198:201], v[58:61]
	v_mfma_f32_16x16x32_bf16 v[58:61], v[178:181], v[208:211], v[70:73]
	v_mfma_f32_16x16x32_bf16 v[34:37], v[154:157], v[194:197], v[34:37]
	v_mfma_f32_16x16x32_bf16 v[46:49], v[154:157], v[208:211], v[46:49]
	v_mfma_f32_16x16x32_bf16 v[154:157], v[182:185], v[212:215], v[58:61]
	v_mfma_f32_16x16x32_bf16 v[58:61], v[186:189], v[194:197], v[78:81]
	v_mfma_f32_16x16x32_bf16 v[78:81], v[190:193], v[198:201], v[58:61]
	v_mfma_f32_16x16x32_bf16 v[58:61], v[186:189], v[208:211], v[86:89]
	v_mfma_f32_16x16x32_bf16 v[86:89], v[190:193], v[212:215], v[58:61]
	v_mfma_f32_16x16x32_bf16 v[34:37], v[158:161], v[198:201], v[34:37]
	v_mfma_f32_16x16x32_bf16 v[46:49], v[158:161], v[212:215], v[46:49]
	s_setprio 0
	s_barrier
	s_nop 2
	ds_read_b128 v[58:61], v175 offset:16384
	ds_read_b128 v[70:73], v175 offset:17408
	ds_read_b128 v[146:149], v175 offset:18432
	ds_read_b128 v[158:161], v175 offset:19456
	ds_read_b128 v[178:181], v175 offset:20480
	ds_read_b128 v[182:185], v175 offset:21504
	ds_read_b128 v[186:189], v175 offset:22528
	ds_read_b128 v[190:193], v175 offset:23552
	s_waitcnt vmcnt(4)
	s_barrier
	s_waitcnt lgkmcnt(0)
	s_setprio 1
	s_waitcnt lgkmcnt(0)
	v_mfma_f32_16x16x32_bf16 v[74:77], v[178:181], v[130:133], v[74:77]
	v_mfma_f32_16x16x32_bf16 v[216:219], v[182:185], v[134:137], v[74:77]
	v_mfma_f32_16x16x32_bf16 v[74:77], v[178:181], v[138:141], v[82:85]
	v_mfma_f32_16x16x32_bf16 v[26:29], v[58:61], v[130:133], v[26:29]
	v_mfma_f32_16x16x32_bf16 v[82:85], v[182:185], v[142:145], v[74:77]
	v_mfma_f32_16x16x32_bf16 v[74:77], v[186:189], v[130:133], v[90:93]
	v_mfma_f32_16x16x32_bf16 v[26:29], v[70:73], v[134:137], v[26:29]
	v_mfma_f32_16x16x32_bf16 v[38:41], v[58:61], v[138:141], v[38:41]
	v_mfma_f32_16x16x32_bf16 v[50:53], v[146:149], v[130:133], v[50:53]
	v_mfma_f32_16x16x32_bf16 v[62:65], v[146:149], v[138:141], v[62:65]
	v_mfma_f32_16x16x32_bf16 v[90:93], v[190:193], v[134:137], v[74:77]
	v_mfma_f32_16x16x32_bf16 v[74:77], v[186:189], v[138:141], v[94:97]
	v_mfma_f32_16x16x32_bf16 v[38:41], v[70:73], v[142:145], v[38:41]
	v_mfma_f32_16x16x32_bf16 v[50:53], v[158:161], v[134:137], v[50:53]
	v_mfma_f32_16x16x32_bf16 v[62:65], v[158:161], v[142:145], v[62:65]
	v_mfma_f32_16x16x32_bf16 v[220:223], v[190:193], v[142:145], v[74:77]
	s_setprio 0
	s_setprio 1
	v_mfma_f32_16x16x32_bf16 v[74:77], v[58:61], v[194:197], v[98:101]
	v_mfma_f32_16x16x32_bf16 v[58:61], v[58:61], v[208:211], v[102:105]
	v_mfma_f32_16x16x32_bf16 v[228:231], v[70:73], v[212:215], v[58:61]
	v_mfma_f32_16x16x32_bf16 v[58:61], v[146:149], v[194:197], v[106:109]
	v_mfma_f32_16x16x32_bf16 v[232:235], v[158:161], v[198:201], v[58:61]
	v_mfma_f32_16x16x32_bf16 v[58:61], v[146:149], v[208:211], v[110:113]
	v_mfma_f32_16x16x32_bf16 v[236:239], v[158:161], v[212:215], v[58:61]
	v_mfma_f32_16x16x32_bf16 v[58:61], v[178:181], v[194:197], v[114:117]
	v_mfma_f32_16x16x32_bf16 v[240:243], v[182:185], v[198:201], v[58:61]
	v_mfma_f32_16x16x32_bf16 v[58:61], v[178:181], v[208:211], v[118:121]
	v_mfma_f32_16x16x32_bf16 v[178:181], v[182:185], v[212:215], v[58:61]
	v_mfma_f32_16x16x32_bf16 v[58:61], v[186:189], v[194:197], v[122:125]
	v_mfma_f32_16x16x32_bf16 v[182:185], v[190:193], v[198:201], v[58:61]
	v_mfma_f32_16x16x32_bf16 v[58:61], v[186:189], v[208:211], v[126:129]
	v_mfma_f32_16x16x32_bf16 v[224:227], v[70:73], v[198:201], v[74:77]
	v_mfma_f32_16x16x32_bf16 v[186:189], v[190:193], v[212:215], v[58:61]
	s_setprio 0
	s_barrier
; #define LDA(dst, b, h)                                                                                     \
;   _Pragma("unroll") for (int m = 0; m < 4; ++m) _Pragma("unroll") for (int k = 0; k < 2; ++k) dst[m][k] = \
;       *reinterpret_cast<const bf16x8*>(shmc + aL + (((b) * 2 + (h)) * 16384 + (m * 2 + k) * 1024))
; #define LDB(dst, b, h)                                                                                     \
;   _Pragma("unroll") for (int n = 0; n < 2; ++n) _Pragma("unroll") for (int k = 0; k < 2; ++k) dst[n][k] = \
;       *reinterpret_cast<const bf16x8*>(shmc + bL + (((b) * 2 + (h)) * 16384 + (n * 2 + k) * 1024))
; #define WAIT_V(n) asm volatile("s_waitcnt vmcnt(" #n ")" ::: "memory")
; #define WAIT_L(n) asm volatile("s_waitcnt lgkmcnt(" #n ")" ::: "memory")
; #define BAR __builtin_amdgcn_s_barrier()
; template <int EPI>
; __device__ __forceinline__ void phase_gemm(const Params& p, const GemmDesc& d, char* shmc) {
;     ...
;     {
;       LDB(B0, 1, 0); LDA(At, 1, 0); WAIT_V(2); BAR; WAIT_L(0); MMA(0, 0, At, B0); BAR;
;       LDB(B1, 1, 1); WAIT_V(0); BAR; WAIT_L(0); MMA(0, 1, At, B1); BAR;
;       LDA(At, 1, 1); BAR; WAIT_L(0); MMA(1, 0, At, B0); MMA(1, 1, At, B1); BAR;
;     }
;     if (wr == 0) BAR;
	ds_read_b128 v[98:101], v162 offset:32768
	ds_read_b128 v[106:109], v162 offset:33792
	ds_read_b128 v[190:193], v162 offset:34816
	ds_read_b128 v[194:197], v162 offset:35840
	ds_read_b128 v[58:61], v175 offset:32768
	ds_read_b128 v[70:73], v175 offset:33792
	ds_read_b128 v[114:117], v175 offset:34816
	ds_read_b128 v[122:125], v175 offset:35840
	ds_read_b128 v[130:133], v175 offset:36864
	ds_read_b128 v[138:141], v175 offset:37888
	ds_read_b128 v[198:201], v175 offset:38912
	ds_read_b128 v[208:211], v175 offset:39936
	s_waitcnt vmcnt(2)
	s_barrier
	s_waitcnt lgkmcnt(0)
	s_setprio 1
	s_waitcnt lgkmcnt(0)
	v_mfma_f32_16x16x32_bf16 v[2:5], v[58:61], v[98:101], v[2:5]
	v_mfma_f32_16x16x32_bf16 v[158:161], v[70:73], v[106:109], v[2:5]
	v_mfma_f32_16x16x32_bf16 v[2:5], v[58:61], v[190:193], v[6:9]
	v_mfma_f32_16x16x32_bf16 v[146:149], v[70:73], v[194:197], v[2:5]
	v_mfma_f32_16x16x32_bf16 v[2:5], v[114:117], v[98:101], v[10:13]
	v_mfma_f32_16x16x32_bf16 v[142:145], v[122:125], v[106:109], v[2:5]
	v_mfma_f32_16x16x32_bf16 v[2:5], v[114:117], v[190:193], v[18:21]
	v_mfma_f32_16x16x32_bf16 v[134:137], v[122:125], v[194:197], v[2:5]
	v_mfma_f32_16x16x32_bf16 v[2:5], v[130:133], v[98:101], v[30:33]
	v_mfma_f32_16x16x32_bf16 v[126:129], v[138:141], v[106:109], v[2:5]
	v_mfma_f32_16x16x32_bf16 v[2:5], v[130:133], v[190:193], v[42:45]
	v_mfma_f32_16x16x32_bf16 v[118:121], v[138:141], v[194:197], v[2:5]
	v_mfma_f32_16x16x32_bf16 v[2:5], v[198:201], v[98:101], v[54:57]
	v_mfma_f32_16x16x32_bf16 v[110:113], v[208:211], v[106:109], v[2:5]
	v_mfma_f32_16x16x32_bf16 v[2:5], v[198:201], v[190:193], v[66:69]
	v_mfma_f32_16x16x32_bf16 v[102:105], v[208:211], v[194:197], v[2:5]
	s_setprio 0
	s_barrier
	ds_read_b128 v[30:33], v162 offset:49152
	ds_read_b128 v[42:45], v162 offset:50176
	ds_read_b128 v[54:57], v162 offset:51200
	ds_read_b128 v[212:215], v162 offset:52224
	s_waitcnt vmcnt(0)
	s_barrier
	s_waitcnt lgkmcnt(0)
	s_setprio 1
	s_waitcnt lgkmcnt(0)
	v_mfma_f32_16x16x32_bf16 v[2:5], v[58:61], v[30:33], v[14:17]
	v_mfma_f32_16x16x32_bf16 v[94:97], v[70:73], v[42:45], v[2:5]
	v_mfma_f32_16x16x32_bf16 v[2:5], v[58:61], v[54:57], v[22:25]
	v_mfma_f32_16x16x32_bf16 v[58:61], v[70:73], v[212:215], v[2:5]
	v_mfma_f32_16x16x32_bf16 v[2:5], v[114:117], v[30:33], v[34:37]
	v_mfma_f32_16x16x32_bf16 v[74:77], v[122:125], v[42:45], v[2:5]
	v_mfma_f32_16x16x32_bf16 v[2:5], v[114:117], v[54:57], v[46:49]
	v_mfma_f32_16x16x32_bf16 v[10:13], v[122:125], v[212:215], v[2:5]
	v_mfma_f32_16x16x32_bf16 v[2:5], v[130:133], v[30:33], v[150:153]
	v_mfma_f32_16x16x32_bf16 v[70:73], v[138:141], v[42:45], v[2:5]
	v_mfma_f32_16x16x32_bf16 v[2:5], v[130:133], v[54:57], v[154:157]
	v_mfma_f32_16x16x32_bf16 v[6:9], v[138:141], v[212:215], v[2:5]
	v_mfma_f32_16x16x32_bf16 v[2:5], v[198:201], v[30:33], v[78:81]
	v_mfma_f32_16x16x32_bf16 v[66:69], v[208:211], v[42:45], v[2:5]
	v_mfma_f32_16x16x32_bf16 v[2:5], v[198:201], v[54:57], v[86:89]
	v_mfma_f32_16x16x32_bf16 v[2:5], v[208:211], v[212:215], v[2:5]
	s_setprio 0
	s_barrier
	ds_read_b128 v[14:17], v175 offset:49152
	ds_read_b128 v[18:21], v175 offset:50176
	ds_read_b128 v[22:25], v175 offset:51200
	ds_read_b128 v[34:37], v175 offset:52224
	ds_read_b128 v[46:49], v175 offset:53248
	ds_read_b128 v[78:81], v175 offset:54272
	ds_read_b128 v[198:201], v175 offset:55296
	ds_read_b128 v[208:211], v175 offset:56320
	s_barrier
	s_waitcnt lgkmcnt(0)
	s_setprio 1
	s_waitcnt lgkmcnt(0)
	v_mfma_f32_16x16x32_bf16 v[26:29], v[14:17], v[98:101], v[26:29]
	v_mfma_f32_16x16x32_bf16 v[154:157], v[18:21], v[106:109], v[26:29]
	v_mfma_f32_16x16x32_bf16 v[26:29], v[14:17], v[190:193], v[38:41]
	v_mfma_f32_16x16x32_bf16 v[150:153], v[18:21], v[194:197], v[26:29]
	v_mfma_f32_16x16x32_bf16 v[26:29], v[22:25], v[98:101], v[50:53]
	v_mfma_f32_16x16x32_bf16 v[138:141], v[34:37], v[106:109], v[26:29]
	v_mfma_f32_16x16x32_bf16 v[26:29], v[22:25], v[190:193], v[62:65]
	v_mfma_f32_16x16x32_bf16 v[130:133], v[34:37], v[194:197], v[26:29]
	v_mfma_f32_16x16x32_bf16 v[26:29], v[46:49], v[98:101], v[216:219]
	v_mfma_f32_16x16x32_bf16 v[122:125], v[78:81], v[106:109], v[26:29]
	v_mfma_f32_16x16x32_bf16 v[26:29], v[46:49], v[190:193], v[82:85]
	v_mfma_f32_16x16x32_bf16 v[114:117], v[78:81], v[194:197], v[26:29]
	v_mfma_f32_16x16x32_bf16 v[26:29], v[198:201], v[98:101], v[90:93]
	v_mfma_f32_16x16x32_bf16 v[106:109], v[208:211], v[106:109], v[26:29]
	v_mfma_f32_16x16x32_bf16 v[26:29], v[198:201], v[190:193], v[220:223]
	v_mfma_f32_16x16x32_bf16 v[98:101], v[208:211], v[194:197], v[26:29]
	s_setprio 0
	s_setprio 1
	v_mfma_f32_16x16x32_bf16 v[26:29], v[14:17], v[30:33], v[224:227]
	v_mfma_f32_16x16x32_bf16 v[14:17], v[14:17], v[54:57], v[228:231]
	v_mfma_f32_16x16x32_bf16 v[90:93], v[18:21], v[42:45], v[26:29]
	v_mfma_f32_16x16x32_bf16 v[26:29], v[18:21], v[212:215], v[14:17]
	v_mfma_f32_16x16x32_bf16 v[14:17], v[22:25], v[30:33], v[232:235]
	v_mfma_f32_16x16x32_bf16 v[86:89], v[34:37], v[42:45], v[14:17]
	v_mfma_f32_16x16x32_bf16 v[14:17], v[22:25], v[54:57], v[236:239]
	v_mfma_f32_16x16x32_bf16 v[22:25], v[34:37], v[212:215], v[14:17]
	v_mfma_f32_16x16x32_bf16 v[14:17], v[46:49], v[30:33], v[240:243]
	v_mfma_f32_16x16x32_bf16 v[82:85], v[78:81], v[42:45], v[14:17]
	v_mfma_f32_16x16x32_bf16 v[14:17], v[46:49], v[54:57], v[178:181]
	v_mfma_f32_16x16x32_bf16 v[18:21], v[78:81], v[212:215], v[14:17]
	v_mfma_f32_16x16x32_bf16 v[14:17], v[198:201], v[30:33], v[182:185]
	v_mfma_f32_16x16x32_bf16 v[78:81], v[208:211], v[42:45], v[14:17]
	v_mfma_f32_16x16x32_bf16 v[14:17], v[198:201], v[54:57], v[186:189]
	v_mfma_f32_16x16x32_bf16 v[14:17], v[208:211], v[212:215], v[14:17]
	s_setprio 0
	s_barrier
	s_and_saveexec_b64 s[8:9], s[6:7]
	s_cbranch_execz .LBB0_1156
	s_barrier

; #define WAIT_V(n) asm volatile("s_waitcnt vmcnt(" #n ")" ::: "memory")
; #define BAR __builtin_amdgcn_s_barrier()
; template <int EPI>
; __device__ __forceinline__ void phase_gemm(const Params& p, const GemmDesc& d, char* shmc) {
;     ...
;     f32x4 acc[2][2][4][2];
; #pragma unroll
;     for (int a = 0; a < 2; ++a)
; #pragma unroll
;       for (int b = 0; b < 2; ++b)
; #pragma unroll
;         for (int m = 0; m < 4; ++m)
; #pragma unroll
;           for (int n = 0; n < 2; ++n) acc[a][b][m][n] = f32x4{0.f, 0.f, 0.f, 0.f};
;     bf16x8 At[4][2], B0[2][2], B1[2][2];
;     if constexpr (EPI == EPI_UP || EPI == EPI_QKV) {
;       if (wid == 0)
;         __builtin_amdgcn_global_load_lds((const unsigned*)(p.rstd + brow + lane * 4), (unsigned*)(shmc + 143360), 16, 0, 0);
;     }
;     STAGE_B(SB(0, 0), 0, 0); STAGE_A(SA(0, 0), 0, 0);
;     STAGE_B(SB(0, 1), 1, 0); STAGE_A(SA(0, 1), 1, 0);
;     if (wr == 1) BAR;
;     WAIT_V(4); BAR;
;     STAGE_B(SB(1, 0), 0, 1); STAGE_A(SA(1, 0), 0, 1); STAGE_B(SB(1, 1), 1, 1);
;     WAIT_V(6); BAR;
;     for (int t = 0; t < nt - 2; t += 2) {
.LBB0_1311:
	s_or_b64 exec, exec, s[44:45]
	v_mov_b32_e32 v141, v131
	s_waitcnt lgkmcnt(0)
	v_lshl_add_u64 v[2:3], s[42:43], 0, v[140:141]
	v_mov_b32_e32 v143, v131
	s_mov_b32 m0, s53
	v_lshl_add_u64 v[4:5], s[42:43], 0, v[142:143]
	v_lshl_add_u64 v[2:3], v[2:3], 0, s[8:9]
	v_lshl_add_u64 v[6:7], s[38:39], 0, v[140:141]
	v_mov_b32_e32 v10, 0
	v_mov_b32_e32 v11, 0
	v_mov_b32_e32 v12, 0
	v_mov_b32_e32 v13, 0
	v_mov_b32_e32 v14, 0
	v_mov_b32_e32 v15, 0
	v_mov_b32_e32 v16, 0
	v_mov_b32_e32 v17, 0
	v_mov_b32_e32 v18, 0
	v_mov_b32_e32 v19, 0
	v_mov_b32_e32 v20, 0
	v_mov_b32_e32 v21, 0
	v_mov_b32_e32 v22, 0
	v_mov_b32_e32 v23, 0
	v_mov_b32_e32 v24, 0
	v_mov_b32_e32 v25, 0
	v_mov_b32_e32 v26, 0
	v_mov_b32_e32 v27, 0
	v_mov_b32_e32 v28, 0
	v_mov_b32_e32 v29, 0
	v_mov_b32_e32 v30, 0
	v_mov_b32_e32 v31, 0
	v_mov_b32_e32 v32, 0
	v_mov_b32_e32 v33, 0
	v_mov_b32_e32 v34, 0
	v_mov_b32_e32 v35, 0
	v_mov_b32_e32 v36, 0
	v_mov_b32_e32 v37, 0
	v_mov_b32_e32 v38, 0
	v_mov_b32_e32 v39, 0
	v_mov_b32_e32 v40, 0
	v_mov_b32_e32 v41, 0
	v_mov_b32_e32 v42, 0
	v_mov_b32_e32 v43, 0
	v_mov_b32_e32 v44, 0
	v_mov_b32_e32 v45, 0
	v_mov_b32_e32 v46, 0
	v_mov_b32_e32 v47, 0
	v_mov_b32_e32 v48, 0
	v_mov_b32_e32 v49, 0
	v_mov_b32_e32 v50, 0
	v_mov_b32_e32 v51, 0
	v_mov_b32_e32 v52, 0
	v_mov_b32_e32 v53, 0
	v_mov_b32_e32 v54, 0
	v_mov_b32_e32 v55, 0
	v_mov_b32_e32 v56, 0
	v_mov_b32_e32 v57, 0
	v_mov_b32_e32 v70, 0
	v_mov_b32_e32 v71, 0
	v_mov_b32_e32 v72, 0
	v_mov_b32_e32 v73, 0
	v_mov_b32_e32 v86, 0
	v_mov_b32_e32 v87, 0
	v_mov_b32_e32 v88, 0
	v_mov_b32_e32 v89, 0
	v_mov_b32_e32 v98, 0
	v_mov_b32_e32 v99, 0
	v_mov_b32_e32 v100, 0
	v_mov_b32_e32 v101, 0
	v_mov_b32_e32 v102, 0
	v_mov_b32_e32 v103, 0
	v_mov_b32_e32 v104, 0
	v_mov_b32_e32 v105, 0
	v_mov_b32_e32 v106, 0
	v_mov_b32_e32 v107, 0
	v_mov_b32_e32 v108, 0
	v_mov_b32_e32 v109, 0
	v_mov_b32_e32 v110, 0
	v_mov_b32_e32 v111, 0
	v_mov_b32_e32 v112, 0
	v_mov_b32_e32 v113, 0
	v_mov_b32_e32 v114, 0
	v_mov_b32_e32 v115, 0
	v_mov_b32_e32 v116, 0
	v_mov_b32_e32 v117, 0
	v_mov_b32_e32 v118, 0
	v_mov_b32_e32 v119, 0
	v_mov_b32_e32 v120, 0
	v_mov_b32_e32 v121, 0
	v_mov_b32_e32 v122, 0
	v_mov_b32_e32 v123, 0
	v_mov_b32_e32 v124, 0
	v_mov_b32_e32 v125, 0
	v_mov_b32_e32 v126, 0
	v_mov_b32_e32 v127, 0
	v_mov_b32_e32 v128, 0
	v_mov_b32_e32 v129, 0
	v_mov_b32_e32 v58, 0
	v_mov_b32_e32 v59, 0
	v_mov_b32_e32 v60, 0
	v_mov_b32_e32 v61, 0
	v_mov_b32_e32 v62, 0
	v_mov_b32_e32 v63, 0
	v_mov_b32_e32 v64, 0
	v_mov_b32_e32 v65, 0
	v_mov_b32_e32 v66, 0
	v_mov_b32_e32 v67, 0
	v_mov_b32_e32 v68, 0
	v_mov_b32_e32 v69, 0
	v_mov_b32_e32 v74, 0
	v_mov_b32_e32 v75, 0
	v_mov_b32_e32 v76, 0
	v_mov_b32_e32 v77, 0
	v_mov_b32_e32 v78, 0
	v_mov_b32_e32 v79, 0
	v_mov_b32_e32 v80, 0
	v_mov_b32_e32 v81, 0
	v_mov_b32_e32 v82, 0
	v_mov_b32_e32 v83, 0
	v_mov_b32_e32 v84, 0
	v_mov_b32_e32 v85, 0
	v_mov_b32_e32 v90, 0
	v_mov_b32_e32 v91, 0
	v_mov_b32_e32 v92, 0
	v_mov_b32_e32 v93, 0
	v_mov_b32_e32 v94, 0
	v_mov_b32_e32 v95, 0
	v_mov_b32_e32 v96, 0
	v_mov_b32_e32 v97, 0
	s_waitcnt vmcnt(2)
	s_barrier
	global_load_lds_dwordx4 v[2:3], off
	v_lshl_add_u64 v[2:3], v[4:5], 0, s[8:9]
	s_mov_b32 m0, s54
	v_lshl_add_u64 v[8:9], s[38:39], 0, v[142:143]
	global_load_lds_dwordx4 v[2:3], off
	v_lshl_add_u64 v[2:3], v[6:7], 0, s[8:9]
	s_mov_b32 m0, s55
	s_add_u32 s42, s42, 0x160080
	global_load_lds_dwordx4 v[2:3], off
	v_lshl_add_u64 v[2:3], v[8:9], 0, s[8:9]
	s_mov_b32 m0, s56
	s_addc_u32 s43, s43, 0
	global_load_lds_dwordx4 v[2:3], off
	s_mov_b32 m0, s57
	s_add_i32 s64, s64, s65
	global_load_lds_dwordx4 v140, s[42:43]
	s_mov_b32 m0, s58
	v_lshl_add_u64 v[144:145], v[132:133], 0, s[40:41]
	global_load_lds_dwordx4 v142, s[42:43]
	s_waitcnt vmcnt(6)
	v_lshl_add_u64 v[146:147], v[134:135], 0, s[40:41]
	v_mad_i64_i32 v[148:149], s[40:41], s64, v154, v[136:137]
	v_mad_i64_i32 v[150:151], s[40:41], s64, v154, v[138:139]
	v_mov_b32_e32 v2, 0
	s_mov_b32 s42, -2
	s_mov_b64 s[40:41], 0
	v_mov_b32_e32 v3, v2
	v_mov_b32_e32 v4, v2
	v_mov_b32_e32 v5, v2
	v_mov_b32_e32 v6, v2
	v_mov_b32_e32 v7, v2
	v_mov_b32_e32 v8, v2
	v_mov_b32_e32 v9, v2
	s_barrier
	v_readfirstlane_b32 s98, v148
	v_readfirstlane_b32 s99, v149
	v_readfirstlane_b32 s100, v144
	v_readfirstlane_b32 s101, v145
	s_nop 3
	v_subrev_u32_e32 v220, s98, v148
	v_add_u32_e32 v220, s10, v220
	v_subrev_u32_e32 v221, s98, v150
	v_add_u32_e32 v221, s10, v221
	v_subrev_u32_e32 v222, s100, v144
	v_add_u32_e32 v222, s18, v222
	v_subrev_u32_e32 v223, s100, v146
	v_add_u32_e32 v223, s18, v223
	v_subrev_u32_e32 v224, s98, v148
	v_add_u32_e32 v224, s20, v224
	v_subrev_u32_e32 v225, s98, v150
	v_add_u32_e32 v225, s20, v225
	v_subrev_u32_e32 v226, s100, v144
	v_add_u32_e32 v226, s22, v226
	v_subrev_u32_e32 v227, s100, v146
	v_add_u32_e32 v227, s22, v227
	v_subrev_u32_e32 v228, s98, v148
	v_add_u32_e32 v228, s24, v228
	v_subrev_u32_e32 v229, s98, v150
	v_add_u32_e32 v229, s24, v229
	v_subrev_u32_e32 v232, s100, v144
	v_add_u32_e32 v232, s26, v232
	v_subrev_u32_e32 v233, s100, v146
	v_add_u32_e32 v233, s26, v233
	v_subrev_u32_e32 v234, s98, v148
	v_add_u32_e32 v234, s30, v234
	v_subrev_u32_e32 v235, s98, v150
	v_add_u32_e32 v235, s30, v235
	v_subrev_u32_e32 v236, s100, v144
	v_add_u32_e32 v236, s36, v236
	v_subrev_u32_e32 v237, s100, v146
	v_add_u32_e32 v237, s36, v237
	s_add_u32 s98, s98, s40
	s_addc_u32 s99, s99, s41
	s_add_u32 s100, s100, s40
	s_addc_u32 s101, s101, s41
; #define LDA(dst, b, h)                                                                                     \
;   _Pragma("unroll") for (int m = 0; m < 4; ++m) _Pragma("unroll") for (int k = 0; k < 2; ++k) dst[m][k] = \
;       *reinterpret_cast<const bf16x8*>(shmc + aL + (((b) * 2 + (h)) * 16384 + (m * 2 + k) * 1024))
; #define LDB(dst, b, h)                                                                                     \
;   _Pragma("unroll") for (int n = 0; n < 2; ++n) _Pragma("unroll") for (int k = 0; k < 2; ++k) dst[n][k] = \
;       *reinterpret_cast<const bf16x8*>(shmc + bL + (((b) * 2 + (h)) * 16384 + (n * 2 + k) * 1024))
; #define OPAQ asm volatile("" : "+v"(aL), "+v"(bL))
; #define WAIT_V(n) asm volatile("s_waitcnt vmcnt(" #n ")" ::: "memory")
; #define WAIT_L(n) asm volatile("s_waitcnt lgkmcnt(" #n ")" ::: "memory")
; #define BAR __builtin_amdgcn_s_barrier()
; #define SCHED __builtin_amdgcn_sched_barrier(0)
; template <int EPI>
; __device__ __forceinline__ void phase_gemm(const Params& p, const GemmDesc& d, char* shmc) {
;     ...
;     for (int t = 0; t < nt - 2; t += 2) {
;       OPAQ;
;       LDB(B0, 0, 0); SCHED; LDA(At, 0, 0); STAGE_A(SA(1, 1), 1, t + 1);
;       WAIT_L(8); BAR; WAIT_L(0); MMA(0, 0, At, B0); BAR; SCHED;
;       LDB(B1, 0, 1); STAGE_B(SB(0, 0), 0, t + 2);
;       BAR; WAIT_L(0); MMA(0, 1, At, B1); BAR;
;       LDA(At, 0, 1); STAGE_A(SA(0, 0), 0, t + 2);
;       BAR; WAIT_L(0); MMA(1, 0, At, B0); BAR; SCHED;
;       STAGE_B(SB(0, 1), 1, t + 2);
;       WAIT_V(6); BAR; MMA(1, 1, At, B1); BAR;
.LBB0_1312:
	s_nop 0
	v_add_u32_e32 v130, 0, v153
	v_add_u32_e32 v141, 0, v152
	s_setprio 0
	ds_read_b128 v[156:159], v130
	ds_read_b128 v[160:163], v130 offset:1024
	ds_read_b128 v[164:167], v130 offset:2048
	ds_read_b128 v[168:171], v130 offset:3072
	ds_read_b128 v[204:207], v130 offset:16384
	ds_read_b128 v[208:211], v130 offset:17408
	ds_read_b128 v[212:215], v130 offset:18432
	ds_read_b128 v[216:219], v130 offset:19456
	ds_read_b128 v[172:175], v141
	ds_read_b128 v[176:179], v141 offset:1024
	ds_read_b128 v[180:183], v141 offset:2048
	ds_read_b128 v[184:187], v141 offset:3072
	ds_read_b128 v[188:191], v141 offset:4096
	ds_read_b128 v[192:195], v141 offset:5120
	ds_read_b128 v[196:199], v141 offset:6144
	ds_read_b128 v[200:203], v141 offset:7168
	s_mov_b32 m0, s59
	s_nop 0
	global_load_lds_dwordx4 v220, s[98:99]
	s_mov_b32 m0, s60
	s_nop 0
	global_load_lds_dwordx4 v221, s[98:99]
	s_waitcnt vmcnt(8)
	s_waitcnt lgkmcnt(0)
	s_setprio 1
	s_barrier
	v_mfma_f32_16x16x32_bf16 v[126:129], v[156:159], v[172:175], v[126:129]
	v_mfma_f32_16x16x32_bf16 v[122:125], v[164:167], v[172:175], v[122:125]
	v_mfma_f32_16x16x32_bf16 v[118:121], v[156:159], v[180:183], v[118:121]
	v_mfma_f32_16x16x32_bf16 v[114:117], v[164:167], v[180:183], v[114:117]
	v_mfma_f32_16x16x32_bf16 v[110:113], v[156:159], v[188:191], v[110:113]
	v_mfma_f32_16x16x32_bf16 v[106:109], v[164:167], v[188:191], v[106:109]
	v_mfma_f32_16x16x32_bf16 v[102:105], v[156:159], v[196:199], v[102:105]
	v_mfma_f32_16x16x32_bf16 v[98:101], v[164:167], v[196:199], v[98:101]
	v_mfma_f32_16x16x32_bf16 v[126:129], v[160:163], v[176:179], v[126:129]
	v_mfma_f32_16x16x32_bf16 v[122:125], v[168:171], v[176:179], v[122:125]
	v_mfma_f32_16x16x32_bf16 v[118:121], v[160:163], v[184:187], v[118:121]
	v_mfma_f32_16x16x32_bf16 v[114:117], v[168:171], v[184:187], v[114:117]
	v_mfma_f32_16x16x32_bf16 v[110:113], v[160:163], v[192:195], v[110:113]
	v_mfma_f32_16x16x32_bf16 v[106:109], v[168:171], v[192:195], v[106:109]
	v_mfma_f32_16x16x32_bf16 v[102:105], v[160:163], v[200:203], v[102:105]
	v_mfma_f32_16x16x32_bf16 v[98:101], v[168:171], v[200:203], v[98:101]
	v_mfma_f32_16x16x32_bf16 v[86:89], v[204:207], v[172:175], v[86:89]
	v_mfma_f32_16x16x32_bf16 v[70:73], v[212:215], v[172:175], v[70:73]
	v_mfma_f32_16x16x32_bf16 v[54:57], v[204:207], v[180:183], v[54:57]
	v_mfma_f32_16x16x32_bf16 v[50:53], v[212:215], v[180:183], v[50:53]
	v_mfma_f32_16x16x32_bf16 v[46:49], v[204:207], v[188:191], v[46:49]
	v_mfma_f32_16x16x32_bf16 v[42:45], v[212:215], v[188:191], v[42:45]
	v_mfma_f32_16x16x32_bf16 v[38:41], v[204:207], v[196:199], v[38:41]
	v_mfma_f32_16x16x32_bf16 v[34:37], v[212:215], v[196:199], v[34:37]
	v_mfma_f32_16x16x32_bf16 v[86:89], v[208:211], v[176:179], v[86:89]
	v_mfma_f32_16x16x32_bf16 v[70:73], v[216:219], v[176:179], v[70:73]
	v_mfma_f32_16x16x32_bf16 v[54:57], v[208:211], v[184:187], v[54:57]
	v_mfma_f32_16x16x32_bf16 v[50:53], v[216:219], v[184:187], v[50:53]
	v_mfma_f32_16x16x32_bf16 v[46:49], v[208:211], v[192:195], v[46:49]
	v_mfma_f32_16x16x32_bf16 v[42:45], v[216:219], v[192:195], v[42:45]
	v_mfma_f32_16x16x32_bf16 v[38:41], v[208:211], v[200:203], v[38:41]
	v_mfma_f32_16x16x32_bf16 v[34:37], v[216:219], v[200:203], v[34:37]
	s_barrier
	s_setprio 0
	ds_read_b128 v[172:175], v141 offset:16384
	ds_read_b128 v[176:179], v141 offset:17408
	ds_read_b128 v[180:183], v141 offset:18432
	ds_read_b128 v[184:187], v141 offset:19456
	ds_read_b128 v[188:191], v141 offset:20480
	ds_read_b128 v[192:195], v141 offset:21504
	ds_read_b128 v[196:199], v141 offset:22528
	ds_read_b128 v[200:203], v141 offset:23552
	s_mov_b32 m0, s34
	s_nop 0
	global_load_lds_dwordx4 v222, s[100:101]
	s_mov_b32 m0, s35
	s_nop 0
	global_load_lds_dwordx4 v223, s[100:101]
	s_mov_b32 m0, s33
	s_nop 0
	global_load_lds_dwordx4 v224, s[98:99]
	s_mov_b32 m0, s46
	s_nop 0
	global_load_lds_dwordx4 v225, s[98:99]
	s_mov_b32 m0, s47
	s_nop 0
	global_load_lds_dwordx4 v226, s[100:101]
	s_mov_b32 m0, s48
	s_nop 0
	global_load_lds_dwordx4 v227, s[100:101]
	s_waitcnt vmcnt(8)
	s_waitcnt lgkmcnt(0)
	s_setprio 1
	s_barrier
	v_mfma_f32_16x16x32_bf16 v[30:33], v[156:159], v[172:175], v[30:33]
	v_mfma_f32_16x16x32_bf16 v[26:29], v[164:167], v[172:175], v[26:29]
	v_mfma_f32_16x16x32_bf16 v[22:25], v[156:159], v[180:183], v[22:25]
	v_mfma_f32_16x16x32_bf16 v[18:21], v[164:167], v[180:183], v[18:21]
	v_mfma_f32_16x16x32_bf16 v[14:17], v[156:159], v[188:191], v[14:17]
	v_mfma_f32_16x16x32_bf16 v[10:13], v[164:167], v[188:191], v[10:13]
	v_mfma_f32_16x16x32_bf16 v[6:9], v[156:159], v[196:199], v[6:9]
	v_mfma_f32_16x16x32_bf16 v[2:5], v[164:167], v[196:199], v[2:5]
	v_mfma_f32_16x16x32_bf16 v[30:33], v[160:163], v[176:179], v[30:33]
	v_mfma_f32_16x16x32_bf16 v[26:29], v[168:171], v[176:179], v[26:29]
	v_mfma_f32_16x16x32_bf16 v[22:25], v[160:163], v[184:187], v[22:25]
	v_mfma_f32_16x16x32_bf16 v[18:21], v[168:171], v[184:187], v[18:21]
	v_mfma_f32_16x16x32_bf16 v[14:17], v[160:163], v[192:195], v[14:17]
	v_mfma_f32_16x16x32_bf16 v[10:13], v[168:171], v[192:195], v[10:13]
	v_mfma_f32_16x16x32_bf16 v[6:9], v[160:163], v[200:203], v[6:9]
	v_mfma_f32_16x16x32_bf16 v[2:5], v[168:171], v[200:203], v[2:5]
	v_mfma_f32_16x16x32_bf16 v[58:61], v[204:207], v[172:175], v[58:61]
	v_mfma_f32_16x16x32_bf16 v[62:65], v[212:215], v[172:175], v[62:65]
	v_mfma_f32_16x16x32_bf16 v[66:69], v[204:207], v[180:183], v[66:69]
	v_mfma_f32_16x16x32_bf16 v[74:77], v[212:215], v[180:183], v[74:77]
	v_mfma_f32_16x16x32_bf16 v[78:81], v[204:207], v[188:191], v[78:81]
	v_mfma_f32_16x16x32_bf16 v[82:85], v[212:215], v[188:191], v[82:85]
	v_mfma_f32_16x16x32_bf16 v[90:93], v[204:207], v[196:199], v[90:93]
	v_mfma_f32_16x16x32_bf16 v[94:97], v[212:215], v[196:199], v[94:97]
	v_mfma_f32_16x16x32_bf16 v[58:61], v[208:211], v[176:179], v[58:61]
	v_mfma_f32_16x16x32_bf16 v[62:65], v[216:219], v[176:179], v[62:65]
	v_mfma_f32_16x16x32_bf16 v[66:69], v[208:211], v[184:187], v[66:69]
	v_mfma_f32_16x16x32_bf16 v[74:77], v[216:219], v[184:187], v[74:77]
	v_mfma_f32_16x16x32_bf16 v[78:81], v[208:211], v[192:195], v[78:81]
	v_mfma_f32_16x16x32_bf16 v[82:85], v[216:219], v[192:195], v[82:85]
	v_mfma_f32_16x16x32_bf16 v[90:93], v[208:211], v[200:203], v[90:93]
	v_mfma_f32_16x16x32_bf16 v[94:97], v[216:219], v[200:203], v[94:97]
	s_barrier
; #define LDA(dst, b, h)                                                                                     \
;   _Pragma("unroll") for (int m = 0; m < 4; ++m) _Pragma("unroll") for (int k = 0; k < 2; ++k) dst[m][k] = \
;       *reinterpret_cast<const bf16x8*>(shmc + aL + (((b) * 2 + (h)) * 16384 + (m * 2 + k) * 1024))
; #define LDB(dst, b, h)                                                                                     \
;   _Pragma("unroll") for (int n = 0; n < 2; ++n) _Pragma("unroll") for (int k = 0; k < 2; ++k) dst[n][k] = \
;       *reinterpret_cast<const bf16x8*>(shmc + bL + (((b) * 2 + (h)) * 16384 + (n * 2 + k) * 1024))
; #define WAIT_V(n) asm volatile("s_waitcnt vmcnt(" #n ")" ::: "memory")
; #define WAIT_L(n) asm volatile("s_waitcnt lgkmcnt(" #n ")" ::: "memory")
; #define BAR __builtin_amdgcn_s_barrier()
; #define SCHED __builtin_amdgcn_sched_barrier(0)
; template <int EPI>
; __device__ __forceinline__ void phase_gemm(const Params& p, const GemmDesc& d, char* shmc) {
;     ...
;       LDB(B0, 1, 0); SCHED; LDA(At, 1, 0); STAGE_A(SA(0, 1), 1, t + 2);
;       WAIT_L(8); BAR; WAIT_L(0); MMA(0, 0, At, B0); BAR; SCHED;
;       LDB(B1, 1, 1); STAGE_B(SB(1, 0), 0, t + 3);
;       BAR; WAIT_L(0); MMA(0, 1, At, B1); BAR;
;       LDA(At, 1, 1); STAGE_A(SA(1, 0), 0, t + 3);
;       BAR; WAIT_L(0); MMA(1, 0, At, B0); BAR; SCHED;
;       STAGE_B(SB(1, 1), 1, t + 3);
;       WAIT_V(6); BAR; MMA(1, 1, At, B1); BAR;
;     }
	s_setprio 0
	ds_read_b128 v[156:159], v130 offset:32768
	ds_read_b128 v[160:163], v130 offset:33792
	ds_read_b128 v[164:167], v130 offset:34816
	ds_read_b128 v[168:171], v130 offset:35840
	ds_read_b128 v[204:207], v130 offset:49152
	ds_read_b128 v[208:211], v130 offset:50176
	ds_read_b128 v[212:215], v130 offset:51200
	ds_read_b128 v[216:219], v130 offset:52224
	ds_read_b128 v[172:175], v141 offset:32768
	ds_read_b128 v[176:179], v141 offset:33792
	ds_read_b128 v[180:183], v141 offset:34816
	ds_read_b128 v[184:187], v141 offset:35840
	ds_read_b128 v[188:191], v141 offset:36864
	ds_read_b128 v[192:195], v141 offset:37888
	ds_read_b128 v[196:199], v141 offset:38912
	ds_read_b128 v[200:203], v141 offset:39936
	s_mov_b32 m0, s49
	s_nop 0
	global_load_lds_dwordx4 v228, s[98:99]
	s_mov_b32 m0, s52
	s_nop 0
	global_load_lds_dwordx4 v229, s[98:99]
	s_waitcnt vmcnt(8)
	s_waitcnt lgkmcnt(0)
	s_setprio 1
	s_barrier
	v_mfma_f32_16x16x32_bf16 v[126:129], v[156:159], v[172:175], v[126:129]
	v_mfma_f32_16x16x32_bf16 v[122:125], v[164:167], v[172:175], v[122:125]
	v_mfma_f32_16x16x32_bf16 v[118:121], v[156:159], v[180:183], v[118:121]
	v_mfma_f32_16x16x32_bf16 v[114:117], v[164:167], v[180:183], v[114:117]
	v_mfma_f32_16x16x32_bf16 v[110:113], v[156:159], v[188:191], v[110:113]
	v_mfma_f32_16x16x32_bf16 v[106:109], v[164:167], v[188:191], v[106:109]
	v_mfma_f32_16x16x32_bf16 v[102:105], v[156:159], v[196:199], v[102:105]
	v_mfma_f32_16x16x32_bf16 v[98:101], v[164:167], v[196:199], v[98:101]
	v_mfma_f32_16x16x32_bf16 v[126:129], v[160:163], v[176:179], v[126:129]
	v_mfma_f32_16x16x32_bf16 v[122:125], v[168:171], v[176:179], v[122:125]
	v_mfma_f32_16x16x32_bf16 v[118:121], v[160:163], v[184:187], v[118:121]
	v_mfma_f32_16x16x32_bf16 v[114:117], v[168:171], v[184:187], v[114:117]
	v_mfma_f32_16x16x32_bf16 v[110:113], v[160:163], v[192:195], v[110:113]
	v_mfma_f32_16x16x32_bf16 v[106:109], v[168:171], v[192:195], v[106:109]
	v_mfma_f32_16x16x32_bf16 v[102:105], v[160:163], v[200:203], v[102:105]
	v_mfma_f32_16x16x32_bf16 v[98:101], v[168:171], v[200:203], v[98:101]
	v_mfma_f32_16x16x32_bf16 v[86:89], v[204:207], v[172:175], v[86:89]
	v_mfma_f32_16x16x32_bf16 v[70:73], v[212:215], v[172:175], v[70:73]
	v_mfma_f32_16x16x32_bf16 v[54:57], v[204:207], v[180:183], v[54:57]
	v_mfma_f32_16x16x32_bf16 v[50:53], v[212:215], v[180:183], v[50:53]
	v_mfma_f32_16x16x32_bf16 v[46:49], v[204:207], v[188:191], v[46:49]
	v_mfma_f32_16x16x32_bf16 v[42:45], v[212:215], v[188:191], v[42:45]
	v_mfma_f32_16x16x32_bf16 v[38:41], v[204:207], v[196:199], v[38:41]
	v_mfma_f32_16x16x32_bf16 v[34:37], v[212:215], v[196:199], v[34:37]
	v_mfma_f32_16x16x32_bf16 v[86:89], v[208:211], v[176:179], v[86:89]
	v_mfma_f32_16x16x32_bf16 v[70:73], v[216:219], v[176:179], v[70:73]
	v_mfma_f32_16x16x32_bf16 v[54:57], v[208:211], v[184:187], v[54:57]
	v_mfma_f32_16x16x32_bf16 v[50:53], v[216:219], v[184:187], v[50:53]
	v_mfma_f32_16x16x32_bf16 v[46:49], v[208:211], v[192:195], v[46:49]
	v_mfma_f32_16x16x32_bf16 v[42:45], v[216:219], v[192:195], v[42:45]
	v_mfma_f32_16x16x32_bf16 v[38:41], v[208:211], v[200:203], v[38:41]
	v_mfma_f32_16x16x32_bf16 v[34:37], v[216:219], v[200:203], v[34:37]
	s_barrier
	s_setprio 0
	ds_read_b128 v[172:175], v141 offset:49152
	ds_read_b128 v[176:179], v141 offset:50176
	ds_read_b128 v[180:183], v141 offset:51200
	ds_read_b128 v[184:187], v141 offset:52224
	ds_read_b128 v[188:191], v141 offset:53248
	ds_read_b128 v[192:195], v141 offset:54272
	ds_read_b128 v[196:199], v141 offset:55296
	ds_read_b128 v[200:203], v141 offset:56320
	s_mov_b32 m0, s53
	s_nop 0
	global_load_lds_dwordx4 v232, s[100:101]
	s_mov_b32 m0, s54
	s_nop 0
	global_load_lds_dwordx4 v233, s[100:101]
	s_mov_b32 m0, s55
	s_nop 0
	global_load_lds_dwordx4 v234, s[98:99]
	s_mov_b32 m0, s56
	s_nop 0
	global_load_lds_dwordx4 v235, s[98:99]
	s_mov_b32 m0, s57
	s_nop 0
	global_load_lds_dwordx4 v236, s[100:101]
	s_mov_b32 m0, s58
	s_nop 0
	global_load_lds_dwordx4 v237, s[100:101]
	s_add_i32 s42, s42, 2
	s_add_u32 s40, s40, 0x100
	s_addc_u32 s41, s41, 0
	s_add_u32 s98, s98, 0x100
	s_addc_u32 s99, s99, 0
	s_add_u32 s100, s100, 0x100
	s_addc_u32 s101, s101, 0
	s_cmpk_gt_u32 s42, 0x53
	s_waitcnt vmcnt(8)
	s_waitcnt lgkmcnt(0)
	s_setprio 1
	s_barrier
	v_mfma_f32_16x16x32_bf16 v[30:33], v[156:159], v[172:175], v[30:33]
	v_mfma_f32_16x16x32_bf16 v[26:29], v[164:167], v[172:175], v[26:29]
	v_mfma_f32_16x16x32_bf16 v[22:25], v[156:159], v[180:183], v[22:25]
	v_mfma_f32_16x16x32_bf16 v[18:21], v[164:167], v[180:183], v[18:21]
	v_mfma_f32_16x16x32_bf16 v[14:17], v[156:159], v[188:191], v[14:17]
	v_mfma_f32_16x16x32_bf16 v[10:13], v[164:167], v[188:191], v[10:13]
	v_mfma_f32_16x16x32_bf16 v[6:9], v[156:159], v[196:199], v[6:9]
	v_mfma_f32_16x16x32_bf16 v[2:5], v[164:167], v[196:199], v[2:5]
	v_mfma_f32_16x16x32_bf16 v[30:33], v[160:163], v[176:179], v[30:33]
	v_mfma_f32_16x16x32_bf16 v[26:29], v[168:171], v[176:179], v[26:29]
	v_mfma_f32_16x16x32_bf16 v[22:25], v[160:163], v[184:187], v[22:25]
	v_mfma_f32_16x16x32_bf16 v[18:21], v[168:171], v[184:187], v[18:21]
	v_mfma_f32_16x16x32_bf16 v[14:17], v[160:163], v[192:195], v[14:17]
	v_mfma_f32_16x16x32_bf16 v[10:13], v[168:171], v[192:195], v[10:13]
	v_mfma_f32_16x16x32_bf16 v[6:9], v[160:163], v[200:203], v[6:9]
	v_mfma_f32_16x16x32_bf16 v[2:5], v[168:171], v[200:203], v[2:5]
	v_mfma_f32_16x16x32_bf16 v[58:61], v[204:207], v[172:175], v[58:61]
	v_mfma_f32_16x16x32_bf16 v[62:65], v[212:215], v[172:175], v[62:65]
	v_mfma_f32_16x16x32_bf16 v[66:69], v[204:207], v[180:183], v[66:69]
	v_mfma_f32_16x16x32_bf16 v[74:77], v[212:215], v[180:183], v[74:77]
	v_mfma_f32_16x16x32_bf16 v[78:81], v[204:207], v[188:191], v[78:81]
	v_mfma_f32_16x16x32_bf16 v[82:85], v[212:215], v[188:191], v[82:85]
	v_mfma_f32_16x16x32_bf16 v[90:93], v[204:207], v[196:199], v[90:93]
	v_mfma_f32_16x16x32_bf16 v[94:97], v[212:215], v[196:199], v[94:97]
	v_mfma_f32_16x16x32_bf16 v[58:61], v[208:211], v[176:179], v[58:61]
	v_mfma_f32_16x16x32_bf16 v[62:65], v[216:219], v[176:179], v[62:65]
	v_mfma_f32_16x16x32_bf16 v[66:69], v[208:211], v[184:187], v[66:69]
	v_mfma_f32_16x16x32_bf16 v[74:77], v[216:219], v[184:187], v[74:77]
	v_mfma_f32_16x16x32_bf16 v[78:81], v[208:211], v[192:195], v[78:81]
	v_mfma_f32_16x16x32_bf16 v[82:85], v[216:219], v[192:195], v[82:85]
	v_mfma_f32_16x16x32_bf16 v[90:93], v[208:211], v[200:203], v[90:93]
	v_mfma_f32_16x16x32_bf16 v[94:97], v[216:219], v[200:203], v[94:97]
	s_barrier
; #define LDA(dst, b, h)                                                                                     \
;   _Pragma("unroll") for (int m = 0; m < 4; ++m) _Pragma("unroll") for (int k = 0; k < 2; ++k) dst[m][k] = \
;       *reinterpret_cast<const bf16x8*>(shmc + aL + (((b) * 2 + (h)) * 16384 + (m * 2 + k) * 1024))
; #define LDB(dst, b, h)                                                                                     \
;   _Pragma("unroll") for (int n = 0; n < 2; ++n) _Pragma("unroll") for (int k = 0; k < 2; ++k) dst[n][k] = \
;       *reinterpret_cast<const bf16x8*>(shmc + bL + (((b) * 2 + (h)) * 16384 + (n * 2 + k) * 1024))
; #define OPAQ asm volatile("" : "+v"(aL), "+v"(bL))
; #define WAIT_V(n) asm volatile("s_waitcnt vmcnt(" #n ")" ::: "memory")
; #define WAIT_L(n) asm volatile("s_waitcnt lgkmcnt(" #n ")" ::: "memory")
; #define BAR __builtin_amdgcn_s_barrier()
; template <int EPI>
; __device__ __forceinline__ void phase_gemm(const Params& p, const GemmDesc& d, char* shmc) {
;     ...
;     }
;     {
;       OPAQ;
;       LDB(B0, 0, 0); LDA(At, 0, 0); STAGE_A(SA(1, 1), 1, nt - 1);
;       BAR; WAIT_L(0); MMA(0, 0, At, B0); BAR;
;       LDB(B1, 0, 1); BAR; WAIT_L(0); MMA(0, 1, At, B1); BAR;
;       LDA(At, 0, 1); WAIT_V(4); BAR; WAIT_L(0); MMA(1, 0, At, B0); MMA(1, 1, At, B1); BAR;
;     }
	s_cbranch_scc0 .LBB0_1312
	s_setprio 0
	s_add_u32 s38, s38, 0x162b80
	s_addc_u32 s39, s39, 0
	v_add_u32_e32 v130, 0, v153
	v_add_u32_e32 v141, 0, v152
	s_mov_b32 m0, s59
	ds_read_b128 v[144:147], v130
	ds_read_b128 v[148:151], v130 offset:1024
	ds_read_b128 v[156:159], v130 offset:2048
	ds_read_b128 v[160:163], v130 offset:3072
	ds_read_b128 v[164:167], v141
	ds_read_b128 v[168:171], v141 offset:1024
	ds_read_b128 v[172:175], v141 offset:2048
	ds_read_b128 v[176:179], v141 offset:3072
	ds_read_b128 v[180:183], v141 offset:4096
	ds_read_b128 v[184:187], v141 offset:5120
	ds_read_b128 v[188:191], v141 offset:6144
	ds_read_b128 v[192:195], v141 offset:7168
	global_load_lds_dwordx4 v140, s[38:39]
	s_mov_b32 m0, s60
	s_nop 0
	global_load_lds_dwordx4 v142, s[38:39]
	s_waitcnt vmcnt(8)
	s_barrier
	s_waitcnt lgkmcnt(0)
	s_setprio 1
	s_waitcnt lgkmcnt(0)
	v_mfma_f32_16x16x32_bf16 v[126:129], v[144:147], v[164:167], v[126:129]
	v_mfma_f32_16x16x32_bf16 v[122:125], v[156:159], v[164:167], v[122:125]
	v_mfma_f32_16x16x32_bf16 v[114:117], v[156:159], v[172:175], v[114:117]
	v_mfma_f32_16x16x32_bf16 v[110:113], v[144:147], v[180:183], v[110:113]
	v_mfma_f32_16x16x32_bf16 v[102:105], v[144:147], v[188:191], v[102:105]
	v_mfma_f32_16x16x32_bf16 v[126:129], v[148:151], v[168:171], v[126:129]
	v_mfma_f32_16x16x32_bf16 v[122:125], v[160:163], v[168:171], v[122:125]
	v_mfma_f32_16x16x32_bf16 v[118:121], v[144:147], v[172:175], v[118:121]
	v_mfma_f32_16x16x32_bf16 v[114:117], v[160:163], v[176:179], v[114:117]
	v_mfma_f32_16x16x32_bf16 v[110:113], v[148:151], v[184:187], v[110:113]
	v_mfma_f32_16x16x32_bf16 v[106:109], v[156:159], v[180:183], v[106:109]
	v_mfma_f32_16x16x32_bf16 v[102:105], v[148:151], v[192:195], v[102:105]
	v_mfma_f32_16x16x32_bf16 v[98:101], v[156:159], v[188:191], v[98:101]
	v_mfma_f32_16x16x32_bf16 v[196:199], v[148:151], v[176:179], v[118:121]
	v_mfma_f32_16x16x32_bf16 v[200:203], v[160:163], v[184:187], v[106:109]
	v_mfma_f32_16x16x32_bf16 v[204:207], v[160:163], v[192:195], v[98:101]
	s_setprio 0
	s_barrier
	s_nop 2
	ds_read_b128 v[98:101], v130 offset:16384
	ds_read_b128 v[106:109], v130 offset:17408
	ds_read_b128 v[118:121], v130 offset:18432
	ds_read_b128 v[208:211], v130 offset:19456
	s_barrier
	s_waitcnt lgkmcnt(0)
	s_setprio 1
	s_waitcnt lgkmcnt(0)
	v_mfma_f32_16x16x32_bf16 v[86:89], v[98:101], v[164:167], v[86:89]
	v_mfma_f32_16x16x32_bf16 v[70:73], v[118:121], v[164:167], v[70:73]
	v_mfma_f32_16x16x32_bf16 v[54:57], v[98:101], v[172:175], v[54:57]
	v_mfma_f32_16x16x32_bf16 v[50:53], v[118:121], v[172:175], v[50:53]
	v_mfma_f32_16x16x32_bf16 v[46:49], v[98:101], v[180:183], v[46:49]
	v_mfma_f32_16x16x32_bf16 v[42:45], v[118:121], v[180:183], v[42:45]
	v_mfma_f32_16x16x32_bf16 v[38:41], v[98:101], v[188:191], v[38:41]
	v_mfma_f32_16x16x32_bf16 v[34:37], v[118:121], v[188:191], v[34:37]
	v_mfma_f32_16x16x32_bf16 v[86:89], v[106:109], v[168:171], v[86:89]
	v_mfma_f32_16x16x32_bf16 v[70:73], v[208:211], v[168:171], v[70:73]
	v_mfma_f32_16x16x32_bf16 v[54:57], v[106:109], v[176:179], v[54:57]
	v_mfma_f32_16x16x32_bf16 v[50:53], v[208:211], v[176:179], v[50:53]
	v_mfma_f32_16x16x32_bf16 v[46:49], v[106:109], v[184:187], v[46:49]
	v_mfma_f32_16x16x32_bf16 v[42:45], v[208:211], v[184:187], v[42:45]
	v_mfma_f32_16x16x32_bf16 v[38:41], v[106:109], v[192:195], v[38:41]
	v_mfma_f32_16x16x32_bf16 v[34:37], v[208:211], v[192:195], v[34:37]
	s_setprio 0
	s_barrier
	ds_read_b128 v[164:167], v141 offset:16384
	ds_read_b128 v[168:171], v141 offset:17408
	ds_read_b128 v[172:175], v141 offset:18432
	ds_read_b128 v[176:179], v141 offset:19456
	ds_read_b128 v[180:183], v141 offset:20480
	ds_read_b128 v[184:187], v141 offset:21504
	ds_read_b128 v[188:191], v141 offset:22528
	ds_read_b128 v[192:195], v141 offset:23552
	s_waitcnt vmcnt(4)
	s_barrier
	s_waitcnt lgkmcnt(0)
	s_setprio 1
	s_waitcnt lgkmcnt(0)
	v_mfma_f32_16x16x32_bf16 v[30:33], v[144:147], v[164:167], v[30:33]
	v_mfma_f32_16x16x32_bf16 v[26:29], v[156:159], v[164:167], v[26:29]
	v_mfma_f32_16x16x32_bf16 v[22:25], v[144:147], v[172:175], v[22:25]
	v_mfma_f32_16x16x32_bf16 v[18:21], v[156:159], v[172:175], v[18:21]
	v_mfma_f32_16x16x32_bf16 v[14:17], v[144:147], v[180:183], v[14:17]
	v_mfma_f32_16x16x32_bf16 v[10:13], v[156:159], v[180:183], v[10:13]
	v_mfma_f32_16x16x32_bf16 v[6:9], v[144:147], v[188:191], v[6:9]
	v_mfma_f32_16x16x32_bf16 v[2:5], v[156:159], v[188:191], v[2:5]
	v_mfma_f32_16x16x32_bf16 v[30:33], v[148:151], v[168:171], v[30:33]
	v_mfma_f32_16x16x32_bf16 v[26:29], v[160:163], v[168:171], v[26:29]
	v_mfma_f32_16x16x32_bf16 v[22:25], v[148:151], v[176:179], v[22:25]
	v_mfma_f32_16x16x32_bf16 v[18:21], v[160:163], v[176:179], v[18:21]
	v_mfma_f32_16x16x32_bf16 v[14:17], v[148:151], v[184:187], v[14:17]
	v_mfma_f32_16x16x32_bf16 v[10:13], v[160:163], v[184:187], v[10:13]
	v_mfma_f32_16x16x32_bf16 v[6:9], v[148:151], v[192:195], v[6:9]
	v_mfma_f32_16x16x32_bf16 v[2:5], v[160:163], v[192:195], v[2:5]
	s_setprio 0
	s_setprio 1
	v_mfma_f32_16x16x32_bf16 v[62:65], v[118:121], v[164:167], v[62:65]
	v_mfma_f32_16x16x32_bf16 v[144:147], v[208:211], v[168:171], v[62:65]
	v_mfma_f32_16x16x32_bf16 v[62:65], v[98:101], v[172:175], v[66:69]
	v_mfma_f32_16x16x32_bf16 v[148:151], v[106:109], v[176:179], v[62:65]
	v_mfma_f32_16x16x32_bf16 v[62:65], v[118:121], v[172:175], v[74:77]
	v_mfma_f32_16x16x32_bf16 v[156:159], v[208:211], v[176:179], v[62:65]
	v_mfma_f32_16x16x32_bf16 v[62:65], v[98:101], v[180:183], v[78:81]
	v_mfma_f32_16x16x32_bf16 v[160:163], v[106:109], v[184:187], v[62:65]
	v_mfma_f32_16x16x32_bf16 v[62:65], v[118:121], v[180:183], v[82:85]
	v_mfma_f32_16x16x32_bf16 v[58:61], v[98:101], v[164:167], v[58:61]
	v_mfma_f32_16x16x32_bf16 v[164:167], v[208:211], v[184:187], v[62:65]
	v_mfma_f32_16x16x32_bf16 v[62:65], v[98:101], v[188:191], v[90:93]
	v_mfma_f32_16x16x32_bf16 v[58:61], v[106:109], v[168:171], v[58:61]
	v_mfma_f32_16x16x32_bf16 v[168:171], v[106:109], v[192:195], v[62:65]
	v_mfma_f32_16x16x32_bf16 v[62:65], v[118:121], v[188:191], v[94:97]
	v_mfma_f32_16x16x32_bf16 v[172:175], v[208:211], v[192:195], v[62:65]
	s_setprio 0
	s_barrier
; #define LDA(dst, b, h)                                                                                     \
;   _Pragma("unroll") for (int m = 0; m < 4; ++m) _Pragma("unroll") for (int k = 0; k < 2; ++k) dst[m][k] = \
;       *reinterpret_cast<const bf16x8*>(shmc + aL + (((b) * 2 + (h)) * 16384 + (m * 2 + k) * 1024))
; #define LDB(dst, b, h)                                                                                     \
;   _Pragma("unroll") for (int n = 0; n < 2; ++n) _Pragma("unroll") for (int k = 0; k < 2; ++k) dst[n][k] = \
;       *reinterpret_cast<const bf16x8*>(shmc + bL + (((b) * 2 + (h)) * 16384 + (n * 2 + k) * 1024))
; #define WAIT_V(n) asm volatile("s_waitcnt vmcnt(" #n ")" ::: "memory")
; #define WAIT_L(n) asm volatile("s_waitcnt lgkmcnt(" #n ")" ::: "memory")
; #define BAR __builtin_amdgcn_s_barrier()
; template <int EPI>
; __device__ __forceinline__ void phase_gemm(const Params& p, const GemmDesc& d, char* shmc) {
;     ...
;     {
;       LDB(B0, 1, 0); LDA(At, 1, 0); WAIT_V(2); BAR; WAIT_L(0); MMA(0, 0, At, B0); BAR;
;       LDB(B1, 1, 1); WAIT_V(0); BAR; WAIT_L(0); MMA(0, 1, At, B1); BAR;
;       LDA(At, 1, 1); BAR; WAIT_L(0); MMA(1, 0, At, B0); MMA(1, 1, At, B1); BAR;
;     }
;     if (wr == 0) BAR;
	ds_read_b128 v[176:179], v130 offset:32768
	ds_read_b128 v[180:183], v130 offset:33792
	ds_read_b128 v[184:187], v130 offset:34816
	ds_read_b128 v[188:191], v130 offset:35840
	s_nop 0
	ds_read_b128 v[62:65], v141 offset:32768
	ds_read_b128 v[78:81], v141 offset:33792
	ds_read_b128 v[94:97], v141 offset:34816
	ds_read_b128 v[192:195], v141 offset:35840
	ds_read_b128 v[208:211], v141 offset:36864
	ds_read_b128 v[212:215], v141 offset:37888
	ds_read_b128 v[216:219], v141 offset:38912
	ds_read_b128 v[220:223], v141 offset:39936
	s_waitcnt vmcnt(2)
	s_barrier
	s_waitcnt lgkmcnt(0)
	s_setprio 1
	s_waitcnt lgkmcnt(0)
	v_mfma_f32_16x16x32_bf16 v[66:69], v[176:179], v[62:65], v[126:129]
	v_mfma_f32_16x16x32_bf16 v[126:129], v[180:183], v[78:81], v[66:69]
	v_mfma_f32_16x16x32_bf16 v[66:69], v[184:187], v[62:65], v[122:125]
	v_mfma_f32_16x16x32_bf16 v[118:121], v[188:191], v[78:81], v[66:69]
	v_mfma_f32_16x16x32_bf16 v[66:69], v[176:179], v[94:97], v[196:199]
	v_mfma_f32_16x16x32_bf16 v[106:109], v[180:183], v[192:195], v[66:69]
	v_mfma_f32_16x16x32_bf16 v[66:69], v[184:187], v[94:97], v[114:117]
	v_mfma_f32_16x16x32_bf16 v[98:101], v[188:191], v[192:195], v[66:69]
	v_mfma_f32_16x16x32_bf16 v[66:69], v[176:179], v[208:211], v[110:113]
	v_mfma_f32_16x16x32_bf16 v[90:93], v[180:183], v[212:215], v[66:69]
	v_mfma_f32_16x16x32_bf16 v[66:69], v[184:187], v[208:211], v[200:203]
	v_mfma_f32_16x16x32_bf16 v[82:85], v[188:191], v[212:215], v[66:69]
	v_mfma_f32_16x16x32_bf16 v[66:69], v[176:179], v[216:219], v[102:105]
	v_mfma_f32_16x16x32_bf16 v[74:77], v[180:183], v[220:223], v[66:69]
	v_mfma_f32_16x16x32_bf16 v[66:69], v[184:187], v[216:219], v[204:207]
	v_mfma_f32_16x16x32_bf16 v[66:69], v[188:191], v[220:223], v[66:69]
	s_setprio 0
	s_barrier
	ds_read_b128 v[196:199], v130 offset:49152
	ds_read_b128 v[200:203], v130 offset:50176
	ds_read_b128 v[204:207], v130 offset:51200
	ds_read_b128 v[224:227], v130 offset:52224
	s_waitcnt vmcnt(0)
	s_barrier
	s_waitcnt lgkmcnt(0)
	s_setprio 1
	s_waitcnt lgkmcnt(0)
	v_mfma_f32_16x16x32_bf16 v[86:89], v[196:199], v[62:65], v[86:89]
	v_mfma_f32_16x16x32_bf16 v[62:65], v[204:207], v[62:65], v[70:73]
	v_mfma_f32_16x16x32_bf16 v[54:57], v[196:199], v[94:97], v[54:57]
	v_mfma_f32_16x16x32_bf16 v[50:53], v[204:207], v[94:97], v[50:53]
	v_mfma_f32_16x16x32_bf16 v[46:49], v[196:199], v[208:211], v[46:49]
	v_mfma_f32_16x16x32_bf16 v[42:45], v[204:207], v[208:211], v[42:45]
	v_mfma_f32_16x16x32_bf16 v[38:41], v[196:199], v[216:219], v[38:41]
	v_mfma_f32_16x16x32_bf16 v[34:37], v[204:207], v[216:219], v[34:37]
	v_mfma_f32_16x16x32_bf16 v[122:125], v[200:203], v[78:81], v[86:89]
	v_mfma_f32_16x16x32_bf16 v[114:117], v[224:227], v[78:81], v[62:65]
	v_mfma_f32_16x16x32_bf16 v[110:113], v[200:203], v[192:195], v[54:57]
	v_mfma_f32_16x16x32_bf16 v[102:105], v[224:227], v[192:195], v[50:53]
	v_mfma_f32_16x16x32_bf16 v[94:97], v[200:203], v[212:215], v[46:49]
	v_mfma_f32_16x16x32_bf16 v[86:89], v[224:227], v[212:215], v[42:45]
	v_mfma_f32_16x16x32_bf16 v[78:81], v[200:203], v[220:223], v[38:41]
	v_mfma_f32_16x16x32_bf16 v[70:73], v[224:227], v[220:223], v[34:37]
	s_setprio 0
	s_barrier
	s_nop 0
	ds_read_b128 v[34:37], v141 offset:49152
	ds_read_b128 v[42:45], v141 offset:50176
	ds_read_b128 v[192:195], v141 offset:51200
	ds_read_b128 v[208:211], v141 offset:52224
	ds_read_b128 v[212:215], v141 offset:53248
	ds_read_b128 v[216:219], v141 offset:54272
	ds_read_b128 v[220:223], v141 offset:55296
	ds_read_b128 v[228:231], v141 offset:56320
	s_barrier
	s_waitcnt lgkmcnt(0)
	s_setprio 1
	s_waitcnt lgkmcnt(0)
	v_mfma_f32_16x16x32_bf16 v[30:33], v[176:179], v[34:37], v[30:33]
	v_mfma_f32_16x16x32_bf16 v[26:29], v[184:187], v[34:37], v[26:29]
	v_mfma_f32_16x16x32_bf16 v[22:25], v[176:179], v[192:195], v[22:25]
	v_mfma_f32_16x16x32_bf16 v[18:21], v[184:187], v[192:195], v[18:21]
	v_mfma_f32_16x16x32_bf16 v[14:17], v[176:179], v[212:215], v[14:17]
	v_mfma_f32_16x16x32_bf16 v[10:13], v[184:187], v[212:215], v[10:13]
	v_mfma_f32_16x16x32_bf16 v[6:9], v[176:179], v[220:223], v[6:9]
	v_mfma_f32_16x16x32_bf16 v[2:5], v[184:187], v[220:223], v[2:5]
	v_mfma_f32_16x16x32_bf16 v[62:65], v[180:183], v[42:45], v[30:33]
	v_mfma_f32_16x16x32_bf16 v[54:57], v[188:191], v[42:45], v[26:29]
	v_mfma_f32_16x16x32_bf16 v[46:49], v[180:183], v[208:211], v[22:25]
	v_mfma_f32_16x16x32_bf16 v[38:41], v[188:191], v[208:211], v[18:21]
	v_mfma_f32_16x16x32_bf16 v[30:33], v[180:183], v[216:219], v[14:17]
	v_mfma_f32_16x16x32_bf16 v[22:25], v[188:191], v[216:219], v[10:13]
	v_mfma_f32_16x16x32_bf16 v[14:17], v[180:183], v[228:231], v[6:9]
	v_mfma_f32_16x16x32_bf16 v[6:9], v[188:191], v[228:231], v[2:5]
	s_setprio 0
	s_setprio 1
	v_mfma_f32_16x16x32_bf16 v[2:5], v[196:199], v[34:37], v[58:61]
	v_mfma_f32_16x16x32_bf16 v[58:61], v[200:203], v[42:45], v[2:5]
	v_mfma_f32_16x16x32_bf16 v[2:5], v[204:207], v[34:37], v[144:147]
	v_mfma_f32_16x16x32_bf16 v[50:53], v[224:227], v[42:45], v[2:5]
	v_mfma_f32_16x16x32_bf16 v[2:5], v[196:199], v[192:195], v[148:151]
	v_mfma_f32_16x16x32_bf16 v[42:45], v[200:203], v[208:211], v[2:5]
	v_mfma_f32_16x16x32_bf16 v[2:5], v[204:207], v[192:195], v[156:159]
	v_mfma_f32_16x16x32_bf16 v[34:37], v[224:227], v[208:211], v[2:5]
	v_mfma_f32_16x16x32_bf16 v[2:5], v[196:199], v[212:215], v[160:163]
	v_mfma_f32_16x16x32_bf16 v[26:29], v[200:203], v[216:219], v[2:5]
	v_mfma_f32_16x16x32_bf16 v[2:5], v[204:207], v[212:215], v[164:167]
	v_mfma_f32_16x16x32_bf16 v[18:21], v[224:227], v[216:219], v[2:5]
	v_mfma_f32_16x16x32_bf16 v[2:5], v[196:199], v[220:223], v[168:171]
	v_mfma_f32_16x16x32_bf16 v[10:13], v[200:203], v[228:231], v[2:5]
	v_mfma_f32_16x16x32_bf16 v[2:5], v[204:207], v[220:223], v[172:175]
	v_mfma_f32_16x16x32_bf16 v[2:5], v[224:227], v[228:231], v[2:5]
	s_setprio 0
	s_barrier
	s_and_saveexec_b64 s[38:39], s[4:5]
	s_cbranch_execz .LBB0_1315
	s_barrier
